# GEMM loops: first sub-phase's 16 ds_read_b128 hoisted above the loop-header SALU address computation (loop-edge edit)
# speedup vs baseline: 1.0106x; 1.0073x over previous
; #define PG8_STAGE(bufoff, gbase, voff) do { _Pragma("unroll") for (int _i = 0; _i < 2; ++_i) \
;         __builtin_amdgcn_global_load_lds((const unsigned*)((const char*)(gbase) + (voff)[_i]), (LAS unsigned*)(lds + (bufoff) + ldsw + _i * 8192), 16, 0, 0); } while (0)
; #define PG8_LDA(dst, b, h) do { _Pragma("unroll") for (int m = 0; m < 4; ++m) _Pragma("unroll") for (int k = 0; k < 2; ++k) dst[m][k] = *(const LAS bf16x8*)(lds + PG8_SA(b, h) + aoff + m * 2048 + k * 1024); } while (0)
; #define PG8_LDB(dst, b, h) do { _Pragma("unroll") for (int n = 0; n < 2; ++n) _Pragma("unroll") for (int k = 0; k < 2; ++k) dst[n][k] = *(const LAS bf16x8*)(lds + PG8_SB(b, h) + boff + n * 2048 + k * 1024); } while (0)
; #define PG8_MMA(ai, bj, At, Bt) do { __builtin_amdgcn_s_setprio(1); _Pragma("unroll") for (int m = 0; m < 4; ++m) _Pragma("unroll") for (int n = 0; n < 2; ++n) _Pragma("unroll") for (int k = 0; k < 2; ++k) \
;         acc[ai][bj][m][n] = __builtin_amdgcn_mfma_f32_16x16x32_bf16(Bt[n][k], At[m][k], acc[ai][bj][m][n], 0, 0, 0); __builtin_amdgcn_s_setprio(0); } while (0)
; #define PG8_WAIT_V(n) asm volatile("s_waitcnt vmcnt(" #n ")" ::: "memory")
; #define PG8_WAIT_L(n) asm volatile("s_waitcnt lgkmcnt(" #n ")" ::: "memory")
; #define PG8_BAR __builtin_amdgcn_s_barrier()
; #define PG8_SCHED __builtin_amdgcn_sched_barrier(0)
; template <class Epi>
; __device__ __forceinline__ void gemm_phase(LAS unsigned char* lds, const Gemm g, const StaticOrder S, const Epi E) {
;     ...
;             PG8_LDB(B0, 0, 0); PG8_LDB(B1, 0, 1); PG8_SCHED; PG8_LDA(At, 0, 0); PG8_STAGE(PG8_SA(1, 1), a1 + hstepA, voffA);
;             PG8_WAIT_V(8); PG8_WAIT_L(0); PG8_BAR; PG8_MMA(0, 0, At, B0); PG8_MMA(0, 1, At, B1); PG8_BAR; PG8_SCHED;
;             PG8_LDA(At, 0, 1); PG8_STAGE(PG8_SB(0, 0), b2, voffB); PG8_STAGE(PG8_SB(0, 1), b2 + hstepB, voffB); PG8_STAGE(PG8_SA(0, 0), a2, voffA);
;             PG8_WAIT_V(8); PG8_WAIT_L(0); PG8_BAR; PG8_MMA(1, 0, At, B0); PG8_MMA(1, 1, At, B1); PG8_BAR; PG8_SCHED;
.LBB0_121:
	s_or_b32 s13, s62, 1
	s_mul_i32 s46, s27, s13
	s_mul_hi_u32 s47, s26, s13
	s_add_i32 s47, s47, s46
	s_mul_i32 s13, s26, s13
	s_add_u32 s13, s24, s13
	s_addc_u32 s63, s25, s47
	s_add_u32 s46, s44, s42
	s_addc_u32 s47, s45, s43
	s_add_u32 s64, s13, 0x80000
	s_addc_u32 s65, s63, 0
	s_add_i32 m0, s21, 0xc000
	global_load_lds_dwordx4 v134, s[64:65]
	s_add_i32 m0, s21, 0xe000
	s_nop 0
	global_load_lds_dwordx4 v130, s[64:65]
	s_waitcnt vmcnt(8)
	s_waitcnt lgkmcnt(0)
	s_barrier
	s_setprio 1
	s_waitcnt lgkmcnt(0)
	v_mfma_f32_16x16x32_bf16 v[116:119], v[148:151], v[180:183], v[116:119]
	v_mfma_f32_16x16x32_bf16 v[112:115], v[156:159], v[180:183], v[112:115]
	v_mfma_f32_16x16x32_bf16 v[108:111], v[148:151], v[188:191], v[108:111]
	v_mfma_f32_16x16x32_bf16 v[104:107], v[156:159], v[188:191], v[104:107]
	v_mfma_f32_16x16x32_bf16 v[92:95], v[148:151], v[196:199], v[92:95]
	v_mfma_f32_16x16x32_bf16 v[88:91], v[156:159], v[196:199], v[88:91]
	v_mfma_f32_16x16x32_bf16 v[76:79], v[148:151], v[204:207], v[76:79]
	v_mfma_f32_16x16x32_bf16 v[72:75], v[156:159], v[204:207], v[72:75]
	v_mfma_f32_16x16x32_bf16 v[116:119], v[152:155], v[184:187], v[116:119]
	v_mfma_f32_16x16x32_bf16 v[112:115], v[160:163], v[184:187], v[112:115]
	v_mfma_f32_16x16x32_bf16 v[108:111], v[152:155], v[192:195], v[108:111]
	v_mfma_f32_16x16x32_bf16 v[104:107], v[160:163], v[192:195], v[104:107]
	v_mfma_f32_16x16x32_bf16 v[92:95], v[152:155], v[200:203], v[92:95]
	v_mfma_f32_16x16x32_bf16 v[88:91], v[160:163], v[200:203], v[88:91]
	v_mfma_f32_16x16x32_bf16 v[76:79], v[152:155], v[208:211], v[76:79]
	v_mfma_f32_16x16x32_bf16 v[72:75], v[160:163], v[208:211], v[72:75]
	s_setprio 0
	s_setprio 1
	v_mfma_f32_16x16x32_bf16 v[124:127], v[164:167], v[180:183], v[124:127]
	v_mfma_f32_16x16x32_bf16 v[120:123], v[172:175], v[180:183], v[120:123]
	v_mfma_f32_16x16x32_bf16 v[100:103], v[164:167], v[188:191], v[100:103]
	v_mfma_f32_16x16x32_bf16 v[96:99], v[172:175], v[188:191], v[96:99]
	v_mfma_f32_16x16x32_bf16 v[84:87], v[164:167], v[196:199], v[84:87]
	v_mfma_f32_16x16x32_bf16 v[80:83], v[172:175], v[196:199], v[80:83]
	v_mfma_f32_16x16x32_bf16 v[68:71], v[164:167], v[204:207], v[68:71]
	v_mfma_f32_16x16x32_bf16 v[64:67], v[172:175], v[204:207], v[64:67]
	v_mfma_f32_16x16x32_bf16 v[124:127], v[168:171], v[184:187], v[124:127]
	v_mfma_f32_16x16x32_bf16 v[120:123], v[176:179], v[184:187], v[120:123]
	v_mfma_f32_16x16x32_bf16 v[100:103], v[168:171], v[192:195], v[100:103]
	v_mfma_f32_16x16x32_bf16 v[96:99], v[176:179], v[192:195], v[96:99]
	v_mfma_f32_16x16x32_bf16 v[84:87], v[168:171], v[200:203], v[84:87]
	v_mfma_f32_16x16x32_bf16 v[80:83], v[176:179], v[200:203], v[80:83]
	v_mfma_f32_16x16x32_bf16 v[68:71], v[168:171], v[208:211], v[68:71]
	v_mfma_f32_16x16x32_bf16 v[64:67], v[176:179], v[208:211], v[64:67]
	s_setprio 0
	s_barrier
	s_add_i32 s13, s57, s33
	s_mov_b32 m0, s13
	ds_read_b128 v[180:183], v145 offset:16384
	ds_read_b128 v[184:187], v145 offset:17408
	ds_read_b128 v[188:191], v145 offset:18432
	ds_read_b128 v[192:195], v145 offset:19456
	ds_read_b128 v[196:199], v145 offset:20480
	ds_read_b128 v[200:203], v145 offset:21504
	ds_read_b128 v[204:207], v145 offset:22528
	ds_read_b128 v[208:211], v145 offset:23552
	global_load_lds_dwordx4 v132, s[40:41]
	s_add_i32 m0, s13, 0x2000
	s_add_u32 s64, s40, 0x80000
	s_addc_u32 s65, s41, 0
	s_add_i32 s13, s58, s33
	global_load_lds_dwordx4 v128, s[40:41]
	s_mov_b32 m0, s13
	s_nop 0
	global_load_lds_dwordx4 v132, s[64:65]
	s_add_i32 m0, s13, 0x2000
	s_nop 0
	global_load_lds_dwordx4 v128, s[64:65]
	s_mov_b32 m0, s21
	s_nop 0
	global_load_lds_dwordx4 v134, s[44:45]
	s_mov_b32 m0, s50
	s_nop 0
	global_load_lds_dwordx4 v130, s[44:45]
	s_waitcnt vmcnt(8)
	s_waitcnt lgkmcnt(0)
	s_barrier
	s_setprio 1
	s_waitcnt lgkmcnt(0)
	v_mfma_f32_16x16x32_bf16 v[60:63], v[148:151], v[180:183], v[60:63]
	v_mfma_f32_16x16x32_bf16 v[56:59], v[156:159], v[180:183], v[56:59]
	v_mfma_f32_16x16x32_bf16 v[44:47], v[148:151], v[188:191], v[44:47]
	v_mfma_f32_16x16x32_bf16 v[40:43], v[156:159], v[188:191], v[40:43]
	v_mfma_f32_16x16x32_bf16 v[28:31], v[148:151], v[196:199], v[28:31]
	v_mfma_f32_16x16x32_bf16 v[24:27], v[156:159], v[196:199], v[24:27]
	v_mfma_f32_16x16x32_bf16 v[12:15], v[148:151], v[204:207], v[12:15]
	v_mfma_f32_16x16x32_bf16 v[8:11], v[156:159], v[204:207], v[8:11]
	v_mfma_f32_16x16x32_bf16 v[60:63], v[152:155], v[184:187], v[60:63]
	v_mfma_f32_16x16x32_bf16 v[56:59], v[160:163], v[184:187], v[56:59]
	v_mfma_f32_16x16x32_bf16 v[44:47], v[152:155], v[192:195], v[44:47]
	v_mfma_f32_16x16x32_bf16 v[40:43], v[160:163], v[192:195], v[40:43]
	v_mfma_f32_16x16x32_bf16 v[28:31], v[152:155], v[200:203], v[28:31]
	v_mfma_f32_16x16x32_bf16 v[24:27], v[160:163], v[200:203], v[24:27]
	v_mfma_f32_16x16x32_bf16 v[12:15], v[152:155], v[208:211], v[12:15]
	v_mfma_f32_16x16x32_bf16 v[8:11], v[160:163], v[208:211], v[8:11]
	s_setprio 0
	s_setprio 1
	v_mfma_f32_16x16x32_bf16 v[52:55], v[164:167], v[180:183], v[52:55]
	v_mfma_f32_16x16x32_bf16 v[48:51], v[172:175], v[180:183], v[48:51]
	v_mfma_f32_16x16x32_bf16 v[36:39], v[164:167], v[188:191], v[36:39]
	v_mfma_f32_16x16x32_bf16 v[32:35], v[172:175], v[188:191], v[32:35]
	v_mfma_f32_16x16x32_bf16 v[20:23], v[164:167], v[196:199], v[20:23]
	v_mfma_f32_16x16x32_bf16 v[16:19], v[172:175], v[196:199], v[16:19]
	v_mfma_f32_16x16x32_bf16 v[4:7], v[164:167], v[204:207], v[4:7]
	v_mfma_f32_16x16x32_bf16 v[0:3], v[172:175], v[204:207], v[0:3]
	v_mfma_f32_16x16x32_bf16 v[52:55], v[168:171], v[184:187], v[52:55]
	v_mfma_f32_16x16x32_bf16 v[48:51], v[176:179], v[184:187], v[48:51]
	v_mfma_f32_16x16x32_bf16 v[36:39], v[168:171], v[192:195], v[36:39]
	v_mfma_f32_16x16x32_bf16 v[32:35], v[176:179], v[192:195], v[32:35]
	v_mfma_f32_16x16x32_bf16 v[20:23], v[168:171], v[200:203], v[20:23]
	v_mfma_f32_16x16x32_bf16 v[16:19], v[176:179], v[200:203], v[16:19]
	v_mfma_f32_16x16x32_bf16 v[4:7], v[168:171], v[208:211], v[4:7]
	v_mfma_f32_16x16x32_bf16 v[0:3], v[176:179], v[208:211], v[0:3]
	s_setprio 0
	s_barrier
; #define PG8_STAGE(bufoff, gbase, voff) do { _Pragma("unroll") for (int _i = 0; _i < 2; ++_i) \
;         __builtin_amdgcn_global_load_lds((const unsigned*)((const char*)(gbase) + (voff)[_i]), (LAS unsigned*)(lds + (bufoff) + ldsw + _i * 8192), 16, 0, 0); } while (0)
; #define PG8_LDA(dst, b, h) do { _Pragma("unroll") for (int m = 0; m < 4; ++m) _Pragma("unroll") for (int k = 0; k < 2; ++k) dst[m][k] = *(const LAS bf16x8*)(lds + PG8_SA(b, h) + aoff + m * 2048 + k * 1024); } while (0)
; #define PG8_LDB(dst, b, h) do { _Pragma("unroll") for (int n = 0; n < 2; ++n) _Pragma("unroll") for (int k = 0; k < 2; ++k) dst[n][k] = *(const LAS bf16x8*)(lds + PG8_SB(b, h) + boff + n * 2048 + k * 1024); } while (0)
; #define PG8_MMA(ai, bj, At, Bt) do { __builtin_amdgcn_s_setprio(1); _Pragma("unroll") for (int m = 0; m < 4; ++m) _Pragma("unroll") for (int n = 0; n < 2; ++n) _Pragma("unroll") for (int k = 0; k < 2; ++k) \
;         acc[ai][bj][m][n] = __builtin_amdgcn_mfma_f32_16x16x32_bf16(Bt[n][k], At[m][k], acc[ai][bj][m][n], 0, 0, 0); __builtin_amdgcn_s_setprio(0); } while (0)
; #define PG8_WAIT_V(n) asm volatile("s_waitcnt vmcnt(" #n ")" ::: "memory")
; #define PG8_WAIT_L(n) asm volatile("s_waitcnt lgkmcnt(" #n ")" ::: "memory")
; #define PG8_BAR __builtin_amdgcn_s_barrier()
; #define PG8_SCHED __builtin_amdgcn_sched_barrier(0)
; template <class Epi>
; __device__ __forceinline__ void gemm_phase(LAS unsigned char* lds, const Gemm g, const StaticOrder S, const Epi E) {
;     ...
;         for (int t = 0; t < nt; t += 2) {
;     ...
;             PG8_LDB(B0, 1, 0); PG8_LDB(B1, 1, 1); PG8_SCHED; PG8_LDA(At, 1, 0); PG8_STAGE(PG8_SA(0, 1), a2 + hstepA, voffA);
;             PG8_WAIT_V(8); PG8_WAIT_L(0); PG8_BAR; PG8_MMA(0, 0, At, B0); PG8_MMA(0, 1, At, B1); PG8_BAR; PG8_SCHED;
;             PG8_LDA(At, 1, 1); PG8_STAGE(PG8_SB(1, 0), b3, voffB); PG8_STAGE(PG8_SB(1, 1), b3 + hstepB, voffB); PG8_STAGE(PG8_SA(1, 0), a3, voffA);
;             PG8_WAIT_V(8); PG8_WAIT_L(0); PG8_BAR; PG8_MMA(1, 0, At, B0); PG8_MMA(1, 1, At, B1); PG8_BAR; PG8_SCHED;
	s_add_i32 s13, 0, 0x18000
	s_add_i32 s63, 0, 0x1c000
	ds_read_b128 v[148:151], v254 offset:32768
	ds_read_b128 v[152:155], v254 offset:33792
	ds_read_b128 v[156:159], v254 offset:34816
	ds_read_b128 v[160:163], v254 offset:35840
	ds_read_b128 v[164:167], v254 offset:49152
	ds_read_b128 v[168:171], v254 offset:50176
	ds_read_b128 v[172:175], v254 offset:51200
	ds_read_b128 v[176:179], v254 offset:52224
	s_add_u32 s44, s44, 0x80000
	s_addc_u32 s45, s45, 0
	s_mov_b32 m0, s51
	ds_read_b128 v[180:183], v145 offset:32768
	ds_read_b128 v[184:187], v145 offset:33792
	ds_read_b128 v[188:191], v145 offset:34816
	ds_read_b128 v[192:195], v145 offset:35840
	ds_read_b128 v[196:199], v145 offset:36864
	ds_read_b128 v[200:203], v145 offset:37888
	ds_read_b128 v[204:207], v145 offset:38912
	ds_read_b128 v[208:211], v145 offset:39936
	global_load_lds_dwordx4 v134, s[44:45]
	s_mov_b32 m0, s52
	s_nop 0
	global_load_lds_dwordx4 v130, s[44:45]
	s_waitcnt vmcnt(8)
	s_waitcnt lgkmcnt(0)
	s_barrier
	s_setprio 1
	s_waitcnt lgkmcnt(0)
	v_mfma_f32_16x16x32_bf16 v[116:119], v[148:151], v[180:183], v[116:119]
	v_mfma_f32_16x16x32_bf16 v[112:115], v[156:159], v[180:183], v[112:115]
	v_mfma_f32_16x16x32_bf16 v[108:111], v[148:151], v[188:191], v[108:111]
	v_mfma_f32_16x16x32_bf16 v[104:107], v[156:159], v[188:191], v[104:107]
	v_mfma_f32_16x16x32_bf16 v[92:95], v[148:151], v[196:199], v[92:95]
	v_mfma_f32_16x16x32_bf16 v[88:91], v[156:159], v[196:199], v[88:91]
	v_mfma_f32_16x16x32_bf16 v[76:79], v[148:151], v[204:207], v[76:79]
	v_mfma_f32_16x16x32_bf16 v[72:75], v[156:159], v[204:207], v[72:75]
	v_mfma_f32_16x16x32_bf16 v[116:119], v[152:155], v[184:187], v[116:119]
	v_mfma_f32_16x16x32_bf16 v[112:115], v[160:163], v[184:187], v[112:115]
	v_mfma_f32_16x16x32_bf16 v[108:111], v[152:155], v[192:195], v[108:111]
	v_mfma_f32_16x16x32_bf16 v[104:107], v[160:163], v[192:195], v[104:107]
	v_mfma_f32_16x16x32_bf16 v[92:95], v[152:155], v[200:203], v[92:95]
	v_mfma_f32_16x16x32_bf16 v[88:91], v[160:163], v[200:203], v[88:91]
	v_mfma_f32_16x16x32_bf16 v[76:79], v[152:155], v[208:211], v[76:79]
	v_mfma_f32_16x16x32_bf16 v[72:75], v[160:163], v[208:211], v[72:75]
	s_setprio 0
	s_setprio 1
	v_mfma_f32_16x16x32_bf16 v[124:127], v[164:167], v[180:183], v[124:127]
	v_mfma_f32_16x16x32_bf16 v[120:123], v[172:175], v[180:183], v[120:123]
	v_mfma_f32_16x16x32_bf16 v[100:103], v[164:167], v[188:191], v[100:103]
	v_mfma_f32_16x16x32_bf16 v[96:99], v[172:175], v[188:191], v[96:99]
	v_mfma_f32_16x16x32_bf16 v[84:87], v[164:167], v[196:199], v[84:87]
	v_mfma_f32_16x16x32_bf16 v[80:83], v[172:175], v[196:199], v[80:83]
	v_mfma_f32_16x16x32_bf16 v[68:71], v[164:167], v[204:207], v[68:71]
	v_mfma_f32_16x16x32_bf16 v[64:67], v[172:175], v[204:207], v[64:67]
	v_mfma_f32_16x16x32_bf16 v[124:127], v[168:171], v[184:187], v[124:127]
	v_mfma_f32_16x16x32_bf16 v[120:123], v[176:179], v[184:187], v[120:123]
	v_mfma_f32_16x16x32_bf16 v[100:103], v[168:171], v[192:195], v[100:103]
	v_mfma_f32_16x16x32_bf16 v[96:99], v[176:179], v[192:195], v[96:99]
	v_mfma_f32_16x16x32_bf16 v[84:87], v[168:171], v[200:203], v[84:87]
	v_mfma_f32_16x16x32_bf16 v[80:83], v[176:179], v[200:203], v[80:83]
	v_mfma_f32_16x16x32_bf16 v[68:71], v[168:171], v[208:211], v[68:71]
	v_mfma_f32_16x16x32_bf16 v[64:67], v[176:179], v[208:211], v[64:67]
	s_setprio 0
	s_barrier
	s_add_u32 s40, s40, s42
	s_addc_u32 s41, s41, s43
	s_add_i32 s13, s13, s33
	s_mov_b32 m0, s13
	ds_read_b128 v[180:183], v145 offset:49152
	ds_read_b128 v[184:187], v145 offset:50176
	ds_read_b128 v[188:191], v145 offset:51200
	ds_read_b128 v[192:195], v145 offset:52224
	ds_read_b128 v[196:199], v145 offset:53248
	ds_read_b128 v[200:203], v145 offset:54272
	ds_read_b128 v[204:207], v145 offset:55296
	ds_read_b128 v[208:211], v145 offset:56320
	global_load_lds_dwordx4 v132, s[40:41]
	s_add_i32 m0, s13, 0x2000
	s_nop 0
	global_load_lds_dwordx4 v128, s[40:41]
	s_add_u32 s40, s40, 0x80000
	s_addc_u32 s41, s41, 0
	s_add_i32 s13, s63, s33
	s_mov_b32 m0, s13
	s_nop 0
	global_load_lds_dwordx4 v132, s[40:41]
	s_add_i32 m0, s13, 0x2000
	s_nop 0
	global_load_lds_dwordx4 v128, s[40:41]
	s_mov_b32 m0, s53
	s_nop 0
	global_load_lds_dwordx4 v134, s[46:47]
	s_mov_b32 m0, s54
	s_nop 0
	global_load_lds_dwordx4 v130, s[46:47]
	s_waitcnt vmcnt(8)
	s_waitcnt lgkmcnt(0)
	s_barrier
	s_setprio 1
	s_waitcnt lgkmcnt(0)
	v_mfma_f32_16x16x32_bf16 v[60:63], v[148:151], v[180:183], v[60:63]
	v_mfma_f32_16x16x32_bf16 v[56:59], v[156:159], v[180:183], v[56:59]
	v_mfma_f32_16x16x32_bf16 v[44:47], v[148:151], v[188:191], v[44:47]
	v_mfma_f32_16x16x32_bf16 v[40:43], v[156:159], v[188:191], v[40:43]
	v_mfma_f32_16x16x32_bf16 v[28:31], v[148:151], v[196:199], v[28:31]
	v_mfma_f32_16x16x32_bf16 v[24:27], v[156:159], v[196:199], v[24:27]
	v_mfma_f32_16x16x32_bf16 v[12:15], v[148:151], v[204:207], v[12:15]
	v_mfma_f32_16x16x32_bf16 v[8:11], v[156:159], v[204:207], v[8:11]
	v_mfma_f32_16x16x32_bf16 v[60:63], v[152:155], v[184:187], v[60:63]
	v_mfma_f32_16x16x32_bf16 v[56:59], v[160:163], v[184:187], v[56:59]
	v_mfma_f32_16x16x32_bf16 v[44:47], v[152:155], v[192:195], v[44:47]
	v_mfma_f32_16x16x32_bf16 v[40:43], v[160:163], v[192:195], v[40:43]
	v_mfma_f32_16x16x32_bf16 v[28:31], v[152:155], v[200:203], v[28:31]
	v_mfma_f32_16x16x32_bf16 v[24:27], v[160:163], v[200:203], v[24:27]
	v_mfma_f32_16x16x32_bf16 v[12:15], v[152:155], v[208:211], v[12:15]
	v_mfma_f32_16x16x32_bf16 v[8:11], v[160:163], v[208:211], v[8:11]
	s_setprio 0
	s_setprio 1
	v_mfma_f32_16x16x32_bf16 v[52:55], v[164:167], v[180:183], v[52:55]
	v_mfma_f32_16x16x32_bf16 v[48:51], v[172:175], v[180:183], v[48:51]
	v_mfma_f32_16x16x32_bf16 v[36:39], v[164:167], v[188:191], v[36:39]
	v_mfma_f32_16x16x32_bf16 v[32:35], v[172:175], v[188:191], v[32:35]
	v_mfma_f32_16x16x32_bf16 v[20:23], v[164:167], v[196:199], v[20:23]
	v_mfma_f32_16x16x32_bf16 v[16:19], v[172:175], v[196:199], v[16:19]
	v_mfma_f32_16x16x32_bf16 v[4:7], v[164:167], v[204:207], v[4:7]
	v_mfma_f32_16x16x32_bf16 v[0:3], v[172:175], v[204:207], v[0:3]
	v_mfma_f32_16x16x32_bf16 v[52:55], v[168:171], v[184:187], v[52:55]
	v_mfma_f32_16x16x32_bf16 v[48:51], v[176:179], v[184:187], v[48:51]
	v_mfma_f32_16x16x32_bf16 v[36:39], v[168:171], v[192:195], v[36:39]
	v_mfma_f32_16x16x32_bf16 v[32:35], v[176:179], v[192:195], v[32:35]
	v_mfma_f32_16x16x32_bf16 v[20:23], v[168:171], v[200:203], v[20:23]
	v_mfma_f32_16x16x32_bf16 v[16:19], v[176:179], v[200:203], v[16:19]
	v_mfma_f32_16x16x32_bf16 v[4:7], v[168:171], v[208:211], v[4:7]
	v_mfma_f32_16x16x32_bf16 v[0:3], v[176:179], v[208:211], v[0:3]
	s_setprio 0
	s_barrier
	s_cmp_gt_u32 s62, 29
	s_mov_b32 s62, s11
	s_cbranch_scc1 .LBB0_126
; #define PG8_STAGE(bufoff, gbase, voff) do { _Pragma("unroll") for (int _i = 0; _i < 2; ++_i) \
;         __builtin_amdgcn_global_load_lds((const unsigned*)((const char*)(gbase) + (voff)[_i]), (LAS unsigned*)(lds + (bufoff) + ldsw + _i * 8192), 16, 0, 0); } while (0)
; #define PG8_LDA(dst, b, h) do { _Pragma("unroll") for (int m = 0; m < 4; ++m) _Pragma("unroll") for (int k = 0; k < 2; ++k) dst[m][k] = *(const LAS bf16x8*)(lds + PG8_SA(b, h) + aoff + m * 2048 + k * 1024); } while (0)
; #define PG8_LDB(dst, b, h) do { _Pragma("unroll") for (int n = 0; n < 2; ++n) _Pragma("unroll") for (int k = 0; k < 2; ++k) dst[n][k] = *(const LAS bf16x8*)(lds + PG8_SB(b, h) + boff + n * 2048 + k * 1024); } while (0)
; #define PG8_SCHED __builtin_amdgcn_sched_barrier(0)
; template <class Epi>
; __device__ __forceinline__ void gemm_phase(LAS unsigned char* lds, const Gemm g, const StaticOrder S, const Epi E) {
;     ...
;             const bool last = (t == nt - 2);
;             const char* a1 = cA + (long)(t + 1) * ksc;
;             const char* a2 = last ? nA : cA + (long)(t + 2) * ksc; const char* b2 = last ? nB : cB + (long)(t + 2) * ksc;
;             const long ks3 = last ? ksn : ksc;
;             const char* a3 = a2 + ks3; const char* b3 = b2 + ks3;
;             PG8_LDB(B0, 0, 0); PG8_LDB(B1, 0, 1); PG8_SCHED; PG8_LDA(At, 0, 0); PG8_STAGE(PG8_SA(1, 1), a1 + hstepA, voffA);
.LBB0_122:
	ds_read_b128 v[148:151], v254
	ds_read_b128 v[152:155], v254 offset:1024
	ds_read_b128 v[156:159], v254 offset:2048
	ds_read_b128 v[160:163], v254 offset:3072
	ds_read_b128 v[164:167], v254 offset:16384
	ds_read_b128 v[168:171], v254 offset:17408
	ds_read_b128 v[172:175], v254 offset:18432
	ds_read_b128 v[176:179], v254 offset:19456
	ds_read_b128 v[180:183], v145
	ds_read_b128 v[184:187], v145 offset:1024
	ds_read_b128 v[188:191], v145 offset:2048
	ds_read_b128 v[192:195], v145 offset:3072
	ds_read_b128 v[196:199], v145 offset:4096
	ds_read_b128 v[200:203], v145 offset:5120
	ds_read_b128 v[204:207], v145 offset:6144
	ds_read_b128 v[208:211], v145 offset:7168
	s_cmp_lg_u32 s62, 30
	s_cselect_b64 s[40:41], -1, 0
	s_cmp_eq_u32 s62, 30
	s_mov_b64 s[44:45], s[30:31]
	s_cbranch_scc1 .LBB0_124
	s_add_i32 s11, s62, 2
	s_mul_i32 s13, s27, s11
	s_mul_hi_u32 s42, s26, s11
	s_add_i32 s42, s42, s13
	s_mul_i32 s11, s26, s11
	s_add_u32 s44, s24, s11
	s_addc_u32 s45, s25, s42

; #define PG8_STAGE(bufoff, gbase, voff) do { _Pragma("unroll") for (int _i = 0; _i < 2; ++_i) \
;         __builtin_amdgcn_global_load_lds((const unsigned*)((const char*)(gbase) + (voff)[_i]), (LAS unsigned*)(lds + (bufoff) + ldsw + _i * 8192), 16, 0, 0); } while (0)
; #define PG8_LDA(dst, b, h) do { _Pragma("unroll") for (int m = 0; m < 4; ++m) _Pragma("unroll") for (int k = 0; k < 2; ++k) dst[m][k] = *(const LAS bf16x8*)(lds + PG8_SA(b, h) + aoff + m * 2048 + k * 1024); } while (0)
; #define PG8_LDB(dst, b, h) do { _Pragma("unroll") for (int n = 0; n < 2; ++n) _Pragma("unroll") for (int k = 0; k < 2; ++k) dst[n][k] = *(const LAS bf16x8*)(lds + PG8_SB(b, h) + boff + n * 2048 + k * 1024); } while (0)
; #define PG8_MMA(ai, bj, At, Bt) do { __builtin_amdgcn_s_setprio(1); _Pragma("unroll") for (int m = 0; m < 4; ++m) _Pragma("unroll") for (int n = 0; n < 2; ++n) _Pragma("unroll") for (int k = 0; k < 2; ++k) \
;         acc[ai][bj][m][n] = __builtin_amdgcn_mfma_f32_16x16x32_bf16(Bt[n][k], At[m][k], acc[ai][bj][m][n], 0, 0, 0); __builtin_amdgcn_s_setprio(0); } while (0)
; #define PG8_WAIT_V(n) asm volatile("s_waitcnt vmcnt(" #n ")" ::: "memory")
; #define PG8_WAIT_L(n) asm volatile("s_waitcnt lgkmcnt(" #n ")" ::: "memory")
; #define PG8_BAR __builtin_amdgcn_s_barrier()
; #define PG8_SCHED __builtin_amdgcn_sched_barrier(0)
; template <class Epi>
; __device__ __forceinline__ void gemm_phase(LAS unsigned char* lds, const Gemm g, const StaticOrder S, const Epi E) {
;     ...
;             PG8_LDB(B0, 0, 0); PG8_LDB(B1, 0, 1); PG8_SCHED; PG8_LDA(At, 0, 0); PG8_STAGE(PG8_SA(1, 1), a1 + hstepA, voffA);
;             PG8_WAIT_V(8); PG8_WAIT_L(0); PG8_BAR; PG8_MMA(0, 0, At, B0); PG8_MMA(0, 1, At, B1); PG8_BAR; PG8_SCHED;
;             PG8_LDA(At, 0, 1); PG8_STAGE(PG8_SB(0, 0), b2, voffB); PG8_STAGE(PG8_SB(0, 1), b2 + hstepB, voffB); PG8_STAGE(PG8_SA(0, 0), a2, voffA);
;             PG8_WAIT_V(8); PG8_WAIT_L(0); PG8_BAR; PG8_MMA(1, 0, At, B0); PG8_MMA(1, 1, At, B1); PG8_BAR; PG8_SCHED;
.LBB0_206:
	s_or_b32 s48, s70, 1
	s_mul_i32 s49, s35, s48
	s_mul_hi_u32 s72, s34, s48
	s_add_i32 s72, s72, s49
	s_mul_i32 s48, s34, s48
	s_add_u32 s73, s30, s48
	s_addc_u32 s74, s31, s72
	s_add_u32 s48, s46, s44
	s_addc_u32 s49, s47, s45
	s_add_u32 s72, s73, 0x160000
	s_addc_u32 s73, s74, 0
	s_add_i32 m0, s50, 0xc000
	global_load_lds_dwordx4 v140, s[72:73]
	s_add_i32 m0, s50, 0xe000
	s_nop 0
	global_load_lds_dwordx4 v144, s[72:73]
	s_waitcnt vmcnt(8)
	s_waitcnt lgkmcnt(0)
	s_barrier
	s_setprio 1
	s_waitcnt lgkmcnt(0)
	v_mfma_f32_16x16x32_bf16 v[124:127], v[128:131], v[180:183], v[124:127]
	v_mfma_f32_16x16x32_bf16 v[120:123], v[136:139], v[180:183], v[120:123]
	v_mfma_f32_16x16x32_bf16 v[108:111], v[128:131], v[188:191], v[108:111]
	v_mfma_f32_16x16x32_bf16 v[104:107], v[136:139], v[188:191], v[104:107]
	v_mfma_f32_16x16x32_bf16 v[92:95], v[128:131], v[196:199], v[92:95]
	v_mfma_f32_16x16x32_bf16 v[88:91], v[136:139], v[196:199], v[88:91]
	v_mfma_f32_16x16x32_bf16 v[76:79], v[128:131], v[204:207], v[76:79]
	v_mfma_f32_16x16x32_bf16 v[72:75], v[136:139], v[204:207], v[72:75]
	v_mfma_f32_16x16x32_bf16 v[124:127], v[132:135], v[184:187], v[124:127]
	v_mfma_f32_16x16x32_bf16 v[120:123], v[152:155], v[184:187], v[120:123]
	v_mfma_f32_16x16x32_bf16 v[108:111], v[132:135], v[192:195], v[108:111]
	v_mfma_f32_16x16x32_bf16 v[104:107], v[152:155], v[192:195], v[104:107]
	v_mfma_f32_16x16x32_bf16 v[92:95], v[132:135], v[200:203], v[92:95]
	v_mfma_f32_16x16x32_bf16 v[88:91], v[152:155], v[200:203], v[88:91]
	v_mfma_f32_16x16x32_bf16 v[76:79], v[132:135], v[208:211], v[76:79]
	v_mfma_f32_16x16x32_bf16 v[72:75], v[152:155], v[208:211], v[72:75]
	s_setprio 0
	s_setprio 1
	v_mfma_f32_16x16x32_bf16 v[116:119], v[156:159], v[180:183], v[116:119]
	v_mfma_f32_16x16x32_bf16 v[112:115], v[172:175], v[180:183], v[112:115]
	v_mfma_f32_16x16x32_bf16 v[100:103], v[156:159], v[188:191], v[100:103]
	v_mfma_f32_16x16x32_bf16 v[96:99], v[172:175], v[188:191], v[96:99]
	v_mfma_f32_16x16x32_bf16 v[84:87], v[156:159], v[196:199], v[84:87]
	v_mfma_f32_16x16x32_bf16 v[80:83], v[172:175], v[196:199], v[80:83]
	v_mfma_f32_16x16x32_bf16 v[68:71], v[156:159], v[204:207], v[68:71]
	v_mfma_f32_16x16x32_bf16 v[64:67], v[172:175], v[204:207], v[64:67]
	v_mfma_f32_16x16x32_bf16 v[116:119], v[168:171], v[184:187], v[116:119]
	v_mfma_f32_16x16x32_bf16 v[112:115], v[176:179], v[184:187], v[112:115]
	v_mfma_f32_16x16x32_bf16 v[100:103], v[168:171], v[192:195], v[100:103]
	v_mfma_f32_16x16x32_bf16 v[96:99], v[176:179], v[192:195], v[96:99]
	v_mfma_f32_16x16x32_bf16 v[84:87], v[168:171], v[200:203], v[84:87]
	v_mfma_f32_16x16x32_bf16 v[80:83], v[176:179], v[200:203], v[80:83]
	v_mfma_f32_16x16x32_bf16 v[68:71], v[168:171], v[208:211], v[68:71]
	v_mfma_f32_16x16x32_bf16 v[64:67], v[176:179], v[208:211], v[64:67]
	s_setprio 0
	s_barrier
	s_add_i32 s72, s59, s33
	s_mov_b32 m0, s72
	ds_read_b128 v[180:183], v166 offset:16384
	ds_read_b128 v[184:187], v166 offset:17408
	ds_read_b128 v[188:191], v166 offset:18432
	ds_read_b128 v[192:195], v166 offset:19456
	ds_read_b128 v[196:199], v166 offset:20480
	ds_read_b128 v[200:203], v166 offset:21504
	ds_read_b128 v[204:207], v166 offset:22528
	ds_read_b128 v[208:211], v166 offset:23552
	global_load_lds_dwordx4 v142, s[42:43]
	s_add_i32 m0, s72, 0x2000
	s_add_u32 s72, s42, 0x160000
	s_addc_u32 s73, s43, 0
	s_add_i32 s74, s60, s33
	global_load_lds_dwordx4 v146, s[42:43]
	s_mov_b32 m0, s74
	s_nop 0
	global_load_lds_dwordx4 v142, s[72:73]
	s_add_i32 m0, s74, 0x2000
	s_nop 0
	global_load_lds_dwordx4 v146, s[72:73]
	s_mov_b32 m0, s50
	s_nop 0
	global_load_lds_dwordx4 v140, s[46:47]
	s_mov_b32 m0, s51
	s_nop 0
	global_load_lds_dwordx4 v144, s[46:47]
	s_waitcnt vmcnt(8)
	s_waitcnt lgkmcnt(0)
	s_barrier
	s_setprio 1
	s_waitcnt lgkmcnt(0)
	v_mfma_f32_16x16x32_bf16 v[60:63], v[128:131], v[180:183], v[60:63]
	v_mfma_f32_16x16x32_bf16 v[56:59], v[136:139], v[180:183], v[56:59]
	v_mfma_f32_16x16x32_bf16 v[44:47], v[128:131], v[188:191], v[44:47]
	v_mfma_f32_16x16x32_bf16 v[40:43], v[136:139], v[188:191], v[40:43]
	v_mfma_f32_16x16x32_bf16 v[28:31], v[128:131], v[196:199], v[28:31]
	v_mfma_f32_16x16x32_bf16 v[24:27], v[136:139], v[196:199], v[24:27]
	v_mfma_f32_16x16x32_bf16 v[12:15], v[128:131], v[204:207], v[12:15]
	v_mfma_f32_16x16x32_bf16 v[8:11], v[136:139], v[204:207], v[8:11]
	v_mfma_f32_16x16x32_bf16 v[60:63], v[132:135], v[184:187], v[60:63]
	v_mfma_f32_16x16x32_bf16 v[56:59], v[152:155], v[184:187], v[56:59]
	v_mfma_f32_16x16x32_bf16 v[44:47], v[132:135], v[192:195], v[44:47]
	v_mfma_f32_16x16x32_bf16 v[40:43], v[152:155], v[192:195], v[40:43]
	v_mfma_f32_16x16x32_bf16 v[28:31], v[132:135], v[200:203], v[28:31]
	v_mfma_f32_16x16x32_bf16 v[24:27], v[152:155], v[200:203], v[24:27]
	v_mfma_f32_16x16x32_bf16 v[12:15], v[132:135], v[208:211], v[12:15]
	v_mfma_f32_16x16x32_bf16 v[8:11], v[152:155], v[208:211], v[8:11]
	s_setprio 0
	s_setprio 1
	v_mfma_f32_16x16x32_bf16 v[52:55], v[156:159], v[180:183], v[52:55]
	v_mfma_f32_16x16x32_bf16 v[48:51], v[172:175], v[180:183], v[48:51]
	v_mfma_f32_16x16x32_bf16 v[36:39], v[156:159], v[188:191], v[36:39]
	v_mfma_f32_16x16x32_bf16 v[32:35], v[172:175], v[188:191], v[32:35]
	v_mfma_f32_16x16x32_bf16 v[20:23], v[156:159], v[196:199], v[20:23]
	v_mfma_f32_16x16x32_bf16 v[16:19], v[172:175], v[196:199], v[16:19]
	v_mfma_f32_16x16x32_bf16 v[4:7], v[156:159], v[204:207], v[4:7]
	v_mfma_f32_16x16x32_bf16 v[0:3], v[172:175], v[204:207], v[0:3]
	v_mfma_f32_16x16x32_bf16 v[52:55], v[168:171], v[184:187], v[52:55]
	v_mfma_f32_16x16x32_bf16 v[48:51], v[176:179], v[184:187], v[48:51]
	v_mfma_f32_16x16x32_bf16 v[36:39], v[168:171], v[192:195], v[36:39]
	v_mfma_f32_16x16x32_bf16 v[32:35], v[176:179], v[192:195], v[32:35]
	v_mfma_f32_16x16x32_bf16 v[20:23], v[168:171], v[200:203], v[20:23]
	v_mfma_f32_16x16x32_bf16 v[16:19], v[176:179], v[200:203], v[16:19]
	v_mfma_f32_16x16x32_bf16 v[4:7], v[168:171], v[208:211], v[4:7]
	v_mfma_f32_16x16x32_bf16 v[0:3], v[176:179], v[208:211], v[0:3]
	s_setprio 0
	s_barrier
; #define PG8_STAGE(bufoff, gbase, voff) do { _Pragma("unroll") for (int _i = 0; _i < 2; ++_i) \
;         __builtin_amdgcn_global_load_lds((const unsigned*)((const char*)(gbase) + (voff)[_i]), (LAS unsigned*)(lds + (bufoff) + ldsw + _i * 8192), 16, 0, 0); } while (0)
; #define PG8_LDA(dst, b, h) do { _Pragma("unroll") for (int m = 0; m < 4; ++m) _Pragma("unroll") for (int k = 0; k < 2; ++k) dst[m][k] = *(const LAS bf16x8*)(lds + PG8_SA(b, h) + aoff + m * 2048 + k * 1024); } while (0)
; #define PG8_LDB(dst, b, h) do { _Pragma("unroll") for (int n = 0; n < 2; ++n) _Pragma("unroll") for (int k = 0; k < 2; ++k) dst[n][k] = *(const LAS bf16x8*)(lds + PG8_SB(b, h) + boff + n * 2048 + k * 1024); } while (0)
; #define PG8_MMA(ai, bj, At, Bt) do { __builtin_amdgcn_s_setprio(1); _Pragma("unroll") for (int m = 0; m < 4; ++m) _Pragma("unroll") for (int n = 0; n < 2; ++n) _Pragma("unroll") for (int k = 0; k < 2; ++k) \
;         acc[ai][bj][m][n] = __builtin_amdgcn_mfma_f32_16x16x32_bf16(Bt[n][k], At[m][k], acc[ai][bj][m][n], 0, 0, 0); __builtin_amdgcn_s_setprio(0); } while (0)
; #define PG8_WAIT_V(n) asm volatile("s_waitcnt vmcnt(" #n ")" ::: "memory")
; #define PG8_WAIT_L(n) asm volatile("s_waitcnt lgkmcnt(" #n ")" ::: "memory")
; #define PG8_BAR __builtin_amdgcn_s_barrier()
; #define PG8_SCHED __builtin_amdgcn_sched_barrier(0)
; template <class Epi>
; __device__ __forceinline__ void gemm_phase(LAS unsigned char* lds, const Gemm g, const StaticOrder S, const Epi E) {
;     ...
;         for (int t = 0; t < nt; t += 2) {
;     ...
;             PG8_LDB(B0, 1, 0); PG8_LDB(B1, 1, 1); PG8_SCHED; PG8_LDA(At, 1, 0); PG8_STAGE(PG8_SA(0, 1), a2 + hstepA, voffA);
;             PG8_WAIT_V(8); PG8_WAIT_L(0); PG8_BAR; PG8_MMA(0, 0, At, B0); PG8_MMA(0, 1, At, B1); PG8_BAR; PG8_SCHED;
;             PG8_LDA(At, 1, 1); PG8_STAGE(PG8_SB(1, 0), b3, voffB); PG8_STAGE(PG8_SB(1, 1), b3 + hstepB, voffB); PG8_STAGE(PG8_SA(1, 0), a3, voffA);
;             PG8_WAIT_V(8); PG8_WAIT_L(0); PG8_BAR; PG8_MMA(1, 0, At, B0); PG8_MMA(1, 1, At, B1); PG8_BAR; PG8_SCHED;
	s_add_i32 s72, 0, 0x18000
	s_add_i32 s73, 0, 0x1c000
	v_add_u32_e32 v152, s72, v164
	v_add_u32_e32 v176, s73, v164
	ds_read_b128 v[128:131], v152
	ds_read_b128 v[132:135], v152 offset:1024
	ds_read_b128 v[136:139], v152 offset:2048
	ds_read_b128 v[152:155], v152 offset:3072
	ds_read_b128 v[156:159], v176
	ds_read_b128 v[168:171], v176 offset:1024
	ds_read_b128 v[172:175], v176 offset:2048
	ds_read_b128 v[176:179], v176 offset:3072
	s_add_u32 s46, s46, 0x160000
	s_addc_u32 s47, s47, 0
	s_mov_b32 m0, s52
	ds_read_b128 v[180:183], v166 offset:32768
	ds_read_b128 v[184:187], v166 offset:33792
	ds_read_b128 v[188:191], v166 offset:34816
	ds_read_b128 v[192:195], v166 offset:35840
	ds_read_b128 v[196:199], v166 offset:36864
	ds_read_b128 v[200:203], v166 offset:37888
	ds_read_b128 v[204:207], v166 offset:38912
	ds_read_b128 v[208:211], v166 offset:39936
	global_load_lds_dwordx4 v140, s[46:47]
	s_mov_b32 m0, s53
	s_nop 0
	global_load_lds_dwordx4 v144, s[46:47]
	s_waitcnt vmcnt(8)
	s_waitcnt lgkmcnt(0)
	s_barrier
	s_setprio 1
	s_waitcnt lgkmcnt(0)
	v_mfma_f32_16x16x32_bf16 v[124:127], v[128:131], v[180:183], v[124:127]
	v_mfma_f32_16x16x32_bf16 v[120:123], v[136:139], v[180:183], v[120:123]
	v_mfma_f32_16x16x32_bf16 v[108:111], v[128:131], v[188:191], v[108:111]
	v_mfma_f32_16x16x32_bf16 v[104:107], v[136:139], v[188:191], v[104:107]
	v_mfma_f32_16x16x32_bf16 v[92:95], v[128:131], v[196:199], v[92:95]
	v_mfma_f32_16x16x32_bf16 v[88:91], v[136:139], v[196:199], v[88:91]
	v_mfma_f32_16x16x32_bf16 v[76:79], v[128:131], v[204:207], v[76:79]
	v_mfma_f32_16x16x32_bf16 v[72:75], v[136:139], v[204:207], v[72:75]
	v_mfma_f32_16x16x32_bf16 v[124:127], v[132:135], v[184:187], v[124:127]
	v_mfma_f32_16x16x32_bf16 v[120:123], v[152:155], v[184:187], v[120:123]
	v_mfma_f32_16x16x32_bf16 v[108:111], v[132:135], v[192:195], v[108:111]
	v_mfma_f32_16x16x32_bf16 v[104:107], v[152:155], v[192:195], v[104:107]
	v_mfma_f32_16x16x32_bf16 v[92:95], v[132:135], v[200:203], v[92:95]
	v_mfma_f32_16x16x32_bf16 v[88:91], v[152:155], v[200:203], v[88:91]
	v_mfma_f32_16x16x32_bf16 v[76:79], v[132:135], v[208:211], v[76:79]
	v_mfma_f32_16x16x32_bf16 v[72:75], v[152:155], v[208:211], v[72:75]
	s_setprio 0
	s_setprio 1
	v_mfma_f32_16x16x32_bf16 v[116:119], v[156:159], v[180:183], v[116:119]
	v_mfma_f32_16x16x32_bf16 v[112:115], v[172:175], v[180:183], v[112:115]
	v_mfma_f32_16x16x32_bf16 v[100:103], v[156:159], v[188:191], v[100:103]
	v_mfma_f32_16x16x32_bf16 v[96:99], v[172:175], v[188:191], v[96:99]
	v_mfma_f32_16x16x32_bf16 v[84:87], v[156:159], v[196:199], v[84:87]
	v_mfma_f32_16x16x32_bf16 v[80:83], v[172:175], v[196:199], v[80:83]
	v_mfma_f32_16x16x32_bf16 v[68:71], v[156:159], v[204:207], v[68:71]
	v_mfma_f32_16x16x32_bf16 v[64:67], v[172:175], v[204:207], v[64:67]
	v_mfma_f32_16x16x32_bf16 v[116:119], v[168:171], v[184:187], v[116:119]
	v_mfma_f32_16x16x32_bf16 v[112:115], v[176:179], v[184:187], v[112:115]
	v_mfma_f32_16x16x32_bf16 v[100:103], v[168:171], v[192:195], v[100:103]
	v_mfma_f32_16x16x32_bf16 v[96:99], v[176:179], v[192:195], v[96:99]
	v_mfma_f32_16x16x32_bf16 v[84:87], v[168:171], v[200:203], v[84:87]
	v_mfma_f32_16x16x32_bf16 v[80:83], v[176:179], v[200:203], v[80:83]
	v_mfma_f32_16x16x32_bf16 v[68:71], v[168:171], v[208:211], v[68:71]
	v_mfma_f32_16x16x32_bf16 v[64:67], v[176:179], v[208:211], v[64:67]
	s_setprio 0
	s_barrier
	s_add_u32 s42, s42, s44
	s_addc_u32 s43, s43, s45
	s_add_i32 s44, s72, s33
	s_mov_b32 m0, s44
	ds_read_b128 v[180:183], v166 offset:49152
	ds_read_b128 v[184:187], v166 offset:50176
	ds_read_b128 v[188:191], v166 offset:51200
	ds_read_b128 v[192:195], v166 offset:52224
	ds_read_b128 v[196:199], v166 offset:53248
	ds_read_b128 v[200:203], v166 offset:54272
	ds_read_b128 v[204:207], v166 offset:55296
	ds_read_b128 v[208:211], v166 offset:56320
	global_load_lds_dwordx4 v142, s[42:43]
	s_add_i32 m0, s44, 0x2000
	s_nop 0
	global_load_lds_dwordx4 v146, s[42:43]
	s_add_u32 s42, s42, 0x160000
	s_addc_u32 s43, s43, 0
	s_add_i32 s44, s73, s33
	s_mov_b32 m0, s44
	s_nop 0
	global_load_lds_dwordx4 v142, s[42:43]
	s_add_i32 m0, s44, 0x2000
	s_nop 0
	global_load_lds_dwordx4 v146, s[42:43]
	s_mov_b32 m0, s55
	s_nop 0
	global_load_lds_dwordx4 v140, s[48:49]
	s_mov_b32 m0, s56
	s_nop 0
	global_load_lds_dwordx4 v144, s[48:49]
	s_waitcnt vmcnt(8)
	s_waitcnt lgkmcnt(0)
	s_barrier
	s_setprio 1
	s_waitcnt lgkmcnt(0)
	v_mfma_f32_16x16x32_bf16 v[60:63], v[128:131], v[180:183], v[60:63]
	v_mfma_f32_16x16x32_bf16 v[56:59], v[136:139], v[180:183], v[56:59]
	v_mfma_f32_16x16x32_bf16 v[44:47], v[128:131], v[188:191], v[44:47]
	v_mfma_f32_16x16x32_bf16 v[40:43], v[136:139], v[188:191], v[40:43]
	v_mfma_f32_16x16x32_bf16 v[28:31], v[128:131], v[196:199], v[28:31]
	v_mfma_f32_16x16x32_bf16 v[24:27], v[136:139], v[196:199], v[24:27]
	v_mfma_f32_16x16x32_bf16 v[12:15], v[128:131], v[204:207], v[12:15]
	v_mfma_f32_16x16x32_bf16 v[8:11], v[136:139], v[204:207], v[8:11]
	v_mfma_f32_16x16x32_bf16 v[60:63], v[132:135], v[184:187], v[60:63]
	v_mfma_f32_16x16x32_bf16 v[56:59], v[152:155], v[184:187], v[56:59]
	v_mfma_f32_16x16x32_bf16 v[44:47], v[132:135], v[192:195], v[44:47]
	v_mfma_f32_16x16x32_bf16 v[40:43], v[152:155], v[192:195], v[40:43]
	v_mfma_f32_16x16x32_bf16 v[28:31], v[132:135], v[200:203], v[28:31]
	v_mfma_f32_16x16x32_bf16 v[24:27], v[152:155], v[200:203], v[24:27]
	v_mfma_f32_16x16x32_bf16 v[12:15], v[132:135], v[208:211], v[12:15]
	v_mfma_f32_16x16x32_bf16 v[8:11], v[152:155], v[208:211], v[8:11]
	s_setprio 0
	s_setprio 1
	v_mfma_f32_16x16x32_bf16 v[52:55], v[156:159], v[180:183], v[52:55]
	v_mfma_f32_16x16x32_bf16 v[48:51], v[172:175], v[180:183], v[48:51]
	v_mfma_f32_16x16x32_bf16 v[36:39], v[156:159], v[188:191], v[36:39]
	v_mfma_f32_16x16x32_bf16 v[32:35], v[172:175], v[188:191], v[32:35]
	v_mfma_f32_16x16x32_bf16 v[20:23], v[156:159], v[196:199], v[20:23]
	v_mfma_f32_16x16x32_bf16 v[16:19], v[172:175], v[196:199], v[16:19]
	v_mfma_f32_16x16x32_bf16 v[4:7], v[156:159], v[204:207], v[4:7]
	v_mfma_f32_16x16x32_bf16 v[0:3], v[172:175], v[204:207], v[0:3]
	v_mfma_f32_16x16x32_bf16 v[52:55], v[168:171], v[184:187], v[52:55]
	v_mfma_f32_16x16x32_bf16 v[48:51], v[176:179], v[184:187], v[48:51]
	v_mfma_f32_16x16x32_bf16 v[36:39], v[168:171], v[192:195], v[36:39]
	v_mfma_f32_16x16x32_bf16 v[32:35], v[176:179], v[192:195], v[32:35]
	v_mfma_f32_16x16x32_bf16 v[20:23], v[168:171], v[200:203], v[20:23]
	v_mfma_f32_16x16x32_bf16 v[16:19], v[176:179], v[200:203], v[16:19]
	v_mfma_f32_16x16x32_bf16 v[4:7], v[168:171], v[208:211], v[4:7]
	v_mfma_f32_16x16x32_bf16 v[0:3], v[176:179], v[208:211], v[0:3]
	s_setprio 0
	s_barrier
	s_cmpk_gt_u32 s70, 0x55
	s_mov_b32 s70, s71
	s_cbranch_scc1 .LBB0_211
; #define PG8_STAGE(bufoff, gbase, voff) do { _Pragma("unroll") for (int _i = 0; _i < 2; ++_i) \
;         __builtin_amdgcn_global_load_lds((const unsigned*)((const char*)(gbase) + (voff)[_i]), (LAS unsigned*)(lds + (bufoff) + ldsw + _i * 8192), 16, 0, 0); } while (0)
; #define PG8_LDA(dst, b, h) do { _Pragma("unroll") for (int m = 0; m < 4; ++m) _Pragma("unroll") for (int k = 0; k < 2; ++k) dst[m][k] = *(const LAS bf16x8*)(lds + PG8_SA(b, h) + aoff + m * 2048 + k * 1024); } while (0)
; #define PG8_LDB(dst, b, h) do { _Pragma("unroll") for (int n = 0; n < 2; ++n) _Pragma("unroll") for (int k = 0; k < 2; ++k) dst[n][k] = *(const LAS bf16x8*)(lds + PG8_SB(b, h) + boff + n * 2048 + k * 1024); } while (0)
; #define PG8_SCHED __builtin_amdgcn_sched_barrier(0)
; template <class Epi>
; __device__ __forceinline__ void gemm_phase(LAS unsigned char* lds, const Gemm g, const StaticOrder S, const Epi E) {
;     ...
;             const bool last = (t == nt - 2);
;             const char* a1 = cA + (long)(t + 1) * ksc;
;             const char* a2 = last ? nA : cA + (long)(t + 2) * ksc; const char* b2 = last ? nB : cB + (long)(t + 2) * ksc;
;             const long ks3 = last ? ksn : ksc;
;             const char* a3 = a2 + ks3; const char* b3 = b2 + ks3;
;             PG8_LDB(B0, 0, 0); PG8_LDB(B1, 0, 1); PG8_SCHED; PG8_LDA(At, 0, 0); PG8_STAGE(PG8_SA(1, 1), a1 + hstepA, voffA);
.LBB0_207:
	v_add_u32_e32 v152, s59, v164
	v_add_u32_e32 v176, s60, v164
	ds_read_b128 v[128:131], v152
	ds_read_b128 v[132:135], v152 offset:1024
	ds_read_b128 v[136:139], v152 offset:2048
	ds_read_b128 v[152:155], v152 offset:3072
	ds_read_b128 v[156:159], v176
	ds_read_b128 v[168:171], v176 offset:1024
	ds_read_b128 v[172:175], v176 offset:2048
	ds_read_b128 v[176:179], v176 offset:3072
	ds_read_b128 v[180:183], v166
	ds_read_b128 v[184:187], v166 offset:1024
	ds_read_b128 v[188:191], v166 offset:2048
	ds_read_b128 v[192:195], v166 offset:3072
	ds_read_b128 v[196:199], v166 offset:4096
	ds_read_b128 v[200:203], v166 offset:5120
	ds_read_b128 v[204:207], v166 offset:6144
	ds_read_b128 v[208:211], v166 offset:7168
	s_cmpk_lg_i32 s70, 0x56
	s_cselect_b64 s[42:43], -1, 0
	s_cmpk_eq_i32 s70, 0x56
	s_mov_b64 s[46:47], s[22:23]
	s_cbranch_scc1 .LBB0_209
	s_add_i32 s44, s70, 2
	s_mul_i32 s45, s35, s44
	s_mul_hi_u32 s46, s34, s44
	s_add_i32 s45, s46, s45
	s_mul_i32 s44, s34, s44
	s_add_u32 s46, s30, s44
	s_addc_u32 s47, s31, s45

; #define PG8_STAGE(bufoff, gbase, voff) do { _Pragma("unroll") for (int _i = 0; _i < 2; ++_i) \
;         __builtin_amdgcn_global_load_lds((const unsigned*)((const char*)(gbase) + (voff)[_i]), (LAS unsigned*)(lds + (bufoff) + ldsw + _i * 8192), 16, 0, 0); } while (0)
; #define PG8_LDA(dst, b, h) do { _Pragma("unroll") for (int m = 0; m < 4; ++m) _Pragma("unroll") for (int k = 0; k < 2; ++k) dst[m][k] = *(const LAS bf16x8*)(lds + PG8_SA(b, h) + aoff + m * 2048 + k * 1024); } while (0)
; #define PG8_LDB(dst, b, h) do { _Pragma("unroll") for (int n = 0; n < 2; ++n) _Pragma("unroll") for (int k = 0; k < 2; ++k) dst[n][k] = *(const LAS bf16x8*)(lds + PG8_SB(b, h) + boff + n * 2048 + k * 1024); } while (0)
; #define PG8_MMA(ai, bj, At, Bt) do { __builtin_amdgcn_s_setprio(1); _Pragma("unroll") for (int m = 0; m < 4; ++m) _Pragma("unroll") for (int n = 0; n < 2; ++n) _Pragma("unroll") for (int k = 0; k < 2; ++k) \
;         acc[ai][bj][m][n] = __builtin_amdgcn_mfma_f32_16x16x32_bf16(Bt[n][k], At[m][k], acc[ai][bj][m][n], 0, 0, 0); __builtin_amdgcn_s_setprio(0); } while (0)
; #define PG8_WAIT_V(n) asm volatile("s_waitcnt vmcnt(" #n ")" ::: "memory")
; #define PG8_WAIT_L(n) asm volatile("s_waitcnt lgkmcnt(" #n ")" ::: "memory")
; #define PG8_BAR __builtin_amdgcn_s_barrier()
; #define PG8_SCHED __builtin_amdgcn_sched_barrier(0)
; template <class Epi>
; __device__ __forceinline__ void gemm_phase(LAS unsigned char* lds, const Gemm g, const StaticOrder S, const Epi E) {
;     ...
;             PG8_LDB(B0, 0, 0); PG8_LDB(B1, 0, 1); PG8_SCHED; PG8_LDA(At, 0, 0); PG8_STAGE(PG8_SA(1, 1), a1 + hstepA, voffA);
;             PG8_WAIT_V(8); PG8_WAIT_L(0); PG8_BAR; PG8_MMA(0, 0, At, B0); PG8_MMA(0, 1, At, B1); PG8_BAR; PG8_SCHED;
;             PG8_LDA(At, 0, 1); PG8_STAGE(PG8_SB(0, 0), b2, voffB); PG8_STAGE(PG8_SB(0, 1), b2 + hstepB, voffB); PG8_STAGE(PG8_SA(0, 0), a2, voffA);
;             PG8_WAIT_V(8); PG8_WAIT_L(0); PG8_BAR; PG8_MMA(1, 0, At, B0); PG8_MMA(1, 1, At, B1); PG8_BAR; PG8_SCHED;
.LBB0_310:
	s_or_b32 s52, s70, 1
	s_mul_i32 s53, s45, s52
	s_mul_hi_u32 s72, s44, s52
	s_add_i32 s73, s72, s53
	s_mul_i32 s72, s44, s52
	s_add_u32 s52, s50, s48
	s_addc_u32 s53, s51, s49
	s_add_u32 s72, s21, s72
	s_addc_u32 s73, s23, s73
	s_add_i32 m0, s31, 0xc000
	global_load_lds_dwordx4 v128, s[72:73]
	s_add_i32 m0, s31, 0xe000
	s_nop 0
	global_load_lds_dwordx4 v132, s[72:73]
	s_waitcnt vmcnt(8)
	s_waitcnt lgkmcnt(0)
	s_barrier
	s_setprio 1
	s_waitcnt lgkmcnt(0)
	v_mfma_f32_16x16x32_bf16 v[124:127], v[148:151], v[180:183], v[124:127]
	v_mfma_f32_16x16x32_bf16 v[120:123], v[156:159], v[180:183], v[120:123]
	v_mfma_f32_16x16x32_bf16 v[116:119], v[148:151], v[188:191], v[116:119]
	v_mfma_f32_16x16x32_bf16 v[112:115], v[156:159], v[188:191], v[112:115]
	v_mfma_f32_16x16x32_bf16 v[108:111], v[148:151], v[196:199], v[108:111]
	v_mfma_f32_16x16x32_bf16 v[100:103], v[156:159], v[196:199], v[100:103]
	v_mfma_f32_16x16x32_bf16 v[76:79], v[148:151], v[204:207], v[76:79]
	v_mfma_f32_16x16x32_bf16 v[72:75], v[156:159], v[204:207], v[72:75]
	v_mfma_f32_16x16x32_bf16 v[124:127], v[152:155], v[184:187], v[124:127]
	v_mfma_f32_16x16x32_bf16 v[120:123], v[160:163], v[184:187], v[120:123]
	v_mfma_f32_16x16x32_bf16 v[116:119], v[152:155], v[192:195], v[116:119]
	v_mfma_f32_16x16x32_bf16 v[112:115], v[160:163], v[192:195], v[112:115]
	v_mfma_f32_16x16x32_bf16 v[108:111], v[152:155], v[200:203], v[108:111]
	v_mfma_f32_16x16x32_bf16 v[100:103], v[160:163], v[200:203], v[100:103]
	v_mfma_f32_16x16x32_bf16 v[76:79], v[152:155], v[208:211], v[76:79]
	v_mfma_f32_16x16x32_bf16 v[72:75], v[160:163], v[208:211], v[72:75]
	s_setprio 0
	s_setprio 1
	v_mfma_f32_16x16x32_bf16 v[104:107], v[164:167], v[180:183], v[104:107]
	v_mfma_f32_16x16x32_bf16 v[96:99], v[172:175], v[180:183], v[96:99]
	v_mfma_f32_16x16x32_bf16 v[92:95], v[164:167], v[188:191], v[92:95]
	v_mfma_f32_16x16x32_bf16 v[88:91], v[172:175], v[188:191], v[88:91]
	v_mfma_f32_16x16x32_bf16 v[84:87], v[164:167], v[196:199], v[84:87]
	v_mfma_f32_16x16x32_bf16 v[80:83], v[172:175], v[196:199], v[80:83]
	v_mfma_f32_16x16x32_bf16 v[68:71], v[164:167], v[204:207], v[68:71]
	v_mfma_f32_16x16x32_bf16 v[64:67], v[172:175], v[204:207], v[64:67]
	v_mfma_f32_16x16x32_bf16 v[104:107], v[168:171], v[184:187], v[104:107]
	v_mfma_f32_16x16x32_bf16 v[96:99], v[176:179], v[184:187], v[96:99]
	v_mfma_f32_16x16x32_bf16 v[92:95], v[168:171], v[192:195], v[92:95]
	v_mfma_f32_16x16x32_bf16 v[88:91], v[176:179], v[192:195], v[88:91]
	v_mfma_f32_16x16x32_bf16 v[84:87], v[168:171], v[200:203], v[84:87]
	v_mfma_f32_16x16x32_bf16 v[80:83], v[176:179], v[200:203], v[80:83]
	v_mfma_f32_16x16x32_bf16 v[68:71], v[168:171], v[208:211], v[68:71]
	v_mfma_f32_16x16x32_bf16 v[64:67], v[176:179], v[208:211], v[64:67]
	s_setprio 0
	s_barrier
	s_add_i32 s72, s62, s54
	s_mov_b32 m0, s72
	ds_read_b128 v[180:183], v145 offset:16384
	ds_read_b128 v[184:187], v145 offset:17408
	ds_read_b128 v[188:191], v145 offset:18432
	ds_read_b128 v[192:195], v145 offset:19456
	ds_read_b128 v[196:199], v145 offset:20480
	ds_read_b128 v[200:203], v145 offset:21504
	ds_read_b128 v[204:207], v145 offset:22528
	ds_read_b128 v[208:211], v145 offset:23552
	global_load_lds_dwordx4 v130, s[46:47]
	s_add_i32 m0, s72, 0x2000
	s_add_u32 s72, s46, 0x80000
	s_addc_u32 s73, s47, 0
	s_add_i32 s74, s63, s54
	global_load_lds_dwordx4 v134, s[46:47]
	s_mov_b32 m0, s74
	s_nop 0
	global_load_lds_dwordx4 v130, s[72:73]
	s_add_i32 m0, s74, 0x2000
	s_nop 0
	global_load_lds_dwordx4 v134, s[72:73]
	s_mov_b32 m0, s31
	s_nop 0
	global_load_lds_dwordx4 v128, s[50:51]
	s_mov_b32 m0, s55
	s_nop 0
	global_load_lds_dwordx4 v132, s[50:51]
	s_waitcnt vmcnt(8)
	s_waitcnt lgkmcnt(0)
	s_barrier
	s_setprio 1
	s_waitcnt lgkmcnt(0)
	v_mfma_f32_16x16x32_bf16 v[60:63], v[148:151], v[180:183], v[60:63]
	v_mfma_f32_16x16x32_bf16 v[56:59], v[156:159], v[180:183], v[56:59]
	v_mfma_f32_16x16x32_bf16 v[48:51], v[148:151], v[188:191], v[48:51]
	v_mfma_f32_16x16x32_bf16 v[40:43], v[156:159], v[188:191], v[40:43]
	v_mfma_f32_16x16x32_bf16 v[32:35], v[148:151], v[196:199], v[32:35]
	v_mfma_f32_16x16x32_bf16 v[24:27], v[156:159], v[196:199], v[24:27]
	v_mfma_f32_16x16x32_bf16 v[16:19], v[148:151], v[204:207], v[16:19]
	v_mfma_f32_16x16x32_bf16 v[8:11], v[156:159], v[204:207], v[8:11]
	v_mfma_f32_16x16x32_bf16 v[60:63], v[152:155], v[184:187], v[60:63]
	v_mfma_f32_16x16x32_bf16 v[56:59], v[160:163], v[184:187], v[56:59]
	v_mfma_f32_16x16x32_bf16 v[48:51], v[152:155], v[192:195], v[48:51]
	v_mfma_f32_16x16x32_bf16 v[40:43], v[160:163], v[192:195], v[40:43]
	v_mfma_f32_16x16x32_bf16 v[32:35], v[152:155], v[200:203], v[32:35]
	v_mfma_f32_16x16x32_bf16 v[24:27], v[160:163], v[200:203], v[24:27]
	v_mfma_f32_16x16x32_bf16 v[16:19], v[152:155], v[208:211], v[16:19]
	v_mfma_f32_16x16x32_bf16 v[8:11], v[160:163], v[208:211], v[8:11]
	s_setprio 0
	s_setprio 1
	v_mfma_f32_16x16x32_bf16 v[52:55], v[164:167], v[180:183], v[52:55]
	v_mfma_f32_16x16x32_bf16 v[44:47], v[172:175], v[180:183], v[44:47]
	v_mfma_f32_16x16x32_bf16 v[36:39], v[164:167], v[188:191], v[36:39]
	v_mfma_f32_16x16x32_bf16 v[28:31], v[172:175], v[188:191], v[28:31]
	v_mfma_f32_16x16x32_bf16 v[20:23], v[164:167], v[196:199], v[20:23]
	v_mfma_f32_16x16x32_bf16 v[12:15], v[172:175], v[196:199], v[12:15]
	v_mfma_f32_16x16x32_bf16 v[4:7], v[164:167], v[204:207], v[4:7]
	v_mfma_f32_16x16x32_bf16 v[0:3], v[172:175], v[204:207], v[0:3]
	v_mfma_f32_16x16x32_bf16 v[52:55], v[168:171], v[184:187], v[52:55]
	v_mfma_f32_16x16x32_bf16 v[44:47], v[176:179], v[184:187], v[44:47]
	v_mfma_f32_16x16x32_bf16 v[36:39], v[168:171], v[192:195], v[36:39]
	v_mfma_f32_16x16x32_bf16 v[28:31], v[176:179], v[192:195], v[28:31]
	v_mfma_f32_16x16x32_bf16 v[20:23], v[168:171], v[200:203], v[20:23]
	v_mfma_f32_16x16x32_bf16 v[12:15], v[176:179], v[200:203], v[12:15]
	v_mfma_f32_16x16x32_bf16 v[4:7], v[168:171], v[208:211], v[4:7]
	v_mfma_f32_16x16x32_bf16 v[0:3], v[176:179], v[208:211], v[0:3]
	s_setprio 0
	s_barrier
; #define PG8_STAGE(bufoff, gbase, voff) do { _Pragma("unroll") for (int _i = 0; _i < 2; ++_i) \
;         __builtin_amdgcn_global_load_lds((const unsigned*)((const char*)(gbase) + (voff)[_i]), (LAS unsigned*)(lds + (bufoff) + ldsw + _i * 8192), 16, 0, 0); } while (0)
; #define PG8_LDA(dst, b, h) do { _Pragma("unroll") for (int m = 0; m < 4; ++m) _Pragma("unroll") for (int k = 0; k < 2; ++k) dst[m][k] = *(const LAS bf16x8*)(lds + PG8_SA(b, h) + aoff + m * 2048 + k * 1024); } while (0)
; #define PG8_LDB(dst, b, h) do { _Pragma("unroll") for (int n = 0; n < 2; ++n) _Pragma("unroll") for (int k = 0; k < 2; ++k) dst[n][k] = *(const LAS bf16x8*)(lds + PG8_SB(b, h) + boff + n * 2048 + k * 1024); } while (0)
; #define PG8_MMA(ai, bj, At, Bt) do { __builtin_amdgcn_s_setprio(1); _Pragma("unroll") for (int m = 0; m < 4; ++m) _Pragma("unroll") for (int n = 0; n < 2; ++n) _Pragma("unroll") for (int k = 0; k < 2; ++k) \
;         acc[ai][bj][m][n] = __builtin_amdgcn_mfma_f32_16x16x32_bf16(Bt[n][k], At[m][k], acc[ai][bj][m][n], 0, 0, 0); __builtin_amdgcn_s_setprio(0); } while (0)
; #define PG8_WAIT_V(n) asm volatile("s_waitcnt vmcnt(" #n ")" ::: "memory")
; #define PG8_WAIT_L(n) asm volatile("s_waitcnt lgkmcnt(" #n ")" ::: "memory")
; #define PG8_BAR __builtin_amdgcn_s_barrier()
; #define PG8_SCHED __builtin_amdgcn_sched_barrier(0)
; template <class Epi>
; __device__ __forceinline__ void gemm_phase(LAS unsigned char* lds, const Gemm g, const StaticOrder S, const Epi E) {
;     ...
;         for (int t = 0; t < nt; t += 2) {
;     ...
;             PG8_LDB(B0, 1, 0); PG8_LDB(B1, 1, 1); PG8_SCHED; PG8_LDA(At, 1, 0); PG8_STAGE(PG8_SA(0, 1), a2 + hstepA, voffA);
;             PG8_WAIT_V(8); PG8_WAIT_L(0); PG8_BAR; PG8_MMA(0, 0, At, B0); PG8_MMA(0, 1, At, B1); PG8_BAR; PG8_SCHED;
;             PG8_LDA(At, 1, 1); PG8_STAGE(PG8_SB(1, 0), b3, voffB); PG8_STAGE(PG8_SB(1, 1), b3 + hstepB, voffB); PG8_STAGE(PG8_SA(1, 0), a3, voffA);
;             PG8_WAIT_V(8); PG8_WAIT_L(0); PG8_BAR; PG8_MMA(1, 0, At, B0); PG8_MMA(1, 1, At, B1); PG8_BAR; PG8_SCHED;
	s_add_i32 s72, 0, 0x18000
	s_add_i32 s73, 0, 0x1c000
	ds_read_b128 v[148:151], v254 offset:32768
	ds_read_b128 v[152:155], v254 offset:33792
	ds_read_b128 v[156:159], v254 offset:34816
	ds_read_b128 v[160:163], v254 offset:35840
	ds_read_b128 v[164:167], v254 offset:49152
	ds_read_b128 v[168:171], v254 offset:50176
	ds_read_b128 v[172:175], v254 offset:51200
	ds_read_b128 v[176:179], v254 offset:52224
	s_add_u32 s50, s50, 0x80000
	s_addc_u32 s51, s51, 0
	s_mov_b32 m0, s56
	ds_read_b128 v[180:183], v145 offset:32768
	ds_read_b128 v[184:187], v145 offset:33792
	ds_read_b128 v[188:191], v145 offset:34816
	ds_read_b128 v[192:195], v145 offset:35840
	ds_read_b128 v[196:199], v145 offset:36864
	ds_read_b128 v[200:203], v145 offset:37888
	ds_read_b128 v[204:207], v145 offset:38912
	ds_read_b128 v[208:211], v145 offset:39936
	global_load_lds_dwordx4 v128, s[50:51]
	s_mov_b32 m0, s57
	s_nop 0
	global_load_lds_dwordx4 v132, s[50:51]
	s_waitcnt vmcnt(8)
	s_waitcnt lgkmcnt(0)
	s_barrier
	s_setprio 1
	s_waitcnt lgkmcnt(0)
	v_mfma_f32_16x16x32_bf16 v[124:127], v[148:151], v[180:183], v[124:127]
	v_mfma_f32_16x16x32_bf16 v[120:123], v[156:159], v[180:183], v[120:123]
	v_mfma_f32_16x16x32_bf16 v[116:119], v[148:151], v[188:191], v[116:119]
	v_mfma_f32_16x16x32_bf16 v[112:115], v[156:159], v[188:191], v[112:115]
	v_mfma_f32_16x16x32_bf16 v[108:111], v[148:151], v[196:199], v[108:111]
	v_mfma_f32_16x16x32_bf16 v[100:103], v[156:159], v[196:199], v[100:103]
	v_mfma_f32_16x16x32_bf16 v[76:79], v[148:151], v[204:207], v[76:79]
	v_mfma_f32_16x16x32_bf16 v[72:75], v[156:159], v[204:207], v[72:75]
	v_mfma_f32_16x16x32_bf16 v[124:127], v[152:155], v[184:187], v[124:127]
	v_mfma_f32_16x16x32_bf16 v[120:123], v[160:163], v[184:187], v[120:123]
	v_mfma_f32_16x16x32_bf16 v[116:119], v[152:155], v[192:195], v[116:119]
	v_mfma_f32_16x16x32_bf16 v[112:115], v[160:163], v[192:195], v[112:115]
	v_mfma_f32_16x16x32_bf16 v[108:111], v[152:155], v[200:203], v[108:111]
	v_mfma_f32_16x16x32_bf16 v[100:103], v[160:163], v[200:203], v[100:103]
	v_mfma_f32_16x16x32_bf16 v[76:79], v[152:155], v[208:211], v[76:79]
	v_mfma_f32_16x16x32_bf16 v[72:75], v[160:163], v[208:211], v[72:75]
	s_setprio 0
	s_setprio 1
	v_mfma_f32_16x16x32_bf16 v[104:107], v[164:167], v[180:183], v[104:107]
	v_mfma_f32_16x16x32_bf16 v[96:99], v[172:175], v[180:183], v[96:99]
	v_mfma_f32_16x16x32_bf16 v[92:95], v[164:167], v[188:191], v[92:95]
	v_mfma_f32_16x16x32_bf16 v[88:91], v[172:175], v[188:191], v[88:91]
	v_mfma_f32_16x16x32_bf16 v[84:87], v[164:167], v[196:199], v[84:87]
	v_mfma_f32_16x16x32_bf16 v[80:83], v[172:175], v[196:199], v[80:83]
	v_mfma_f32_16x16x32_bf16 v[68:71], v[164:167], v[204:207], v[68:71]
	v_mfma_f32_16x16x32_bf16 v[64:67], v[172:175], v[204:207], v[64:67]
	v_mfma_f32_16x16x32_bf16 v[104:107], v[168:171], v[184:187], v[104:107]
	v_mfma_f32_16x16x32_bf16 v[96:99], v[176:179], v[184:187], v[96:99]
	v_mfma_f32_16x16x32_bf16 v[92:95], v[168:171], v[192:195], v[92:95]
	v_mfma_f32_16x16x32_bf16 v[88:91], v[176:179], v[192:195], v[88:91]
	v_mfma_f32_16x16x32_bf16 v[84:87], v[168:171], v[200:203], v[84:87]
	v_mfma_f32_16x16x32_bf16 v[80:83], v[176:179], v[200:203], v[80:83]
	v_mfma_f32_16x16x32_bf16 v[68:71], v[168:171], v[208:211], v[68:71]
	v_mfma_f32_16x16x32_bf16 v[64:67], v[176:179], v[208:211], v[64:67]
	s_setprio 0
	s_barrier
	s_add_u32 s46, s46, s48
	s_addc_u32 s47, s47, s49
	s_add_i32 s48, s72, s54
	s_mov_b32 m0, s48
	ds_read_b128 v[180:183], v145 offset:49152
	ds_read_b128 v[184:187], v145 offset:50176
	ds_read_b128 v[188:191], v145 offset:51200
	ds_read_b128 v[192:195], v145 offset:52224
	ds_read_b128 v[196:199], v145 offset:53248
	ds_read_b128 v[200:203], v145 offset:54272
	ds_read_b128 v[204:207], v145 offset:55296
	ds_read_b128 v[208:211], v145 offset:56320
	global_load_lds_dwordx4 v130, s[46:47]
	s_add_i32 m0, s48, 0x2000
	s_nop 0
	global_load_lds_dwordx4 v134, s[46:47]
	s_add_u32 s46, s46, 0x80000
	s_addc_u32 s47, s47, 0
	s_add_i32 s48, s73, s54
	s_mov_b32 m0, s48
	s_nop 0
	global_load_lds_dwordx4 v130, s[46:47]
	s_add_i32 m0, s48, 0x2000
	s_nop 0
	global_load_lds_dwordx4 v134, s[46:47]
	s_mov_b32 m0, s58
	s_nop 0
	global_load_lds_dwordx4 v128, s[52:53]
	s_mov_b32 m0, s59
	s_nop 0
	global_load_lds_dwordx4 v132, s[52:53]
	s_waitcnt vmcnt(8)
	s_waitcnt lgkmcnt(0)
	s_barrier
	s_setprio 1
	s_waitcnt lgkmcnt(0)
	v_mfma_f32_16x16x32_bf16 v[60:63], v[148:151], v[180:183], v[60:63]
	v_mfma_f32_16x16x32_bf16 v[56:59], v[156:159], v[180:183], v[56:59]
	v_mfma_f32_16x16x32_bf16 v[48:51], v[148:151], v[188:191], v[48:51]
	v_mfma_f32_16x16x32_bf16 v[40:43], v[156:159], v[188:191], v[40:43]
	v_mfma_f32_16x16x32_bf16 v[32:35], v[148:151], v[196:199], v[32:35]
	v_mfma_f32_16x16x32_bf16 v[24:27], v[156:159], v[196:199], v[24:27]
	v_mfma_f32_16x16x32_bf16 v[16:19], v[148:151], v[204:207], v[16:19]
	v_mfma_f32_16x16x32_bf16 v[8:11], v[156:159], v[204:207], v[8:11]
	v_mfma_f32_16x16x32_bf16 v[60:63], v[152:155], v[184:187], v[60:63]
	v_mfma_f32_16x16x32_bf16 v[56:59], v[160:163], v[184:187], v[56:59]
	v_mfma_f32_16x16x32_bf16 v[48:51], v[152:155], v[192:195], v[48:51]
	v_mfma_f32_16x16x32_bf16 v[40:43], v[160:163], v[192:195], v[40:43]
	v_mfma_f32_16x16x32_bf16 v[32:35], v[152:155], v[200:203], v[32:35]
	v_mfma_f32_16x16x32_bf16 v[24:27], v[160:163], v[200:203], v[24:27]
	v_mfma_f32_16x16x32_bf16 v[16:19], v[152:155], v[208:211], v[16:19]
	v_mfma_f32_16x16x32_bf16 v[8:11], v[160:163], v[208:211], v[8:11]
	s_setprio 0
	s_setprio 1
	v_mfma_f32_16x16x32_bf16 v[52:55], v[164:167], v[180:183], v[52:55]
	v_mfma_f32_16x16x32_bf16 v[44:47], v[172:175], v[180:183], v[44:47]
	v_mfma_f32_16x16x32_bf16 v[36:39], v[164:167], v[188:191], v[36:39]
	v_mfma_f32_16x16x32_bf16 v[28:31], v[172:175], v[188:191], v[28:31]
	v_mfma_f32_16x16x32_bf16 v[20:23], v[164:167], v[196:199], v[20:23]
	v_mfma_f32_16x16x32_bf16 v[12:15], v[172:175], v[196:199], v[12:15]
	v_mfma_f32_16x16x32_bf16 v[4:7], v[164:167], v[204:207], v[4:7]
	v_mfma_f32_16x16x32_bf16 v[0:3], v[172:175], v[204:207], v[0:3]
	v_mfma_f32_16x16x32_bf16 v[52:55], v[168:171], v[184:187], v[52:55]
	v_mfma_f32_16x16x32_bf16 v[44:47], v[176:179], v[184:187], v[44:47]
	v_mfma_f32_16x16x32_bf16 v[36:39], v[168:171], v[192:195], v[36:39]
	v_mfma_f32_16x16x32_bf16 v[28:31], v[176:179], v[192:195], v[28:31]
	v_mfma_f32_16x16x32_bf16 v[20:23], v[168:171], v[200:203], v[20:23]
	v_mfma_f32_16x16x32_bf16 v[12:15], v[176:179], v[200:203], v[12:15]
	v_mfma_f32_16x16x32_bf16 v[4:7], v[168:171], v[208:211], v[4:7]
	v_mfma_f32_16x16x32_bf16 v[0:3], v[176:179], v[208:211], v[0:3]
	s_setprio 0
	s_barrier
	s_cmp_gt_u32 s70, 29
	s_mov_b32 s70, s71
	s_cbranch_scc1 .LBB0_315
; #define PG8_STAGE(bufoff, gbase, voff) do { _Pragma("unroll") for (int _i = 0; _i < 2; ++_i) \
;         __builtin_amdgcn_global_load_lds((const unsigned*)((const char*)(gbase) + (voff)[_i]), (LAS unsigned*)(lds + (bufoff) + ldsw + _i * 8192), 16, 0, 0); } while (0)
; #define PG8_LDA(dst, b, h) do { _Pragma("unroll") for (int m = 0; m < 4; ++m) _Pragma("unroll") for (int k = 0; k < 2; ++k) dst[m][k] = *(const LAS bf16x8*)(lds + PG8_SA(b, h) + aoff + m * 2048 + k * 1024); } while (0)
; #define PG8_LDB(dst, b, h) do { _Pragma("unroll") for (int n = 0; n < 2; ++n) _Pragma("unroll") for (int k = 0; k < 2; ++k) dst[n][k] = *(const LAS bf16x8*)(lds + PG8_SB(b, h) + boff + n * 2048 + k * 1024); } while (0)
; #define PG8_SCHED __builtin_amdgcn_sched_barrier(0)
; template <class Epi>
; __device__ __forceinline__ void gemm_phase(LAS unsigned char* lds, const Gemm g, const StaticOrder S, const Epi E) {
;     ...
;             const bool last = (t == nt - 2);
;             const char* a1 = cA + (long)(t + 1) * ksc;
;             const char* a2 = last ? nA : cA + (long)(t + 2) * ksc; const char* b2 = last ? nB : cB + (long)(t + 2) * ksc;
;             const long ks3 = last ? ksn : ksc;
;             const char* a3 = a2 + ks3; const char* b3 = b2 + ks3;
;             PG8_LDB(B0, 0, 0); PG8_LDB(B1, 0, 1); PG8_SCHED; PG8_LDA(At, 0, 0); PG8_STAGE(PG8_SA(1, 1), a1 + hstepA, voffA);
.LBB0_311:
	ds_read_b128 v[148:151], v254
	ds_read_b128 v[152:155], v254 offset:1024
	ds_read_b128 v[156:159], v254 offset:2048
	ds_read_b128 v[160:163], v254 offset:3072
	ds_read_b128 v[164:167], v254 offset:16384
	ds_read_b128 v[168:171], v254 offset:17408
	ds_read_b128 v[172:175], v254 offset:18432
	ds_read_b128 v[176:179], v254 offset:19456
	ds_read_b128 v[180:183], v145
	ds_read_b128 v[184:187], v145 offset:1024
	ds_read_b128 v[188:191], v145 offset:2048
	ds_read_b128 v[192:195], v145 offset:3072
	ds_read_b128 v[196:199], v145 offset:4096
	ds_read_b128 v[200:203], v145 offset:5120
	ds_read_b128 v[204:207], v145 offset:6144
	ds_read_b128 v[208:211], v145 offset:7168
	s_cmp_lg_u32 s70, 30
	s_mov_b32 s71, 32
	s_cselect_b64 s[46:47], -1, 0
	s_cmp_eq_u32 s70, 30
	s_mov_b64 s[50:51], s[24:25]
	s_cbranch_scc1 .LBB0_313
	s_add_i32 s71, s70, 2
	s_mul_i32 s48, s45, s71
	s_mul_hi_u32 s49, s44, s71
	s_add_i32 s49, s49, s48
	s_mul_i32 s48, s44, s71
	s_add_u32 s50, s42, s48
	s_addc_u32 s51, s43, s49

; #define PG8_STAGE(bufoff, gbase, voff) do { _Pragma("unroll") for (int _i = 0; _i < 2; ++_i) \
;         __builtin_amdgcn_global_load_lds((const unsigned*)((const char*)(gbase) + (voff)[_i]), (LAS unsigned*)(lds + (bufoff) + ldsw + _i * 8192), 16, 0, 0); } while (0)
; #define PG8_LDA(dst, b, h) do { _Pragma("unroll") for (int m = 0; m < 4; ++m) _Pragma("unroll") for (int k = 0; k < 2; ++k) dst[m][k] = *(const LAS bf16x8*)(lds + PG8_SA(b, h) + aoff + m * 2048 + k * 1024); } while (0)
; #define PG8_LDB(dst, b, h) do { _Pragma("unroll") for (int n = 0; n < 2; ++n) _Pragma("unroll") for (int k = 0; k < 2; ++k) dst[n][k] = *(const LAS bf16x8*)(lds + PG8_SB(b, h) + boff + n * 2048 + k * 1024); } while (0)
; #define PG8_MMA(ai, bj, At, Bt) do { __builtin_amdgcn_s_setprio(1); _Pragma("unroll") for (int m = 0; m < 4; ++m) _Pragma("unroll") for (int n = 0; n < 2; ++n) _Pragma("unroll") for (int k = 0; k < 2; ++k) \
;         acc[ai][bj][m][n] = __builtin_amdgcn_mfma_f32_16x16x32_bf16(Bt[n][k], At[m][k], acc[ai][bj][m][n], 0, 0, 0); __builtin_amdgcn_s_setprio(0); } while (0)
; #define PG8_WAIT_V(n) asm volatile("s_waitcnt vmcnt(" #n ")" ::: "memory")
; #define PG8_WAIT_L(n) asm volatile("s_waitcnt lgkmcnt(" #n ")" ::: "memory")
; #define PG8_BAR __builtin_amdgcn_s_barrier()
; #define PG8_SCHED __builtin_amdgcn_sched_barrier(0)
; template <class Epi>
; __device__ __forceinline__ void gemm_phase(LAS unsigned char* lds, const Gemm g, const StaticOrder S, const Epi E) {
;     ...
;             PG8_LDB(B0, 0, 0); PG8_LDB(B1, 0, 1); PG8_SCHED; PG8_LDA(At, 0, 0); PG8_STAGE(PG8_SA(1, 1), a1 + hstepA, voffA);
;             PG8_WAIT_V(8); PG8_WAIT_L(0); PG8_BAR; PG8_MMA(0, 0, At, B0); PG8_MMA(0, 1, At, B1); PG8_BAR; PG8_SCHED;
;             PG8_LDA(At, 0, 1); PG8_STAGE(PG8_SB(0, 0), b2, voffB); PG8_STAGE(PG8_SB(0, 1), b2 + hstepB, voffB); PG8_STAGE(PG8_SA(0, 0), a2, voffA);
;             PG8_WAIT_V(8); PG8_WAIT_L(0); PG8_BAR; PG8_MMA(1, 0, At, B0); PG8_MMA(1, 1, At, B1); PG8_BAR; PG8_SCHED;
.LBB0_566:
	s_or_b32 s21, s29, 1
	s_mul_i32 s58, s45, s21
	s_mul_hi_u32 s59, s44, s21
	s_add_i32 s59, s59, s58
	s_mul_i32 s21, s44, s21
	s_add_u32 s21, s42, s21
	s_addc_u32 s75, s43, s59
	s_add_u32 s58, s56, s54
	s_addc_u32 s59, s57, s55
	s_add_u32 s74, s21, 0x80000
	s_addc_u32 s75, s75, 0
	s_add_i32 m0, s31, 0xc000
	global_load_lds_dwordx4 v140, s[74:75]
	s_add_i32 m0, s31, 0xe000
	s_nop 0
	global_load_lds_dwordx4 v144, s[74:75]
	s_waitcnt vmcnt(8)
	s_waitcnt lgkmcnt(0)
	s_barrier
	s_setprio 1
	s_waitcnt lgkmcnt(0)
	v_mfma_f32_16x16x32_bf16 v[124:127], v[128:131], v[180:183], v[124:127]
	v_mfma_f32_16x16x32_bf16 v[120:123], v[136:139], v[180:183], v[120:123]
	v_mfma_f32_16x16x32_bf16 v[108:111], v[128:131], v[188:191], v[108:111]
	v_mfma_f32_16x16x32_bf16 v[104:107], v[136:139], v[188:191], v[104:107]
	v_mfma_f32_16x16x32_bf16 v[92:95], v[128:131], v[196:199], v[92:95]
	v_mfma_f32_16x16x32_bf16 v[88:91], v[136:139], v[196:199], v[88:91]
	v_mfma_f32_16x16x32_bf16 v[76:79], v[128:131], v[204:207], v[76:79]
	v_mfma_f32_16x16x32_bf16 v[72:75], v[136:139], v[204:207], v[72:75]
	v_mfma_f32_16x16x32_bf16 v[124:127], v[132:135], v[184:187], v[124:127]
	v_mfma_f32_16x16x32_bf16 v[120:123], v[152:155], v[184:187], v[120:123]
	v_mfma_f32_16x16x32_bf16 v[108:111], v[132:135], v[192:195], v[108:111]
	v_mfma_f32_16x16x32_bf16 v[104:107], v[152:155], v[192:195], v[104:107]
	v_mfma_f32_16x16x32_bf16 v[92:95], v[132:135], v[200:203], v[92:95]
	v_mfma_f32_16x16x32_bf16 v[88:91], v[152:155], v[200:203], v[88:91]
	v_mfma_f32_16x16x32_bf16 v[76:79], v[132:135], v[208:211], v[76:79]
	v_mfma_f32_16x16x32_bf16 v[72:75], v[152:155], v[208:211], v[72:75]
	s_setprio 0
	s_setprio 1
	v_mfma_f32_16x16x32_bf16 v[116:119], v[156:159], v[180:183], v[116:119]
	v_mfma_f32_16x16x32_bf16 v[112:115], v[172:175], v[180:183], v[112:115]
	v_mfma_f32_16x16x32_bf16 v[100:103], v[156:159], v[188:191], v[100:103]
	v_mfma_f32_16x16x32_bf16 v[96:99], v[172:175], v[188:191], v[96:99]
	v_mfma_f32_16x16x32_bf16 v[84:87], v[156:159], v[196:199], v[84:87]
	v_mfma_f32_16x16x32_bf16 v[80:83], v[172:175], v[196:199], v[80:83]
	v_mfma_f32_16x16x32_bf16 v[68:71], v[156:159], v[204:207], v[68:71]
	v_mfma_f32_16x16x32_bf16 v[64:67], v[172:175], v[204:207], v[64:67]
	v_mfma_f32_16x16x32_bf16 v[116:119], v[168:171], v[184:187], v[116:119]
	v_mfma_f32_16x16x32_bf16 v[112:115], v[176:179], v[184:187], v[112:115]
	v_mfma_f32_16x16x32_bf16 v[100:103], v[168:171], v[192:195], v[100:103]
	v_mfma_f32_16x16x32_bf16 v[96:99], v[176:179], v[192:195], v[96:99]
	v_mfma_f32_16x16x32_bf16 v[84:87], v[168:171], v[200:203], v[84:87]
	v_mfma_f32_16x16x32_bf16 v[80:83], v[176:179], v[200:203], v[80:83]
	v_mfma_f32_16x16x32_bf16 v[68:71], v[168:171], v[208:211], v[68:71]
	v_mfma_f32_16x16x32_bf16 v[64:67], v[176:179], v[208:211], v[64:67]
	s_setprio 0
	s_barrier
	s_add_i32 s21, s67, s33
	s_mov_b32 m0, s21
	ds_read_b128 v[180:183], v166 offset:16384
	ds_read_b128 v[184:187], v166 offset:17408
	ds_read_b128 v[188:191], v166 offset:18432
	ds_read_b128 v[192:195], v166 offset:19456
	ds_read_b128 v[196:199], v166 offset:20480
	ds_read_b128 v[200:203], v166 offset:21504
	ds_read_b128 v[204:207], v166 offset:22528
	ds_read_b128 v[208:211], v166 offset:23552
	global_load_lds_dwordx4 v142, s[52:53]
	s_add_i32 m0, s21, 0x2000
	s_add_u32 s74, s52, 0x80000
	s_addc_u32 s75, s53, 0
	s_add_i32 s21, s68, s33
	global_load_lds_dwordx4 v146, s[52:53]
	s_mov_b32 m0, s21
	s_nop 0
	global_load_lds_dwordx4 v142, s[74:75]
	s_add_i32 m0, s21, 0x2000
	s_nop 0
	global_load_lds_dwordx4 v146, s[74:75]
	s_mov_b32 m0, s31
	s_nop 0
	global_load_lds_dwordx4 v140, s[56:57]
	s_mov_b32 m0, s60
	s_nop 0
	global_load_lds_dwordx4 v144, s[56:57]
	s_waitcnt vmcnt(8)
	s_waitcnt lgkmcnt(0)
	s_barrier
	s_setprio 1
	s_waitcnt lgkmcnt(0)
	v_mfma_f32_16x16x32_bf16 v[60:63], v[128:131], v[180:183], v[60:63]
	v_mfma_f32_16x16x32_bf16 v[56:59], v[136:139], v[180:183], v[56:59]
	v_mfma_f32_16x16x32_bf16 v[44:47], v[128:131], v[188:191], v[44:47]
	v_mfma_f32_16x16x32_bf16 v[40:43], v[136:139], v[188:191], v[40:43]
	v_mfma_f32_16x16x32_bf16 v[28:31], v[128:131], v[196:199], v[28:31]
	v_mfma_f32_16x16x32_bf16 v[24:27], v[136:139], v[196:199], v[24:27]
	v_mfma_f32_16x16x32_bf16 v[12:15], v[128:131], v[204:207], v[12:15]
	v_mfma_f32_16x16x32_bf16 v[8:11], v[136:139], v[204:207], v[8:11]
	v_mfma_f32_16x16x32_bf16 v[60:63], v[132:135], v[184:187], v[60:63]
	v_mfma_f32_16x16x32_bf16 v[56:59], v[152:155], v[184:187], v[56:59]
	v_mfma_f32_16x16x32_bf16 v[44:47], v[132:135], v[192:195], v[44:47]
	v_mfma_f32_16x16x32_bf16 v[40:43], v[152:155], v[192:195], v[40:43]
	v_mfma_f32_16x16x32_bf16 v[28:31], v[132:135], v[200:203], v[28:31]
	v_mfma_f32_16x16x32_bf16 v[24:27], v[152:155], v[200:203], v[24:27]
	v_mfma_f32_16x16x32_bf16 v[12:15], v[132:135], v[208:211], v[12:15]
	v_mfma_f32_16x16x32_bf16 v[8:11], v[152:155], v[208:211], v[8:11]
	s_setprio 0
	s_setprio 1
	v_mfma_f32_16x16x32_bf16 v[52:55], v[156:159], v[180:183], v[52:55]
	v_mfma_f32_16x16x32_bf16 v[48:51], v[172:175], v[180:183], v[48:51]
	v_mfma_f32_16x16x32_bf16 v[36:39], v[156:159], v[188:191], v[36:39]
	v_mfma_f32_16x16x32_bf16 v[32:35], v[172:175], v[188:191], v[32:35]
	v_mfma_f32_16x16x32_bf16 v[20:23], v[156:159], v[196:199], v[20:23]
	v_mfma_f32_16x16x32_bf16 v[16:19], v[172:175], v[196:199], v[16:19]
	v_mfma_f32_16x16x32_bf16 v[4:7], v[156:159], v[204:207], v[4:7]
	v_mfma_f32_16x16x32_bf16 v[0:3], v[172:175], v[204:207], v[0:3]
	v_mfma_f32_16x16x32_bf16 v[52:55], v[168:171], v[184:187], v[52:55]
	v_mfma_f32_16x16x32_bf16 v[48:51], v[176:179], v[184:187], v[48:51]
	v_mfma_f32_16x16x32_bf16 v[36:39], v[168:171], v[192:195], v[36:39]
	v_mfma_f32_16x16x32_bf16 v[32:35], v[176:179], v[192:195], v[32:35]
	v_mfma_f32_16x16x32_bf16 v[20:23], v[168:171], v[200:203], v[20:23]
	v_mfma_f32_16x16x32_bf16 v[16:19], v[176:179], v[200:203], v[16:19]
	v_mfma_f32_16x16x32_bf16 v[4:7], v[168:171], v[208:211], v[4:7]
	v_mfma_f32_16x16x32_bf16 v[0:3], v[176:179], v[208:211], v[0:3]
	s_setprio 0
	s_barrier
; #define PG8_STAGE(bufoff, gbase, voff) do { _Pragma("unroll") for (int _i = 0; _i < 2; ++_i) \
;         __builtin_amdgcn_global_load_lds((const unsigned*)((const char*)(gbase) + (voff)[_i]), (LAS unsigned*)(lds + (bufoff) + ldsw + _i * 8192), 16, 0, 0); } while (0)
; #define PG8_LDA(dst, b, h) do { _Pragma("unroll") for (int m = 0; m < 4; ++m) _Pragma("unroll") for (int k = 0; k < 2; ++k) dst[m][k] = *(const LAS bf16x8*)(lds + PG8_SA(b, h) + aoff + m * 2048 + k * 1024); } while (0)
; #define PG8_LDB(dst, b, h) do { _Pragma("unroll") for (int n = 0; n < 2; ++n) _Pragma("unroll") for (int k = 0; k < 2; ++k) dst[n][k] = *(const LAS bf16x8*)(lds + PG8_SB(b, h) + boff + n * 2048 + k * 1024); } while (0)
; #define PG8_MMA(ai, bj, At, Bt) do { __builtin_amdgcn_s_setprio(1); _Pragma("unroll") for (int m = 0; m < 4; ++m) _Pragma("unroll") for (int n = 0; n < 2; ++n) _Pragma("unroll") for (int k = 0; k < 2; ++k) \
;         acc[ai][bj][m][n] = __builtin_amdgcn_mfma_f32_16x16x32_bf16(Bt[n][k], At[m][k], acc[ai][bj][m][n], 0, 0, 0); __builtin_amdgcn_s_setprio(0); } while (0)
; #define PG8_WAIT_V(n) asm volatile("s_waitcnt vmcnt(" #n ")" ::: "memory")
; #define PG8_WAIT_L(n) asm volatile("s_waitcnt lgkmcnt(" #n ")" ::: "memory")
; #define PG8_BAR __builtin_amdgcn_s_barrier()
; #define PG8_SCHED __builtin_amdgcn_sched_barrier(0)
; template <class Epi>
; __device__ __forceinline__ void gemm_phase(LAS unsigned char* lds, const Gemm g, const StaticOrder S, const Epi E) {
;     ...
;         for (int t = 0; t < nt; t += 2) {
;     ...
;             PG8_LDB(B0, 1, 0); PG8_LDB(B1, 1, 1); PG8_SCHED; PG8_LDA(At, 1, 0); PG8_STAGE(PG8_SA(0, 1), a2 + hstepA, voffA);
;             PG8_WAIT_V(8); PG8_WAIT_L(0); PG8_BAR; PG8_MMA(0, 0, At, B0); PG8_MMA(0, 1, At, B1); PG8_BAR; PG8_SCHED;
;             PG8_LDA(At, 1, 1); PG8_STAGE(PG8_SB(1, 0), b3, voffB); PG8_STAGE(PG8_SB(1, 1), b3 + hstepB, voffB); PG8_STAGE(PG8_SA(1, 0), a3, voffA);
;             PG8_WAIT_V(8); PG8_WAIT_L(0); PG8_BAR; PG8_MMA(1, 0, At, B0); PG8_MMA(1, 1, At, B1); PG8_BAR; PG8_SCHED;
	s_add_i32 s21, 0, 0x18000
	s_add_i32 s74, 0, 0x1c000
	v_add_u32_e32 v152, s21, v164
	v_add_u32_e32 v176, s74, v164
	ds_read_b128 v[128:131], v152
	ds_read_b128 v[132:135], v152 offset:1024
	ds_read_b128 v[136:139], v152 offset:2048
	ds_read_b128 v[152:155], v152 offset:3072
	ds_read_b128 v[156:159], v176
	ds_read_b128 v[168:171], v176 offset:1024
	ds_read_b128 v[172:175], v176 offset:2048
	ds_read_b128 v[176:179], v176 offset:3072
	s_add_u32 s56, s56, 0x80000
	s_addc_u32 s57, s57, 0
	s_mov_b32 m0, s61
	ds_read_b128 v[180:183], v166 offset:32768
	ds_read_b128 v[184:187], v166 offset:33792
	ds_read_b128 v[188:191], v166 offset:34816
	ds_read_b128 v[192:195], v166 offset:35840
	ds_read_b128 v[196:199], v166 offset:36864
	ds_read_b128 v[200:203], v166 offset:37888
	ds_read_b128 v[204:207], v166 offset:38912
	ds_read_b128 v[208:211], v166 offset:39936
	global_load_lds_dwordx4 v140, s[56:57]
	s_mov_b32 m0, s62
	s_nop 0
	global_load_lds_dwordx4 v144, s[56:57]
	s_waitcnt vmcnt(8)
	s_waitcnt lgkmcnt(0)
	s_barrier
	s_setprio 1
	s_waitcnt lgkmcnt(0)
	v_mfma_f32_16x16x32_bf16 v[124:127], v[128:131], v[180:183], v[124:127]
	v_mfma_f32_16x16x32_bf16 v[120:123], v[136:139], v[180:183], v[120:123]
	v_mfma_f32_16x16x32_bf16 v[108:111], v[128:131], v[188:191], v[108:111]
	v_mfma_f32_16x16x32_bf16 v[104:107], v[136:139], v[188:191], v[104:107]
	v_mfma_f32_16x16x32_bf16 v[92:95], v[128:131], v[196:199], v[92:95]
	v_mfma_f32_16x16x32_bf16 v[88:91], v[136:139], v[196:199], v[88:91]
	v_mfma_f32_16x16x32_bf16 v[76:79], v[128:131], v[204:207], v[76:79]
	v_mfma_f32_16x16x32_bf16 v[72:75], v[136:139], v[204:207], v[72:75]
	v_mfma_f32_16x16x32_bf16 v[124:127], v[132:135], v[184:187], v[124:127]
	v_mfma_f32_16x16x32_bf16 v[120:123], v[152:155], v[184:187], v[120:123]
	v_mfma_f32_16x16x32_bf16 v[108:111], v[132:135], v[192:195], v[108:111]
	v_mfma_f32_16x16x32_bf16 v[104:107], v[152:155], v[192:195], v[104:107]
	v_mfma_f32_16x16x32_bf16 v[92:95], v[132:135], v[200:203], v[92:95]
	v_mfma_f32_16x16x32_bf16 v[88:91], v[152:155], v[200:203], v[88:91]
	v_mfma_f32_16x16x32_bf16 v[76:79], v[132:135], v[208:211], v[76:79]
	v_mfma_f32_16x16x32_bf16 v[72:75], v[152:155], v[208:211], v[72:75]
	s_setprio 0
	s_setprio 1
	v_mfma_f32_16x16x32_bf16 v[116:119], v[156:159], v[180:183], v[116:119]
	v_mfma_f32_16x16x32_bf16 v[112:115], v[172:175], v[180:183], v[112:115]
	v_mfma_f32_16x16x32_bf16 v[100:103], v[156:159], v[188:191], v[100:103]
	v_mfma_f32_16x16x32_bf16 v[96:99], v[172:175], v[188:191], v[96:99]
	v_mfma_f32_16x16x32_bf16 v[84:87], v[156:159], v[196:199], v[84:87]
	v_mfma_f32_16x16x32_bf16 v[80:83], v[172:175], v[196:199], v[80:83]
	v_mfma_f32_16x16x32_bf16 v[68:71], v[156:159], v[204:207], v[68:71]
	v_mfma_f32_16x16x32_bf16 v[64:67], v[172:175], v[204:207], v[64:67]
	v_mfma_f32_16x16x32_bf16 v[116:119], v[168:171], v[184:187], v[116:119]
	v_mfma_f32_16x16x32_bf16 v[112:115], v[176:179], v[184:187], v[112:115]
	v_mfma_f32_16x16x32_bf16 v[100:103], v[168:171], v[192:195], v[100:103]
	v_mfma_f32_16x16x32_bf16 v[96:99], v[176:179], v[192:195], v[96:99]
	v_mfma_f32_16x16x32_bf16 v[84:87], v[168:171], v[200:203], v[84:87]
	v_mfma_f32_16x16x32_bf16 v[80:83], v[176:179], v[200:203], v[80:83]
	v_mfma_f32_16x16x32_bf16 v[68:71], v[168:171], v[208:211], v[68:71]
	v_mfma_f32_16x16x32_bf16 v[64:67], v[176:179], v[208:211], v[64:67]
	s_setprio 0
	s_barrier
	s_add_u32 s52, s52, s54
	s_addc_u32 s53, s53, s55
	s_add_i32 s21, s21, s33
	s_mov_b32 m0, s21
	ds_read_b128 v[180:183], v166 offset:49152
	ds_read_b128 v[184:187], v166 offset:50176
	ds_read_b128 v[188:191], v166 offset:51200
	ds_read_b128 v[192:195], v166 offset:52224
	ds_read_b128 v[196:199], v166 offset:53248
	ds_read_b128 v[200:203], v166 offset:54272
	ds_read_b128 v[204:207], v166 offset:55296
	ds_read_b128 v[208:211], v166 offset:56320
	global_load_lds_dwordx4 v142, s[52:53]
	s_add_i32 m0, s21, 0x2000
	s_nop 0
	global_load_lds_dwordx4 v146, s[52:53]
	s_add_u32 s52, s52, 0x80000
	s_addc_u32 s53, s53, 0
	s_add_i32 s21, s74, s33
	s_mov_b32 m0, s21
	s_nop 0
	global_load_lds_dwordx4 v142, s[52:53]
	s_add_i32 m0, s21, 0x2000
	s_nop 0
	global_load_lds_dwordx4 v146, s[52:53]
	s_mov_b32 m0, s64
	s_nop 0
	global_load_lds_dwordx4 v140, s[58:59]
	s_mov_b32 m0, s65
	s_nop 0
	global_load_lds_dwordx4 v144, s[58:59]
	s_waitcnt vmcnt(8)
	s_waitcnt lgkmcnt(0)
	s_barrier
	s_setprio 1
	s_waitcnt lgkmcnt(0)
	v_mfma_f32_16x16x32_bf16 v[60:63], v[128:131], v[180:183], v[60:63]
	v_mfma_f32_16x16x32_bf16 v[56:59], v[136:139], v[180:183], v[56:59]
	v_mfma_f32_16x16x32_bf16 v[44:47], v[128:131], v[188:191], v[44:47]
	v_mfma_f32_16x16x32_bf16 v[40:43], v[136:139], v[188:191], v[40:43]
	v_mfma_f32_16x16x32_bf16 v[28:31], v[128:131], v[196:199], v[28:31]
	v_mfma_f32_16x16x32_bf16 v[24:27], v[136:139], v[196:199], v[24:27]
	v_mfma_f32_16x16x32_bf16 v[12:15], v[128:131], v[204:207], v[12:15]
	v_mfma_f32_16x16x32_bf16 v[8:11], v[136:139], v[204:207], v[8:11]
	v_mfma_f32_16x16x32_bf16 v[60:63], v[132:135], v[184:187], v[60:63]
	v_mfma_f32_16x16x32_bf16 v[56:59], v[152:155], v[184:187], v[56:59]
	v_mfma_f32_16x16x32_bf16 v[44:47], v[132:135], v[192:195], v[44:47]
	v_mfma_f32_16x16x32_bf16 v[40:43], v[152:155], v[192:195], v[40:43]
	v_mfma_f32_16x16x32_bf16 v[28:31], v[132:135], v[200:203], v[28:31]
	v_mfma_f32_16x16x32_bf16 v[24:27], v[152:155], v[200:203], v[24:27]
	v_mfma_f32_16x16x32_bf16 v[12:15], v[132:135], v[208:211], v[12:15]
	v_mfma_f32_16x16x32_bf16 v[8:11], v[152:155], v[208:211], v[8:11]
	s_setprio 0
	s_setprio 1
	v_mfma_f32_16x16x32_bf16 v[52:55], v[156:159], v[180:183], v[52:55]
	v_mfma_f32_16x16x32_bf16 v[48:51], v[172:175], v[180:183], v[48:51]
	v_mfma_f32_16x16x32_bf16 v[36:39], v[156:159], v[188:191], v[36:39]
	v_mfma_f32_16x16x32_bf16 v[32:35], v[172:175], v[188:191], v[32:35]
	v_mfma_f32_16x16x32_bf16 v[20:23], v[156:159], v[196:199], v[20:23]
	v_mfma_f32_16x16x32_bf16 v[16:19], v[172:175], v[196:199], v[16:19]
	v_mfma_f32_16x16x32_bf16 v[4:7], v[156:159], v[204:207], v[4:7]
	v_mfma_f32_16x16x32_bf16 v[0:3], v[172:175], v[204:207], v[0:3]
	v_mfma_f32_16x16x32_bf16 v[52:55], v[168:171], v[184:187], v[52:55]
	v_mfma_f32_16x16x32_bf16 v[48:51], v[176:179], v[184:187], v[48:51]
	v_mfma_f32_16x16x32_bf16 v[36:39], v[168:171], v[192:195], v[36:39]
	v_mfma_f32_16x16x32_bf16 v[32:35], v[176:179], v[192:195], v[32:35]
	v_mfma_f32_16x16x32_bf16 v[20:23], v[168:171], v[200:203], v[20:23]
	v_mfma_f32_16x16x32_bf16 v[16:19], v[176:179], v[200:203], v[16:19]
	v_mfma_f32_16x16x32_bf16 v[4:7], v[168:171], v[208:211], v[4:7]
	v_mfma_f32_16x16x32_bf16 v[0:3], v[176:179], v[208:211], v[0:3]
	s_setprio 0
	s_barrier
	s_cmp_gt_u32 s29, 29
	s_mov_b32 s29, s19
	s_cbranch_scc1 .LBB0_571
; #define PG8_STAGE(bufoff, gbase, voff) do { _Pragma("unroll") for (int _i = 0; _i < 2; ++_i) \
;         __builtin_amdgcn_global_load_lds((const unsigned*)((const char*)(gbase) + (voff)[_i]), (LAS unsigned*)(lds + (bufoff) + ldsw + _i * 8192), 16, 0, 0); } while (0)
; #define PG8_LDA(dst, b, h) do { _Pragma("unroll") for (int m = 0; m < 4; ++m) _Pragma("unroll") for (int k = 0; k < 2; ++k) dst[m][k] = *(const LAS bf16x8*)(lds + PG8_SA(b, h) + aoff + m * 2048 + k * 1024); } while (0)
; #define PG8_LDB(dst, b, h) do { _Pragma("unroll") for (int n = 0; n < 2; ++n) _Pragma("unroll") for (int k = 0; k < 2; ++k) dst[n][k] = *(const LAS bf16x8*)(lds + PG8_SB(b, h) + boff + n * 2048 + k * 1024); } while (0)
; #define PG8_SCHED __builtin_amdgcn_sched_barrier(0)
; template <class Epi>
; __device__ __forceinline__ void gemm_phase(LAS unsigned char* lds, const Gemm g, const StaticOrder S, const Epi E) {
;     ...
;             const bool last = (t == nt - 2);
;             const char* a1 = cA + (long)(t + 1) * ksc;
;             const char* a2 = last ? nA : cA + (long)(t + 2) * ksc; const char* b2 = last ? nB : cB + (long)(t + 2) * ksc;
;             const long ks3 = last ? ksn : ksc;
;             const char* a3 = a2 + ks3; const char* b3 = b2 + ks3;
;             PG8_LDB(B0, 0, 0); PG8_LDB(B1, 0, 1); PG8_SCHED; PG8_LDA(At, 0, 0); PG8_STAGE(PG8_SA(1, 1), a1 + hstepA, voffA);
.LBB0_567:
	v_add_u32_e32 v152, s67, v164
	v_add_u32_e32 v176, s68, v164
	ds_read_b128 v[128:131], v152
	ds_read_b128 v[132:135], v152 offset:1024
	ds_read_b128 v[136:139], v152 offset:2048
	ds_read_b128 v[152:155], v152 offset:3072
	ds_read_b128 v[156:159], v176
	ds_read_b128 v[168:171], v176 offset:1024
	ds_read_b128 v[172:175], v176 offset:2048
	ds_read_b128 v[176:179], v176 offset:3072
	ds_read_b128 v[180:183], v166
	ds_read_b128 v[184:187], v166 offset:1024
	ds_read_b128 v[188:191], v166 offset:2048
	ds_read_b128 v[192:195], v166 offset:3072
	ds_read_b128 v[196:199], v166 offset:4096
	ds_read_b128 v[200:203], v166 offset:5120
	ds_read_b128 v[204:207], v166 offset:6144
	ds_read_b128 v[208:211], v166 offset:7168
	s_cmp_lg_u32 s29, 30
	s_cselect_b64 s[52:53], -1, 0
	s_cmp_eq_u32 s29, 30
	s_mov_b64 s[56:57], s[48:49]
	s_cbranch_scc1 .LBB0_569
	s_add_i32 s19, s29, 2
	s_mul_i32 s21, s45, s19
	s_mul_hi_u32 s54, s44, s19
	s_add_i32 s54, s54, s21
	s_mul_i32 s19, s44, s19
	s_add_u32 s56, s42, s19
	s_addc_u32 s57, s43, s54

; #define PG8_STAGE(bufoff, gbase, voff) do { _Pragma("unroll") for (int _i = 0; _i < 2; ++_i) \
;         __builtin_amdgcn_global_load_lds((const unsigned*)((const char*)(gbase) + (voff)[_i]), (LAS unsigned*)(lds + (bufoff) + ldsw + _i * 8192), 16, 0, 0); } while (0)
; #define PG8_LDA(dst, b, h) do { _Pragma("unroll") for (int m = 0; m < 4; ++m) _Pragma("unroll") for (int k = 0; k < 2; ++k) dst[m][k] = *(const LAS bf16x8*)(lds + PG8_SA(b, h) + aoff + m * 2048 + k * 1024); } while (0)
; #define PG8_LDB(dst, b, h) do { _Pragma("unroll") for (int n = 0; n < 2; ++n) _Pragma("unroll") for (int k = 0; k < 2; ++k) dst[n][k] = *(const LAS bf16x8*)(lds + PG8_SB(b, h) + boff + n * 2048 + k * 1024); } while (0)
; #define PG8_MMA(ai, bj, At, Bt) do { __builtin_amdgcn_s_setprio(1); _Pragma("unroll") for (int m = 0; m < 4; ++m) _Pragma("unroll") for (int n = 0; n < 2; ++n) _Pragma("unroll") for (int k = 0; k < 2; ++k) \
;         acc[ai][bj][m][n] = __builtin_amdgcn_mfma_f32_16x16x32_bf16(Bt[n][k], At[m][k], acc[ai][bj][m][n], 0, 0, 0); __builtin_amdgcn_s_setprio(0); } while (0)
; #define PG8_WAIT_V(n) asm volatile("s_waitcnt vmcnt(" #n ")" ::: "memory")
; #define PG8_WAIT_L(n) asm volatile("s_waitcnt lgkmcnt(" #n ")" ::: "memory")
; #define PG8_BAR __builtin_amdgcn_s_barrier()
; #define PG8_SCHED __builtin_amdgcn_sched_barrier(0)
; template <class Epi>
; __device__ __forceinline__ void gemm_phase(LAS unsigned char* lds, const Gemm g, const StaticOrder S, const Epi E) {
;     ...
;             const char* a1 = cA + (long)(t + 1) * ksc;
;             const char* a2 = last ? nA : cA + (long)(t + 2) * ksc; const char* b2 = last ? nB : cB + (long)(t + 2) * ksc;
;             const long ks3 = last ? ksn : ksc;
;             const char* a3 = a2 + ks3; const char* b3 = b2 + ks3;
;             PG8_LDB(B0, 0, 0); PG8_LDB(B1, 0, 1); PG8_SCHED; PG8_LDA(At, 0, 0); PG8_STAGE(PG8_SA(1, 1), a1 + hstepA, voffA);
;             PG8_WAIT_V(8); PG8_WAIT_L(0); PG8_BAR; PG8_MMA(0, 0, At, B0); PG8_MMA(0, 1, At, B1); PG8_BAR; PG8_SCHED;
;             PG8_LDA(At, 0, 1); PG8_STAGE(PG8_SB(0, 0), b2, voffB); PG8_STAGE(PG8_SB(0, 1), b2 + hstepB, voffB); PG8_STAGE(PG8_SA(0, 0), a2, voffA);
;             PG8_WAIT_V(8); PG8_WAIT_L(0); PG8_BAR; PG8_MMA(1, 0, At, B0); PG8_MMA(1, 1, At, B1); PG8_BAR; PG8_SCHED;
.LBB0_666:
	s_or_b32 s13, s66, 1
	s_mul_i32 s48, s27, s13
	s_mul_hi_u32 s49, s26, s13
	s_add_i32 s49, s49, s48
	s_mul_i32 s13, s26, s13
	s_add_u32 s13, s24, s13
	s_addc_u32 s67, s25, s49
	s_add_u32 s48, s46, s44
	s_addc_u32 s49, s47, s45
	s_add_u32 s68, s13, 0x80000
	s_addc_u32 s69, s67, 0
	s_add_i32 m0, s21, 0xc000
	global_load_lds_dwordx4 v134, s[68:69]
	s_add_i32 m0, s21, 0xe000
	s_nop 0
	global_load_lds_dwordx4 v130, s[68:69]
	s_waitcnt vmcnt(8)
	s_waitcnt lgkmcnt(0)
	s_barrier
	s_setprio 1
	s_waitcnt lgkmcnt(0)
	v_mfma_f32_16x16x32_bf16 v[116:119], v[148:151], v[180:183], v[116:119]
	v_mfma_f32_16x16x32_bf16 v[112:115], v[156:159], v[180:183], v[112:115]
	v_mfma_f32_16x16x32_bf16 v[108:111], v[148:151], v[188:191], v[108:111]
	v_mfma_f32_16x16x32_bf16 v[104:107], v[156:159], v[188:191], v[104:107]
	v_mfma_f32_16x16x32_bf16 v[92:95], v[148:151], v[196:199], v[92:95]
	v_mfma_f32_16x16x32_bf16 v[88:91], v[156:159], v[196:199], v[88:91]
	v_mfma_f32_16x16x32_bf16 v[76:79], v[148:151], v[204:207], v[76:79]
	v_mfma_f32_16x16x32_bf16 v[72:75], v[156:159], v[204:207], v[72:75]
	v_mfma_f32_16x16x32_bf16 v[116:119], v[152:155], v[184:187], v[116:119]
	v_mfma_f32_16x16x32_bf16 v[112:115], v[160:163], v[184:187], v[112:115]
	v_mfma_f32_16x16x32_bf16 v[108:111], v[152:155], v[192:195], v[108:111]
	v_mfma_f32_16x16x32_bf16 v[104:107], v[160:163], v[192:195], v[104:107]
	v_mfma_f32_16x16x32_bf16 v[92:95], v[152:155], v[200:203], v[92:95]
	v_mfma_f32_16x16x32_bf16 v[88:91], v[160:163], v[200:203], v[88:91]
	v_mfma_f32_16x16x32_bf16 v[76:79], v[152:155], v[208:211], v[76:79]
	v_mfma_f32_16x16x32_bf16 v[72:75], v[160:163], v[208:211], v[72:75]
	s_setprio 0
	s_setprio 1
	v_mfma_f32_16x16x32_bf16 v[124:127], v[164:167], v[180:183], v[124:127]
	v_mfma_f32_16x16x32_bf16 v[120:123], v[172:175], v[180:183], v[120:123]
	v_mfma_f32_16x16x32_bf16 v[100:103], v[164:167], v[188:191], v[100:103]
	v_mfma_f32_16x16x32_bf16 v[96:99], v[172:175], v[188:191], v[96:99]
	v_mfma_f32_16x16x32_bf16 v[84:87], v[164:167], v[196:199], v[84:87]
	v_mfma_f32_16x16x32_bf16 v[80:83], v[172:175], v[196:199], v[80:83]
	v_mfma_f32_16x16x32_bf16 v[68:71], v[164:167], v[204:207], v[68:71]
	v_mfma_f32_16x16x32_bf16 v[64:67], v[172:175], v[204:207], v[64:67]
	v_mfma_f32_16x16x32_bf16 v[124:127], v[168:171], v[184:187], v[124:127]
	v_mfma_f32_16x16x32_bf16 v[120:123], v[176:179], v[184:187], v[120:123]
	v_mfma_f32_16x16x32_bf16 v[100:103], v[168:171], v[192:195], v[100:103]
	v_mfma_f32_16x16x32_bf16 v[96:99], v[176:179], v[192:195], v[96:99]
	v_mfma_f32_16x16x32_bf16 v[84:87], v[168:171], v[200:203], v[84:87]
	v_mfma_f32_16x16x32_bf16 v[80:83], v[176:179], v[200:203], v[80:83]
	v_mfma_f32_16x16x32_bf16 v[68:71], v[168:171], v[208:211], v[68:71]
	v_mfma_f32_16x16x32_bf16 v[64:67], v[176:179], v[208:211], v[64:67]
	s_setprio 0
	s_barrier
	s_add_i32 s13, s61, s51
	s_mov_b32 m0, s13
	ds_read_b128 v[180:183], v145 offset:16384
	ds_read_b128 v[184:187], v145 offset:17408
	ds_read_b128 v[188:191], v145 offset:18432
	ds_read_b128 v[192:195], v145 offset:19456
	ds_read_b128 v[196:199], v145 offset:20480
	ds_read_b128 v[200:203], v145 offset:21504
	ds_read_b128 v[204:207], v145 offset:22528
	ds_read_b128 v[208:211], v145 offset:23552
	global_load_lds_dwordx4 v132, s[42:43]
	s_add_i32 m0, s13, 0x2000
	s_add_u32 s68, s42, 0x80000
	s_addc_u32 s69, s43, 0
	s_add_i32 s13, s62, s51
	global_load_lds_dwordx4 v128, s[42:43]
	s_mov_b32 m0, s13
	s_nop 0
	global_load_lds_dwordx4 v132, s[68:69]
	s_add_i32 m0, s13, 0x2000
	s_nop 0
	global_load_lds_dwordx4 v128, s[68:69]
	s_mov_b32 m0, s21
	s_nop 0
	global_load_lds_dwordx4 v134, s[46:47]
	s_mov_b32 m0, s54
	s_nop 0
	global_load_lds_dwordx4 v130, s[46:47]
	s_waitcnt vmcnt(8)
	s_waitcnt lgkmcnt(0)
	s_barrier
	s_setprio 1
	s_waitcnt lgkmcnt(0)
	v_mfma_f32_16x16x32_bf16 v[60:63], v[148:151], v[180:183], v[60:63]
	v_mfma_f32_16x16x32_bf16 v[56:59], v[156:159], v[180:183], v[56:59]
	v_mfma_f32_16x16x32_bf16 v[44:47], v[148:151], v[188:191], v[44:47]
	v_mfma_f32_16x16x32_bf16 v[40:43], v[156:159], v[188:191], v[40:43]
	v_mfma_f32_16x16x32_bf16 v[28:31], v[148:151], v[196:199], v[28:31]
	v_mfma_f32_16x16x32_bf16 v[24:27], v[156:159], v[196:199], v[24:27]
	v_mfma_f32_16x16x32_bf16 v[12:15], v[148:151], v[204:207], v[12:15]
	v_mfma_f32_16x16x32_bf16 v[8:11], v[156:159], v[204:207], v[8:11]
	v_mfma_f32_16x16x32_bf16 v[60:63], v[152:155], v[184:187], v[60:63]
	v_mfma_f32_16x16x32_bf16 v[56:59], v[160:163], v[184:187], v[56:59]
	v_mfma_f32_16x16x32_bf16 v[44:47], v[152:155], v[192:195], v[44:47]
	v_mfma_f32_16x16x32_bf16 v[40:43], v[160:163], v[192:195], v[40:43]
	v_mfma_f32_16x16x32_bf16 v[28:31], v[152:155], v[200:203], v[28:31]
	v_mfma_f32_16x16x32_bf16 v[24:27], v[160:163], v[200:203], v[24:27]
	v_mfma_f32_16x16x32_bf16 v[12:15], v[152:155], v[208:211], v[12:15]
	v_mfma_f32_16x16x32_bf16 v[8:11], v[160:163], v[208:211], v[8:11]
	s_setprio 0
	s_setprio 1
	v_mfma_f32_16x16x32_bf16 v[52:55], v[164:167], v[180:183], v[52:55]
	v_mfma_f32_16x16x32_bf16 v[48:51], v[172:175], v[180:183], v[48:51]
	v_mfma_f32_16x16x32_bf16 v[36:39], v[164:167], v[188:191], v[36:39]
	v_mfma_f32_16x16x32_bf16 v[32:35], v[172:175], v[188:191], v[32:35]
	v_mfma_f32_16x16x32_bf16 v[20:23], v[164:167], v[196:199], v[20:23]
	v_mfma_f32_16x16x32_bf16 v[16:19], v[172:175], v[196:199], v[16:19]
	v_mfma_f32_16x16x32_bf16 v[4:7], v[164:167], v[204:207], v[4:7]
	v_mfma_f32_16x16x32_bf16 v[0:3], v[172:175], v[204:207], v[0:3]
	v_mfma_f32_16x16x32_bf16 v[52:55], v[168:171], v[184:187], v[52:55]
	v_mfma_f32_16x16x32_bf16 v[48:51], v[176:179], v[184:187], v[48:51]
	v_mfma_f32_16x16x32_bf16 v[36:39], v[168:171], v[192:195], v[36:39]
	v_mfma_f32_16x16x32_bf16 v[32:35], v[176:179], v[192:195], v[32:35]
	v_mfma_f32_16x16x32_bf16 v[20:23], v[168:171], v[200:203], v[20:23]
	v_mfma_f32_16x16x32_bf16 v[16:19], v[176:179], v[200:203], v[16:19]
	v_mfma_f32_16x16x32_bf16 v[4:7], v[168:171], v[208:211], v[4:7]
	v_mfma_f32_16x16x32_bf16 v[0:3], v[176:179], v[208:211], v[0:3]
	s_setprio 0
	s_barrier
; #define PG8_STAGE(bufoff, gbase, voff) do { _Pragma("unroll") for (int _i = 0; _i < 2; ++_i) \
;         __builtin_amdgcn_global_load_lds((const unsigned*)((const char*)(gbase) + (voff)[_i]), (LAS unsigned*)(lds + (bufoff) + ldsw + _i * 8192), 16, 0, 0); } while (0)
; #define PG8_LDA(dst, b, h) do { _Pragma("unroll") for (int m = 0; m < 4; ++m) _Pragma("unroll") for (int k = 0; k < 2; ++k) dst[m][k] = *(const LAS bf16x8*)(lds + PG8_SA(b, h) + aoff + m * 2048 + k * 1024); } while (0)
; #define PG8_LDB(dst, b, h) do { _Pragma("unroll") for (int n = 0; n < 2; ++n) _Pragma("unroll") for (int k = 0; k < 2; ++k) dst[n][k] = *(const LAS bf16x8*)(lds + PG8_SB(b, h) + boff + n * 2048 + k * 1024); } while (0)
; #define PG8_MMA(ai, bj, At, Bt) do { __builtin_amdgcn_s_setprio(1); _Pragma("unroll") for (int m = 0; m < 4; ++m) _Pragma("unroll") for (int n = 0; n < 2; ++n) _Pragma("unroll") for (int k = 0; k < 2; ++k) \
;         acc[ai][bj][m][n] = __builtin_amdgcn_mfma_f32_16x16x32_bf16(Bt[n][k], At[m][k], acc[ai][bj][m][n], 0, 0, 0); __builtin_amdgcn_s_setprio(0); } while (0)
; #define PG8_WAIT_V(n) asm volatile("s_waitcnt vmcnt(" #n ")" ::: "memory")
; #define PG8_WAIT_L(n) asm volatile("s_waitcnt lgkmcnt(" #n ")" ::: "memory")
; #define PG8_BAR __builtin_amdgcn_s_barrier()
; #define PG8_SCHED __builtin_amdgcn_sched_barrier(0)
; template <class Epi>
; __device__ __forceinline__ void gemm_phase(LAS unsigned char* lds, const Gemm g, const StaticOrder S, const Epi E) {
;     ...
;             PG8_LDB(B0, 1, 0); PG8_LDB(B1, 1, 1); PG8_SCHED; PG8_LDA(At, 1, 0); PG8_STAGE(PG8_SA(0, 1), a2 + hstepA, voffA);
;             PG8_WAIT_V(8); PG8_WAIT_L(0); PG8_BAR; PG8_MMA(0, 0, At, B0); PG8_MMA(0, 1, At, B1); PG8_BAR; PG8_SCHED;
;             PG8_LDA(At, 1, 1); PG8_STAGE(PG8_SB(1, 0), b3, voffB); PG8_STAGE(PG8_SB(1, 1), b3 + hstepB, voffB); PG8_STAGE(PG8_SA(1, 0), a3, voffA);
;             PG8_WAIT_V(8); PG8_WAIT_L(0); PG8_BAR; PG8_MMA(1, 0, At, B0); PG8_MMA(1, 1, At, B1); PG8_BAR; PG8_SCHED;
;         }
	s_add_i32 s13, 0, 0x18000
	s_add_i32 s67, 0, 0x1c000
	ds_read_b128 v[148:151], v254 offset:32768
	ds_read_b128 v[152:155], v254 offset:33792
	ds_read_b128 v[156:159], v254 offset:34816
	ds_read_b128 v[160:163], v254 offset:35840
	ds_read_b128 v[164:167], v254 offset:49152
	ds_read_b128 v[168:171], v254 offset:50176
	ds_read_b128 v[172:175], v254 offset:51200
	ds_read_b128 v[176:179], v254 offset:52224
	s_add_u32 s46, s46, 0x80000
	s_addc_u32 s47, s47, 0
	s_mov_b32 m0, s55
	ds_read_b128 v[180:183], v145 offset:32768
	ds_read_b128 v[184:187], v145 offset:33792
	ds_read_b128 v[188:191], v145 offset:34816
	ds_read_b128 v[192:195], v145 offset:35840
	ds_read_b128 v[196:199], v145 offset:36864
	ds_read_b128 v[200:203], v145 offset:37888
	ds_read_b128 v[204:207], v145 offset:38912
	ds_read_b128 v[208:211], v145 offset:39936
	global_load_lds_dwordx4 v134, s[46:47]
	s_mov_b32 m0, s56
	s_nop 0
	global_load_lds_dwordx4 v130, s[46:47]
	s_waitcnt vmcnt(8)
	s_waitcnt lgkmcnt(0)
	s_barrier
	s_setprio 1
	s_waitcnt lgkmcnt(0)
	v_mfma_f32_16x16x32_bf16 v[116:119], v[148:151], v[180:183], v[116:119]
	v_mfma_f32_16x16x32_bf16 v[112:115], v[156:159], v[180:183], v[112:115]
	v_mfma_f32_16x16x32_bf16 v[108:111], v[148:151], v[188:191], v[108:111]
	v_mfma_f32_16x16x32_bf16 v[104:107], v[156:159], v[188:191], v[104:107]
	v_mfma_f32_16x16x32_bf16 v[92:95], v[148:151], v[196:199], v[92:95]
	v_mfma_f32_16x16x32_bf16 v[88:91], v[156:159], v[196:199], v[88:91]
	v_mfma_f32_16x16x32_bf16 v[76:79], v[148:151], v[204:207], v[76:79]
	v_mfma_f32_16x16x32_bf16 v[72:75], v[156:159], v[204:207], v[72:75]
	v_mfma_f32_16x16x32_bf16 v[116:119], v[152:155], v[184:187], v[116:119]
	v_mfma_f32_16x16x32_bf16 v[112:115], v[160:163], v[184:187], v[112:115]
	v_mfma_f32_16x16x32_bf16 v[108:111], v[152:155], v[192:195], v[108:111]
	v_mfma_f32_16x16x32_bf16 v[104:107], v[160:163], v[192:195], v[104:107]
	v_mfma_f32_16x16x32_bf16 v[92:95], v[152:155], v[200:203], v[92:95]
	v_mfma_f32_16x16x32_bf16 v[88:91], v[160:163], v[200:203], v[88:91]
	v_mfma_f32_16x16x32_bf16 v[76:79], v[152:155], v[208:211], v[76:79]
	v_mfma_f32_16x16x32_bf16 v[72:75], v[160:163], v[208:211], v[72:75]
	s_setprio 0
	s_setprio 1
	v_mfma_f32_16x16x32_bf16 v[124:127], v[164:167], v[180:183], v[124:127]
	v_mfma_f32_16x16x32_bf16 v[120:123], v[172:175], v[180:183], v[120:123]
	v_mfma_f32_16x16x32_bf16 v[100:103], v[164:167], v[188:191], v[100:103]
	v_mfma_f32_16x16x32_bf16 v[96:99], v[172:175], v[188:191], v[96:99]
	v_mfma_f32_16x16x32_bf16 v[84:87], v[164:167], v[196:199], v[84:87]
	v_mfma_f32_16x16x32_bf16 v[80:83], v[172:175], v[196:199], v[80:83]
	v_mfma_f32_16x16x32_bf16 v[68:71], v[164:167], v[204:207], v[68:71]
	v_mfma_f32_16x16x32_bf16 v[64:67], v[172:175], v[204:207], v[64:67]
	v_mfma_f32_16x16x32_bf16 v[124:127], v[168:171], v[184:187], v[124:127]
	v_mfma_f32_16x16x32_bf16 v[120:123], v[176:179], v[184:187], v[120:123]
	v_mfma_f32_16x16x32_bf16 v[100:103], v[168:171], v[192:195], v[100:103]
	v_mfma_f32_16x16x32_bf16 v[96:99], v[176:179], v[192:195], v[96:99]
	v_mfma_f32_16x16x32_bf16 v[84:87], v[168:171], v[200:203], v[84:87]
	v_mfma_f32_16x16x32_bf16 v[80:83], v[176:179], v[200:203], v[80:83]
	v_mfma_f32_16x16x32_bf16 v[68:71], v[168:171], v[208:211], v[68:71]
	v_mfma_f32_16x16x32_bf16 v[64:67], v[176:179], v[208:211], v[64:67]
	s_setprio 0
	s_barrier
	s_add_u32 s42, s42, s44
	s_addc_u32 s43, s43, s45
	s_add_i32 s13, s13, s51
	s_mov_b32 m0, s13
	ds_read_b128 v[180:183], v145 offset:49152
	ds_read_b128 v[184:187], v145 offset:50176
	ds_read_b128 v[188:191], v145 offset:51200
	ds_read_b128 v[192:195], v145 offset:52224
	ds_read_b128 v[196:199], v145 offset:53248
	ds_read_b128 v[200:203], v145 offset:54272
	ds_read_b128 v[204:207], v145 offset:55296
	ds_read_b128 v[208:211], v145 offset:56320
	global_load_lds_dwordx4 v132, s[42:43]
	s_add_i32 m0, s13, 0x2000
	s_nop 0
	global_load_lds_dwordx4 v128, s[42:43]
	s_add_u32 s42, s42, 0x80000
	s_addc_u32 s43, s43, 0
	s_add_i32 s13, s67, s51
	s_mov_b32 m0, s13
	s_nop 0
	global_load_lds_dwordx4 v132, s[42:43]
	s_add_i32 m0, s13, 0x2000
	s_nop 0
	global_load_lds_dwordx4 v128, s[42:43]
	s_mov_b32 m0, s57
	s_nop 0
	global_load_lds_dwordx4 v134, s[48:49]
	s_mov_b32 m0, s58
	s_nop 0
	global_load_lds_dwordx4 v130, s[48:49]
	s_waitcnt vmcnt(8)
	s_waitcnt lgkmcnt(0)
	s_barrier
	s_setprio 1
	s_waitcnt lgkmcnt(0)
	v_mfma_f32_16x16x32_bf16 v[60:63], v[148:151], v[180:183], v[60:63]
	v_mfma_f32_16x16x32_bf16 v[56:59], v[156:159], v[180:183], v[56:59]
	v_mfma_f32_16x16x32_bf16 v[44:47], v[148:151], v[188:191], v[44:47]
	v_mfma_f32_16x16x32_bf16 v[40:43], v[156:159], v[188:191], v[40:43]
	v_mfma_f32_16x16x32_bf16 v[28:31], v[148:151], v[196:199], v[28:31]
	v_mfma_f32_16x16x32_bf16 v[24:27], v[156:159], v[196:199], v[24:27]
	v_mfma_f32_16x16x32_bf16 v[12:15], v[148:151], v[204:207], v[12:15]
	v_mfma_f32_16x16x32_bf16 v[8:11], v[156:159], v[204:207], v[8:11]
	v_mfma_f32_16x16x32_bf16 v[60:63], v[152:155], v[184:187], v[60:63]
	v_mfma_f32_16x16x32_bf16 v[56:59], v[160:163], v[184:187], v[56:59]
	v_mfma_f32_16x16x32_bf16 v[44:47], v[152:155], v[192:195], v[44:47]
	v_mfma_f32_16x16x32_bf16 v[40:43], v[160:163], v[192:195], v[40:43]
	v_mfma_f32_16x16x32_bf16 v[28:31], v[152:155], v[200:203], v[28:31]
	v_mfma_f32_16x16x32_bf16 v[24:27], v[160:163], v[200:203], v[24:27]
	v_mfma_f32_16x16x32_bf16 v[12:15], v[152:155], v[208:211], v[12:15]
	v_mfma_f32_16x16x32_bf16 v[8:11], v[160:163], v[208:211], v[8:11]
	s_setprio 0
	s_setprio 1
	v_mfma_f32_16x16x32_bf16 v[52:55], v[164:167], v[180:183], v[52:55]
	v_mfma_f32_16x16x32_bf16 v[48:51], v[172:175], v[180:183], v[48:51]
	v_mfma_f32_16x16x32_bf16 v[36:39], v[164:167], v[188:191], v[36:39]
	v_mfma_f32_16x16x32_bf16 v[32:35], v[172:175], v[188:191], v[32:35]
	v_mfma_f32_16x16x32_bf16 v[20:23], v[164:167], v[196:199], v[20:23]
	v_mfma_f32_16x16x32_bf16 v[16:19], v[172:175], v[196:199], v[16:19]
	v_mfma_f32_16x16x32_bf16 v[4:7], v[164:167], v[204:207], v[4:7]
	v_mfma_f32_16x16x32_bf16 v[0:3], v[172:175], v[204:207], v[0:3]
	v_mfma_f32_16x16x32_bf16 v[52:55], v[168:171], v[184:187], v[52:55]
	v_mfma_f32_16x16x32_bf16 v[48:51], v[176:179], v[184:187], v[48:51]
	v_mfma_f32_16x16x32_bf16 v[36:39], v[168:171], v[192:195], v[36:39]
	v_mfma_f32_16x16x32_bf16 v[32:35], v[176:179], v[192:195], v[32:35]
	v_mfma_f32_16x16x32_bf16 v[20:23], v[168:171], v[200:203], v[20:23]
	v_mfma_f32_16x16x32_bf16 v[16:19], v[176:179], v[200:203], v[16:19]
	v_mfma_f32_16x16x32_bf16 v[4:7], v[168:171], v[208:211], v[4:7]
	v_mfma_f32_16x16x32_bf16 v[0:3], v[176:179], v[208:211], v[0:3]
	s_setprio 0
	s_barrier
	s_cmp_gt_u32 s66, 29
	s_mov_b32 s66, s11
	s_cbranch_scc1 .LBB0_671
; #define PG8_STAGE(bufoff, gbase, voff) do { _Pragma("unroll") for (int _i = 0; _i < 2; ++_i) \
;         __builtin_amdgcn_global_load_lds((const unsigned*)((const char*)(gbase) + (voff)[_i]), (LAS unsigned*)(lds + (bufoff) + ldsw + _i * 8192), 16, 0, 0); } while (0)
; #define PG8_LDA(dst, b, h) do { _Pragma("unroll") for (int m = 0; m < 4; ++m) _Pragma("unroll") for (int k = 0; k < 2; ++k) dst[m][k] = *(const LAS bf16x8*)(lds + PG8_SA(b, h) + aoff + m * 2048 + k * 1024); } while (0)
; #define PG8_LDB(dst, b, h) do { _Pragma("unroll") for (int n = 0; n < 2; ++n) _Pragma("unroll") for (int k = 0; k < 2; ++k) dst[n][k] = *(const LAS bf16x8*)(lds + PG8_SB(b, h) + boff + n * 2048 + k * 1024); } while (0)
; #define PG8_SCHED __builtin_amdgcn_sched_barrier(0)
; template <class Epi>
; __device__ __forceinline__ void gemm_phase(LAS unsigned char* lds, const Gemm g, const StaticOrder S, const Epi E) {
;     ...
;             const bool last = (t == nt - 2);
;             const char* a1 = cA + (long)(t + 1) * ksc;
;             const char* a2 = last ? nA : cA + (long)(t + 2) * ksc; const char* b2 = last ? nB : cB + (long)(t + 2) * ksc;
;             const long ks3 = last ? ksn : ksc;
;             const char* a3 = a2 + ks3; const char* b3 = b2 + ks3;
;             PG8_LDB(B0, 0, 0); PG8_LDB(B1, 0, 1); PG8_SCHED; PG8_LDA(At, 0, 0); PG8_STAGE(PG8_SA(1, 1), a1 + hstepA, voffA);
.LBB0_667:
	ds_read_b128 v[148:151], v254
	ds_read_b128 v[152:155], v254 offset:1024
	ds_read_b128 v[156:159], v254 offset:2048
	ds_read_b128 v[160:163], v254 offset:3072
	ds_read_b128 v[164:167], v254 offset:16384
	ds_read_b128 v[168:171], v254 offset:17408
	ds_read_b128 v[172:175], v254 offset:18432
	ds_read_b128 v[176:179], v254 offset:19456
	ds_read_b128 v[180:183], v145
	ds_read_b128 v[184:187], v145 offset:1024
	ds_read_b128 v[188:191], v145 offset:2048
	ds_read_b128 v[192:195], v145 offset:3072
	ds_read_b128 v[196:199], v145 offset:4096
	ds_read_b128 v[200:203], v145 offset:5120
	ds_read_b128 v[204:207], v145 offset:6144
	ds_read_b128 v[208:211], v145 offset:7168
	s_cmp_lg_u32 s66, 30
	s_cselect_b64 s[42:43], -1, 0
	s_cmp_eq_u32 s66, 30
	s_mov_b64 s[46:47], s[30:31]
	s_cbranch_scc1 .LBB0_669
	s_add_i32 s11, s66, 2
	s_mul_i32 s13, s27, s11
	s_mul_hi_u32 s44, s26, s11
	s_add_i32 s44, s44, s13
	s_mul_i32 s11, s26, s11
	s_add_u32 s46, s24, s11
	s_addc_u32 s47, s25, s44

; #define PG8_STAGE(bufoff, gbase, voff) do { _Pragma("unroll") for (int _i = 0; _i < 2; ++_i) \
;         __builtin_amdgcn_global_load_lds((const unsigned*)((const char*)(gbase) + (voff)[_i]), (LAS unsigned*)(lds + (bufoff) + ldsw + _i * 8192), 16, 0, 0); } while (0)
; #define PG8_LDA(dst, b, h) do { _Pragma("unroll") for (int m = 0; m < 4; ++m) _Pragma("unroll") for (int k = 0; k < 2; ++k) dst[m][k] = *(const LAS bf16x8*)(lds + PG8_SA(b, h) + aoff + m * 2048 + k * 1024); } while (0)
; #define PG8_LDB(dst, b, h) do { _Pragma("unroll") for (int n = 0; n < 2; ++n) _Pragma("unroll") for (int k = 0; k < 2; ++k) dst[n][k] = *(const LAS bf16x8*)(lds + PG8_SB(b, h) + boff + n * 2048 + k * 1024); } while (0)
; #define PG8_MMA(ai, bj, At, Bt) do { __builtin_amdgcn_s_setprio(1); _Pragma("unroll") for (int m = 0; m < 4; ++m) _Pragma("unroll") for (int n = 0; n < 2; ++n) _Pragma("unroll") for (int k = 0; k < 2; ++k) \
;         acc[ai][bj][m][n] = __builtin_amdgcn_mfma_f32_16x16x32_bf16(Bt[n][k], At[m][k], acc[ai][bj][m][n], 0, 0, 0); __builtin_amdgcn_s_setprio(0); } while (0)
; #define PG8_WAIT_V(n) asm volatile("s_waitcnt vmcnt(" #n ")" ::: "memory")
; #define PG8_WAIT_L(n) asm volatile("s_waitcnt lgkmcnt(" #n ")" ::: "memory")
; #define PG8_BAR __builtin_amdgcn_s_barrier()
; #define PG8_SCHED __builtin_amdgcn_sched_barrier(0)
; template <class Epi>
; __device__ __forceinline__ void gemm_phase(LAS unsigned char* lds, const Gemm g, const StaticOrder S, const Epi E) {
;     ...
;             const char* a1 = cA + (long)(t + 1) * ksc;
;             const char* a2 = last ? nA : cA + (long)(t + 2) * ksc; const char* b2 = last ? nB : cB + (long)(t + 2) * ksc;
;             const long ks3 = last ? ksn : ksc;
;             const char* a3 = a2 + ks3; const char* b3 = b2 + ks3;
;             PG8_LDB(B0, 0, 0); PG8_LDB(B1, 0, 1); PG8_SCHED; PG8_LDA(At, 0, 0); PG8_STAGE(PG8_SA(1, 1), a1 + hstepA, voffA);
;             PG8_WAIT_V(8); PG8_WAIT_L(0); PG8_BAR; PG8_MMA(0, 0, At, B0); PG8_MMA(0, 1, At, B1); PG8_BAR; PG8_SCHED;
;             PG8_LDA(At, 0, 1); PG8_STAGE(PG8_SB(0, 0), b2, voffB); PG8_STAGE(PG8_SB(0, 1), b2 + hstepB, voffB); PG8_STAGE(PG8_SA(0, 0), a2, voffA);
;             PG8_WAIT_V(8); PG8_WAIT_L(0); PG8_BAR; PG8_MMA(1, 0, At, B0); PG8_MMA(1, 1, At, B1); PG8_BAR; PG8_SCHED;
.LBB0_753:
	s_or_b32 s48, s71, 1
	s_mul_i32 s49, s35, s48
	s_mul_hi_u32 s73, s34, s48
	s_add_i32 s73, s73, s49
	s_mul_i32 s48, s34, s48
	s_add_u32 s74, s30, s48
	s_addc_u32 s73, s31, s73
	s_add_u32 s48, s46, s44
	s_addc_u32 s49, s47, s45
	s_add_u32 s74, s74, 0x160000
	s_addc_u32 s75, s73, 0
	s_add_i32 m0, s52, 0xc000
	global_load_lds_dwordx4 v140, s[74:75]
	s_add_i32 m0, s52, 0xe000
	s_nop 0
	global_load_lds_dwordx4 v144, s[74:75]
	s_waitcnt vmcnt(8)
	s_waitcnt lgkmcnt(0)
	s_barrier
	s_setprio 1
	s_waitcnt lgkmcnt(0)
	v_mfma_f32_16x16x32_bf16 v[124:127], v[128:131], v[180:183], v[124:127]
	v_mfma_f32_16x16x32_bf16 v[120:123], v[136:139], v[180:183], v[120:123]
	v_mfma_f32_16x16x32_bf16 v[108:111], v[128:131], v[188:191], v[108:111]
	v_mfma_f32_16x16x32_bf16 v[104:107], v[136:139], v[188:191], v[104:107]
	v_mfma_f32_16x16x32_bf16 v[92:95], v[128:131], v[196:199], v[92:95]
	v_mfma_f32_16x16x32_bf16 v[88:91], v[136:139], v[196:199], v[88:91]
	v_mfma_f32_16x16x32_bf16 v[76:79], v[128:131], v[204:207], v[76:79]
	v_mfma_f32_16x16x32_bf16 v[72:75], v[136:139], v[204:207], v[72:75]
	v_mfma_f32_16x16x32_bf16 v[124:127], v[132:135], v[184:187], v[124:127]
	v_mfma_f32_16x16x32_bf16 v[120:123], v[152:155], v[184:187], v[120:123]
	v_mfma_f32_16x16x32_bf16 v[108:111], v[132:135], v[192:195], v[108:111]
	v_mfma_f32_16x16x32_bf16 v[104:107], v[152:155], v[192:195], v[104:107]
	v_mfma_f32_16x16x32_bf16 v[92:95], v[132:135], v[200:203], v[92:95]
	v_mfma_f32_16x16x32_bf16 v[88:91], v[152:155], v[200:203], v[88:91]
	v_mfma_f32_16x16x32_bf16 v[76:79], v[132:135], v[208:211], v[76:79]
	v_mfma_f32_16x16x32_bf16 v[72:75], v[152:155], v[208:211], v[72:75]
	s_setprio 0
	s_setprio 1
	v_mfma_f32_16x16x32_bf16 v[116:119], v[156:159], v[180:183], v[116:119]
	v_mfma_f32_16x16x32_bf16 v[112:115], v[172:175], v[180:183], v[112:115]
	v_mfma_f32_16x16x32_bf16 v[100:103], v[156:159], v[188:191], v[100:103]
	v_mfma_f32_16x16x32_bf16 v[96:99], v[172:175], v[188:191], v[96:99]
	v_mfma_f32_16x16x32_bf16 v[84:87], v[156:159], v[196:199], v[84:87]
	v_mfma_f32_16x16x32_bf16 v[80:83], v[172:175], v[196:199], v[80:83]
	v_mfma_f32_16x16x32_bf16 v[68:71], v[156:159], v[204:207], v[68:71]
	v_mfma_f32_16x16x32_bf16 v[64:67], v[172:175], v[204:207], v[64:67]
	v_mfma_f32_16x16x32_bf16 v[116:119], v[168:171], v[184:187], v[116:119]
	v_mfma_f32_16x16x32_bf16 v[112:115], v[176:179], v[184:187], v[112:115]
	v_mfma_f32_16x16x32_bf16 v[100:103], v[168:171], v[192:195], v[100:103]
	v_mfma_f32_16x16x32_bf16 v[96:99], v[176:179], v[192:195], v[96:99]
	v_mfma_f32_16x16x32_bf16 v[84:87], v[168:171], v[200:203], v[84:87]
	v_mfma_f32_16x16x32_bf16 v[80:83], v[176:179], v[200:203], v[80:83]
	v_mfma_f32_16x16x32_bf16 v[68:71], v[168:171], v[208:211], v[68:71]
	v_mfma_f32_16x16x32_bf16 v[64:67], v[176:179], v[208:211], v[64:67]
	s_setprio 0
	s_barrier
	s_add_i32 s73, s60, s51
	s_mov_b32 m0, s73
	ds_read_b128 v[180:183], v166 offset:16384
	ds_read_b128 v[184:187], v166 offset:17408
	ds_read_b128 v[188:191], v166 offset:18432
	ds_read_b128 v[192:195], v166 offset:19456
	ds_read_b128 v[196:199], v166 offset:20480
	ds_read_b128 v[200:203], v166 offset:21504
	ds_read_b128 v[204:207], v166 offset:22528
	ds_read_b128 v[208:211], v166 offset:23552
	global_load_lds_dwordx4 v142, s[42:43]
	s_add_i32 m0, s73, 0x2000
	s_add_u32 s74, s42, 0x160000
	s_addc_u32 s75, s43, 0
	s_add_i32 s73, s61, s51
	global_load_lds_dwordx4 v146, s[42:43]
	s_mov_b32 m0, s73
	s_nop 0
	global_load_lds_dwordx4 v142, s[74:75]
	s_add_i32 m0, s73, 0x2000
	s_nop 0
	global_load_lds_dwordx4 v146, s[74:75]
	s_mov_b32 m0, s52
	s_nop 0
	global_load_lds_dwordx4 v140, s[46:47]
	s_mov_b32 m0, s53
	s_nop 0
	global_load_lds_dwordx4 v144, s[46:47]
	s_waitcnt vmcnt(8)
	s_waitcnt lgkmcnt(0)
	s_barrier
	s_setprio 1
	s_waitcnt lgkmcnt(0)
	v_mfma_f32_16x16x32_bf16 v[60:63], v[128:131], v[180:183], v[60:63]
	v_mfma_f32_16x16x32_bf16 v[56:59], v[136:139], v[180:183], v[56:59]
	v_mfma_f32_16x16x32_bf16 v[44:47], v[128:131], v[188:191], v[44:47]
	v_mfma_f32_16x16x32_bf16 v[40:43], v[136:139], v[188:191], v[40:43]
	v_mfma_f32_16x16x32_bf16 v[28:31], v[128:131], v[196:199], v[28:31]
	v_mfma_f32_16x16x32_bf16 v[24:27], v[136:139], v[196:199], v[24:27]
	v_mfma_f32_16x16x32_bf16 v[12:15], v[128:131], v[204:207], v[12:15]
	v_mfma_f32_16x16x32_bf16 v[8:11], v[136:139], v[204:207], v[8:11]
	v_mfma_f32_16x16x32_bf16 v[60:63], v[132:135], v[184:187], v[60:63]
	v_mfma_f32_16x16x32_bf16 v[56:59], v[152:155], v[184:187], v[56:59]
	v_mfma_f32_16x16x32_bf16 v[44:47], v[132:135], v[192:195], v[44:47]
	v_mfma_f32_16x16x32_bf16 v[40:43], v[152:155], v[192:195], v[40:43]
	v_mfma_f32_16x16x32_bf16 v[28:31], v[132:135], v[200:203], v[28:31]
	v_mfma_f32_16x16x32_bf16 v[24:27], v[152:155], v[200:203], v[24:27]
	v_mfma_f32_16x16x32_bf16 v[12:15], v[132:135], v[208:211], v[12:15]
	v_mfma_f32_16x16x32_bf16 v[8:11], v[152:155], v[208:211], v[8:11]
	s_setprio 0
	s_setprio 1
	v_mfma_f32_16x16x32_bf16 v[52:55], v[156:159], v[180:183], v[52:55]
	v_mfma_f32_16x16x32_bf16 v[48:51], v[172:175], v[180:183], v[48:51]
	v_mfma_f32_16x16x32_bf16 v[36:39], v[156:159], v[188:191], v[36:39]
	v_mfma_f32_16x16x32_bf16 v[32:35], v[172:175], v[188:191], v[32:35]
	v_mfma_f32_16x16x32_bf16 v[20:23], v[156:159], v[196:199], v[20:23]
	v_mfma_f32_16x16x32_bf16 v[16:19], v[172:175], v[196:199], v[16:19]
	v_mfma_f32_16x16x32_bf16 v[4:7], v[156:159], v[204:207], v[4:7]
	v_mfma_f32_16x16x32_bf16 v[0:3], v[172:175], v[204:207], v[0:3]
	v_mfma_f32_16x16x32_bf16 v[52:55], v[168:171], v[184:187], v[52:55]
	v_mfma_f32_16x16x32_bf16 v[48:51], v[176:179], v[184:187], v[48:51]
	v_mfma_f32_16x16x32_bf16 v[36:39], v[168:171], v[192:195], v[36:39]
	v_mfma_f32_16x16x32_bf16 v[32:35], v[176:179], v[192:195], v[32:35]
	v_mfma_f32_16x16x32_bf16 v[20:23], v[168:171], v[200:203], v[20:23]
	v_mfma_f32_16x16x32_bf16 v[16:19], v[176:179], v[200:203], v[16:19]
	v_mfma_f32_16x16x32_bf16 v[4:7], v[168:171], v[208:211], v[4:7]
	v_mfma_f32_16x16x32_bf16 v[0:3], v[176:179], v[208:211], v[0:3]
	s_setprio 0
	s_barrier
; #define PG8_STAGE(bufoff, gbase, voff) do { _Pragma("unroll") for (int _i = 0; _i < 2; ++_i) \
;         __builtin_amdgcn_global_load_lds((const unsigned*)((const char*)(gbase) + (voff)[_i]), (LAS unsigned*)(lds + (bufoff) + ldsw + _i * 8192), 16, 0, 0); } while (0)
; #define PG8_LDA(dst, b, h) do { _Pragma("unroll") for (int m = 0; m < 4; ++m) _Pragma("unroll") for (int k = 0; k < 2; ++k) dst[m][k] = *(const LAS bf16x8*)(lds + PG8_SA(b, h) + aoff + m * 2048 + k * 1024); } while (0)
; #define PG8_LDB(dst, b, h) do { _Pragma("unroll") for (int n = 0; n < 2; ++n) _Pragma("unroll") for (int k = 0; k < 2; ++k) dst[n][k] = *(const LAS bf16x8*)(lds + PG8_SB(b, h) + boff + n * 2048 + k * 1024); } while (0)
; #define PG8_MMA(ai, bj, At, Bt) do { __builtin_amdgcn_s_setprio(1); _Pragma("unroll") for (int m = 0; m < 4; ++m) _Pragma("unroll") for (int n = 0; n < 2; ++n) _Pragma("unroll") for (int k = 0; k < 2; ++k) \
;         acc[ai][bj][m][n] = __builtin_amdgcn_mfma_f32_16x16x32_bf16(Bt[n][k], At[m][k], acc[ai][bj][m][n], 0, 0, 0); __builtin_amdgcn_s_setprio(0); } while (0)
; #define PG8_WAIT_V(n) asm volatile("s_waitcnt vmcnt(" #n ")" ::: "memory")
; #define PG8_WAIT_L(n) asm volatile("s_waitcnt lgkmcnt(" #n ")" ::: "memory")
; #define PG8_BAR __builtin_amdgcn_s_barrier()
; #define PG8_SCHED __builtin_amdgcn_sched_barrier(0)
; template <class Epi>
; __device__ __forceinline__ void gemm_phase(LAS unsigned char* lds, const Gemm g, const StaticOrder S, const Epi E) {
;     ...
;             PG8_LDB(B0, 1, 0); PG8_LDB(B1, 1, 1); PG8_SCHED; PG8_LDA(At, 1, 0); PG8_STAGE(PG8_SA(0, 1), a2 + hstepA, voffA);
;             PG8_WAIT_V(8); PG8_WAIT_L(0); PG8_BAR; PG8_MMA(0, 0, At, B0); PG8_MMA(0, 1, At, B1); PG8_BAR; PG8_SCHED;
;             PG8_LDA(At, 1, 1); PG8_STAGE(PG8_SB(1, 0), b3, voffB); PG8_STAGE(PG8_SB(1, 1), b3 + hstepB, voffB); PG8_STAGE(PG8_SA(1, 0), a3, voffA);
;             PG8_WAIT_V(8); PG8_WAIT_L(0); PG8_BAR; PG8_MMA(1, 0, At, B0); PG8_MMA(1, 1, At, B1); PG8_BAR; PG8_SCHED;
;         }
	s_add_i32 s73, 0, 0x18000
	s_add_i32 s74, 0, 0x1c000
	v_add_u32_e32 v152, s73, v164
	v_add_u32_e32 v176, s74, v164
	ds_read_b128 v[128:131], v152
	ds_read_b128 v[132:135], v152 offset:1024
	ds_read_b128 v[136:139], v152 offset:2048
	ds_read_b128 v[152:155], v152 offset:3072
	ds_read_b128 v[156:159], v176
	ds_read_b128 v[168:171], v176 offset:1024
	ds_read_b128 v[172:175], v176 offset:2048
	ds_read_b128 v[176:179], v176 offset:3072
	s_add_u32 s46, s46, 0x160000
	s_addc_u32 s47, s47, 0
	s_mov_b32 m0, s54
	ds_read_b128 v[180:183], v166 offset:32768
	ds_read_b128 v[184:187], v166 offset:33792
	ds_read_b128 v[188:191], v166 offset:34816
	ds_read_b128 v[192:195], v166 offset:35840
	ds_read_b128 v[196:199], v166 offset:36864
	ds_read_b128 v[200:203], v166 offset:37888
	ds_read_b128 v[204:207], v166 offset:38912
	ds_read_b128 v[208:211], v166 offset:39936
	global_load_lds_dwordx4 v140, s[46:47]
	s_mov_b32 m0, s55
	s_nop 0
	global_load_lds_dwordx4 v144, s[46:47]
	s_waitcnt vmcnt(8)
	s_waitcnt lgkmcnt(0)
	s_barrier
	s_setprio 1
	s_waitcnt lgkmcnt(0)
	v_mfma_f32_16x16x32_bf16 v[124:127], v[128:131], v[180:183], v[124:127]
	v_mfma_f32_16x16x32_bf16 v[120:123], v[136:139], v[180:183], v[120:123]
	v_mfma_f32_16x16x32_bf16 v[108:111], v[128:131], v[188:191], v[108:111]
	v_mfma_f32_16x16x32_bf16 v[104:107], v[136:139], v[188:191], v[104:107]
	v_mfma_f32_16x16x32_bf16 v[92:95], v[128:131], v[196:199], v[92:95]
	v_mfma_f32_16x16x32_bf16 v[88:91], v[136:139], v[196:199], v[88:91]
	v_mfma_f32_16x16x32_bf16 v[76:79], v[128:131], v[204:207], v[76:79]
	v_mfma_f32_16x16x32_bf16 v[72:75], v[136:139], v[204:207], v[72:75]
	v_mfma_f32_16x16x32_bf16 v[124:127], v[132:135], v[184:187], v[124:127]
	v_mfma_f32_16x16x32_bf16 v[120:123], v[152:155], v[184:187], v[120:123]
	v_mfma_f32_16x16x32_bf16 v[108:111], v[132:135], v[192:195], v[108:111]
	v_mfma_f32_16x16x32_bf16 v[104:107], v[152:155], v[192:195], v[104:107]
	v_mfma_f32_16x16x32_bf16 v[92:95], v[132:135], v[200:203], v[92:95]
	v_mfma_f32_16x16x32_bf16 v[88:91], v[152:155], v[200:203], v[88:91]
	v_mfma_f32_16x16x32_bf16 v[76:79], v[132:135], v[208:211], v[76:79]
	v_mfma_f32_16x16x32_bf16 v[72:75], v[152:155], v[208:211], v[72:75]
	s_setprio 0
	s_setprio 1
	v_mfma_f32_16x16x32_bf16 v[116:119], v[156:159], v[180:183], v[116:119]
	v_mfma_f32_16x16x32_bf16 v[112:115], v[172:175], v[180:183], v[112:115]
	v_mfma_f32_16x16x32_bf16 v[100:103], v[156:159], v[188:191], v[100:103]
	v_mfma_f32_16x16x32_bf16 v[96:99], v[172:175], v[188:191], v[96:99]
	v_mfma_f32_16x16x32_bf16 v[84:87], v[156:159], v[196:199], v[84:87]
	v_mfma_f32_16x16x32_bf16 v[80:83], v[172:175], v[196:199], v[80:83]
	v_mfma_f32_16x16x32_bf16 v[68:71], v[156:159], v[204:207], v[68:71]
	v_mfma_f32_16x16x32_bf16 v[64:67], v[172:175], v[204:207], v[64:67]
	v_mfma_f32_16x16x32_bf16 v[116:119], v[168:171], v[184:187], v[116:119]
	v_mfma_f32_16x16x32_bf16 v[112:115], v[176:179], v[184:187], v[112:115]
	v_mfma_f32_16x16x32_bf16 v[100:103], v[168:171], v[192:195], v[100:103]
	v_mfma_f32_16x16x32_bf16 v[96:99], v[176:179], v[192:195], v[96:99]
	v_mfma_f32_16x16x32_bf16 v[84:87], v[168:171], v[200:203], v[84:87]
	v_mfma_f32_16x16x32_bf16 v[80:83], v[176:179], v[200:203], v[80:83]
	v_mfma_f32_16x16x32_bf16 v[68:71], v[168:171], v[208:211], v[68:71]
	v_mfma_f32_16x16x32_bf16 v[64:67], v[176:179], v[208:211], v[64:67]
	s_setprio 0
	s_barrier
	s_add_u32 s42, s42, s44
	s_addc_u32 s43, s43, s45
	s_add_i32 s44, s73, s51
	s_mov_b32 m0, s44
	ds_read_b128 v[180:183], v166 offset:49152
	ds_read_b128 v[184:187], v166 offset:50176
	ds_read_b128 v[188:191], v166 offset:51200
	ds_read_b128 v[192:195], v166 offset:52224
	ds_read_b128 v[196:199], v166 offset:53248
	ds_read_b128 v[200:203], v166 offset:54272
	ds_read_b128 v[204:207], v166 offset:55296
	ds_read_b128 v[208:211], v166 offset:56320
	global_load_lds_dwordx4 v142, s[42:43]
	s_add_i32 m0, s44, 0x2000
	s_nop 0
	global_load_lds_dwordx4 v146, s[42:43]
	s_add_u32 s42, s42, 0x160000
	s_addc_u32 s43, s43, 0
	s_add_i32 s44, s74, s51
	s_mov_b32 m0, s44
	s_nop 0
	global_load_lds_dwordx4 v142, s[42:43]
	s_add_i32 m0, s44, 0x2000
	s_nop 0
	global_load_lds_dwordx4 v146, s[42:43]
	s_mov_b32 m0, s57
	s_nop 0
	global_load_lds_dwordx4 v140, s[48:49]
	s_mov_b32 m0, s58
	s_nop 0
	global_load_lds_dwordx4 v144, s[48:49]
	s_waitcnt vmcnt(8)
	s_waitcnt lgkmcnt(0)
	s_barrier
	s_setprio 1
	s_waitcnt lgkmcnt(0)
	v_mfma_f32_16x16x32_bf16 v[60:63], v[128:131], v[180:183], v[60:63]
	v_mfma_f32_16x16x32_bf16 v[56:59], v[136:139], v[180:183], v[56:59]
	v_mfma_f32_16x16x32_bf16 v[44:47], v[128:131], v[188:191], v[44:47]
	v_mfma_f32_16x16x32_bf16 v[40:43], v[136:139], v[188:191], v[40:43]
	v_mfma_f32_16x16x32_bf16 v[28:31], v[128:131], v[196:199], v[28:31]
	v_mfma_f32_16x16x32_bf16 v[24:27], v[136:139], v[196:199], v[24:27]
	v_mfma_f32_16x16x32_bf16 v[12:15], v[128:131], v[204:207], v[12:15]
	v_mfma_f32_16x16x32_bf16 v[8:11], v[136:139], v[204:207], v[8:11]
	v_mfma_f32_16x16x32_bf16 v[60:63], v[132:135], v[184:187], v[60:63]
	v_mfma_f32_16x16x32_bf16 v[56:59], v[152:155], v[184:187], v[56:59]
	v_mfma_f32_16x16x32_bf16 v[44:47], v[132:135], v[192:195], v[44:47]
	v_mfma_f32_16x16x32_bf16 v[40:43], v[152:155], v[192:195], v[40:43]
	v_mfma_f32_16x16x32_bf16 v[28:31], v[132:135], v[200:203], v[28:31]
	v_mfma_f32_16x16x32_bf16 v[24:27], v[152:155], v[200:203], v[24:27]
	v_mfma_f32_16x16x32_bf16 v[12:15], v[132:135], v[208:211], v[12:15]
	v_mfma_f32_16x16x32_bf16 v[8:11], v[152:155], v[208:211], v[8:11]
	s_setprio 0
	s_setprio 1
	v_mfma_f32_16x16x32_bf16 v[52:55], v[156:159], v[180:183], v[52:55]
	v_mfma_f32_16x16x32_bf16 v[48:51], v[172:175], v[180:183], v[48:51]
	v_mfma_f32_16x16x32_bf16 v[36:39], v[156:159], v[188:191], v[36:39]
	v_mfma_f32_16x16x32_bf16 v[32:35], v[172:175], v[188:191], v[32:35]
	v_mfma_f32_16x16x32_bf16 v[20:23], v[156:159], v[196:199], v[20:23]
	v_mfma_f32_16x16x32_bf16 v[16:19], v[172:175], v[196:199], v[16:19]
	v_mfma_f32_16x16x32_bf16 v[4:7], v[156:159], v[204:207], v[4:7]
	v_mfma_f32_16x16x32_bf16 v[0:3], v[172:175], v[204:207], v[0:3]
	v_mfma_f32_16x16x32_bf16 v[52:55], v[168:171], v[184:187], v[52:55]
	v_mfma_f32_16x16x32_bf16 v[48:51], v[176:179], v[184:187], v[48:51]
	v_mfma_f32_16x16x32_bf16 v[36:39], v[168:171], v[192:195], v[36:39]
	v_mfma_f32_16x16x32_bf16 v[32:35], v[176:179], v[192:195], v[32:35]
	v_mfma_f32_16x16x32_bf16 v[20:23], v[168:171], v[200:203], v[20:23]
	v_mfma_f32_16x16x32_bf16 v[16:19], v[176:179], v[200:203], v[16:19]
	v_mfma_f32_16x16x32_bf16 v[4:7], v[168:171], v[208:211], v[4:7]
	v_mfma_f32_16x16x32_bf16 v[0:3], v[176:179], v[208:211], v[0:3]
	s_setprio 0
	s_barrier
	s_cmpk_gt_u32 s71, 0x55
	s_mov_b32 s71, s72
	s_cbranch_scc1 .LBB0_758
; #define PG8_STAGE(bufoff, gbase, voff) do { _Pragma("unroll") for (int _i = 0; _i < 2; ++_i) \
;         __builtin_amdgcn_global_load_lds((const unsigned*)((const char*)(gbase) + (voff)[_i]), (LAS unsigned*)(lds + (bufoff) + ldsw + _i * 8192), 16, 0, 0); } while (0)
; #define PG8_LDA(dst, b, h) do { _Pragma("unroll") for (int m = 0; m < 4; ++m) _Pragma("unroll") for (int k = 0; k < 2; ++k) dst[m][k] = *(const LAS bf16x8*)(lds + PG8_SA(b, h) + aoff + m * 2048 + k * 1024); } while (0)
; #define PG8_LDB(dst, b, h) do { _Pragma("unroll") for (int n = 0; n < 2; ++n) _Pragma("unroll") for (int k = 0; k < 2; ++k) dst[n][k] = *(const LAS bf16x8*)(lds + PG8_SB(b, h) + boff + n * 2048 + k * 1024); } while (0)
; #define PG8_SCHED __builtin_amdgcn_sched_barrier(0)
; template <class Epi>
; __device__ __forceinline__ void gemm_phase(LAS unsigned char* lds, const Gemm g, const StaticOrder S, const Epi E) {
;     ...
;             const bool last = (t == nt - 2);
;             const char* a1 = cA + (long)(t + 1) * ksc;
;             const char* a2 = last ? nA : cA + (long)(t + 2) * ksc; const char* b2 = last ? nB : cB + (long)(t + 2) * ksc;
;             const long ks3 = last ? ksn : ksc;
;             const char* a3 = a2 + ks3; const char* b3 = b2 + ks3;
;             PG8_LDB(B0, 0, 0); PG8_LDB(B1, 0, 1); PG8_SCHED; PG8_LDA(At, 0, 0); PG8_STAGE(PG8_SA(1, 1), a1 + hstepA, voffA);
.LBB0_754:
	v_add_u32_e32 v152, s60, v164
	v_add_u32_e32 v176, s61, v164
	ds_read_b128 v[128:131], v152
	ds_read_b128 v[132:135], v152 offset:1024
	ds_read_b128 v[136:139], v152 offset:2048
	ds_read_b128 v[152:155], v152 offset:3072
	ds_read_b128 v[156:159], v176
	ds_read_b128 v[168:171], v176 offset:1024
	ds_read_b128 v[172:175], v176 offset:2048
	ds_read_b128 v[176:179], v176 offset:3072
	ds_read_b128 v[180:183], v166
	ds_read_b128 v[184:187], v166 offset:1024
	ds_read_b128 v[188:191], v166 offset:2048
	ds_read_b128 v[192:195], v166 offset:3072
	ds_read_b128 v[196:199], v166 offset:4096
	ds_read_b128 v[200:203], v166 offset:5120
	ds_read_b128 v[204:207], v166 offset:6144
	ds_read_b128 v[208:211], v166 offset:7168
	s_cmpk_lg_i32 s71, 0x56
	s_cselect_b64 s[42:43], -1, 0
	s_cmpk_eq_i32 s71, 0x56
	s_mov_b64 s[46:47], s[22:23]
	s_cbranch_scc1 .LBB0_756
	s_add_i32 s44, s71, 2
	s_mul_i32 s45, s35, s44
	s_mul_hi_u32 s46, s34, s44
	s_add_i32 s45, s46, s45
	s_mul_i32 s44, s34, s44
	s_add_u32 s46, s30, s44
	s_addc_u32 s47, s31, s45

; #define PG8_STAGE(bufoff, gbase, voff) do { _Pragma("unroll") for (int _i = 0; _i < 2; ++_i) \
;         __builtin_amdgcn_global_load_lds((const unsigned*)((const char*)(gbase) + (voff)[_i]), (LAS unsigned*)(lds + (bufoff) + ldsw + _i * 8192), 16, 0, 0); } while (0)
; #define PG8_LDA(dst, b, h) do { _Pragma("unroll") for (int m = 0; m < 4; ++m) _Pragma("unroll") for (int k = 0; k < 2; ++k) dst[m][k] = *(const LAS bf16x8*)(lds + PG8_SA(b, h) + aoff + m * 2048 + k * 1024); } while (0)
; #define PG8_LDB(dst, b, h) do { _Pragma("unroll") for (int n = 0; n < 2; ++n) _Pragma("unroll") for (int k = 0; k < 2; ++k) dst[n][k] = *(const LAS bf16x8*)(lds + PG8_SB(b, h) + boff + n * 2048 + k * 1024); } while (0)
; #define PG8_MMA(ai, bj, At, Bt) do { __builtin_amdgcn_s_setprio(1); _Pragma("unroll") for (int m = 0; m < 4; ++m) _Pragma("unroll") for (int n = 0; n < 2; ++n) _Pragma("unroll") for (int k = 0; k < 2; ++k) \
;         acc[ai][bj][m][n] = __builtin_amdgcn_mfma_f32_16x16x32_bf16(Bt[n][k], At[m][k], acc[ai][bj][m][n], 0, 0, 0); __builtin_amdgcn_s_setprio(0); } while (0)
; #define PG8_WAIT_V(n) asm volatile("s_waitcnt vmcnt(" #n ")" ::: "memory")
; #define PG8_WAIT_L(n) asm volatile("s_waitcnt lgkmcnt(" #n ")" ::: "memory")
; #define PG8_BAR __builtin_amdgcn_s_barrier()
; #define PG8_SCHED __builtin_amdgcn_sched_barrier(0)
; template <class Epi>
; __device__ __forceinline__ void gemm_phase(LAS unsigned char* lds, const Gemm g, const StaticOrder S, const Epi E) {
;     ...
;             const char* a1 = cA + (long)(t + 1) * ksc;
;             const char* a2 = last ? nA : cA + (long)(t + 2) * ksc; const char* b2 = last ? nB : cB + (long)(t + 2) * ksc;
;             const long ks3 = last ? ksn : ksc;
;             const char* a3 = a2 + ks3; const char* b3 = b2 + ks3;
;             PG8_LDB(B0, 0, 0); PG8_LDB(B1, 0, 1); PG8_SCHED; PG8_LDA(At, 0, 0); PG8_STAGE(PG8_SA(1, 1), a1 + hstepA, voffA);
;             PG8_WAIT_V(8); PG8_WAIT_L(0); PG8_BAR; PG8_MMA(0, 0, At, B0); PG8_MMA(0, 1, At, B1); PG8_BAR; PG8_SCHED;
;             PG8_LDA(At, 0, 1); PG8_STAGE(PG8_SB(0, 0), b2, voffB); PG8_STAGE(PG8_SB(0, 1), b2 + hstepB, voffB); PG8_STAGE(PG8_SA(0, 0), a2, voffA);
;             PG8_WAIT_V(8); PG8_WAIT_L(0); PG8_BAR; PG8_MMA(1, 0, At, B0); PG8_MMA(1, 1, At, B1); PG8_BAR; PG8_SCHED;
.LBB0_853:
	s_or_b32 s13, s64, 1
	s_mul_i32 s48, s27, s13
	s_mul_hi_u32 s49, s26, s13
	s_add_i32 s49, s49, s48
	s_mul_i32 s13, s26, s13
	s_add_u32 s13, s24, s13
	s_addc_u32 s65, s25, s49
	s_add_u32 s48, s46, s44
	s_addc_u32 s49, s47, s45
	s_add_u32 s66, s13, 0x80000
	s_addc_u32 s67, s65, 0
	s_add_i32 m0, s21, 0xc000
	global_load_lds_dwordx4 v134, s[66:67]
	s_add_i32 m0, s21, 0xe000
	s_nop 0
	global_load_lds_dwordx4 v130, s[66:67]
	s_waitcnt vmcnt(8)
	s_waitcnt lgkmcnt(0)
	s_barrier
	s_setprio 1
	s_waitcnt lgkmcnt(0)
	v_mfma_f32_16x16x32_bf16 v[116:119], v[148:151], v[180:183], v[116:119]
	v_mfma_f32_16x16x32_bf16 v[112:115], v[156:159], v[180:183], v[112:115]
	v_mfma_f32_16x16x32_bf16 v[108:111], v[148:151], v[188:191], v[108:111]
	v_mfma_f32_16x16x32_bf16 v[104:107], v[156:159], v[188:191], v[104:107]
	v_mfma_f32_16x16x32_bf16 v[92:95], v[148:151], v[196:199], v[92:95]
	v_mfma_f32_16x16x32_bf16 v[88:91], v[156:159], v[196:199], v[88:91]
	v_mfma_f32_16x16x32_bf16 v[76:79], v[148:151], v[204:207], v[76:79]
	v_mfma_f32_16x16x32_bf16 v[72:75], v[156:159], v[204:207], v[72:75]
	v_mfma_f32_16x16x32_bf16 v[116:119], v[152:155], v[184:187], v[116:119]
	v_mfma_f32_16x16x32_bf16 v[112:115], v[160:163], v[184:187], v[112:115]
	v_mfma_f32_16x16x32_bf16 v[108:111], v[152:155], v[192:195], v[108:111]
	v_mfma_f32_16x16x32_bf16 v[104:107], v[160:163], v[192:195], v[104:107]
	v_mfma_f32_16x16x32_bf16 v[92:95], v[152:155], v[200:203], v[92:95]
	v_mfma_f32_16x16x32_bf16 v[88:91], v[160:163], v[200:203], v[88:91]
	v_mfma_f32_16x16x32_bf16 v[76:79], v[152:155], v[208:211], v[76:79]
	v_mfma_f32_16x16x32_bf16 v[72:75], v[160:163], v[208:211], v[72:75]
	s_setprio 0
	s_setprio 1
	v_mfma_f32_16x16x32_bf16 v[124:127], v[164:167], v[180:183], v[124:127]
	v_mfma_f32_16x16x32_bf16 v[120:123], v[172:175], v[180:183], v[120:123]
	v_mfma_f32_16x16x32_bf16 v[100:103], v[164:167], v[188:191], v[100:103]
	v_mfma_f32_16x16x32_bf16 v[96:99], v[172:175], v[188:191], v[96:99]
	v_mfma_f32_16x16x32_bf16 v[84:87], v[164:167], v[196:199], v[84:87]
	v_mfma_f32_16x16x32_bf16 v[80:83], v[172:175], v[196:199], v[80:83]
	v_mfma_f32_16x16x32_bf16 v[68:71], v[164:167], v[204:207], v[68:71]
	v_mfma_f32_16x16x32_bf16 v[64:67], v[172:175], v[204:207], v[64:67]
	v_mfma_f32_16x16x32_bf16 v[124:127], v[168:171], v[184:187], v[124:127]
	v_mfma_f32_16x16x32_bf16 v[120:123], v[176:179], v[184:187], v[120:123]
	v_mfma_f32_16x16x32_bf16 v[100:103], v[168:171], v[192:195], v[100:103]
	v_mfma_f32_16x16x32_bf16 v[96:99], v[176:179], v[192:195], v[96:99]
	v_mfma_f32_16x16x32_bf16 v[84:87], v[168:171], v[200:203], v[84:87]
	v_mfma_f32_16x16x32_bf16 v[80:83], v[176:179], v[200:203], v[80:83]
	v_mfma_f32_16x16x32_bf16 v[68:71], v[168:171], v[208:211], v[68:71]
	v_mfma_f32_16x16x32_bf16 v[64:67], v[176:179], v[208:211], v[64:67]
	s_setprio 0
	s_barrier
	s_add_i32 s13, s59, s33
	s_mov_b32 m0, s13
	ds_read_b128 v[180:183], v145 offset:16384
	ds_read_b128 v[184:187], v145 offset:17408
	ds_read_b128 v[188:191], v145 offset:18432
	ds_read_b128 v[192:195], v145 offset:19456
	ds_read_b128 v[196:199], v145 offset:20480
	ds_read_b128 v[200:203], v145 offset:21504
	ds_read_b128 v[204:207], v145 offset:22528
	ds_read_b128 v[208:211], v145 offset:23552
	global_load_lds_dwordx4 v132, s[42:43]
	s_add_i32 m0, s13, 0x2000
	s_add_u32 s66, s42, 0x80000
	s_addc_u32 s67, s43, 0
	s_add_i32 s13, s60, s33
	global_load_lds_dwordx4 v128, s[42:43]
	s_mov_b32 m0, s13
	s_nop 0
	global_load_lds_dwordx4 v132, s[66:67]
	s_add_i32 m0, s13, 0x2000
	s_nop 0
	global_load_lds_dwordx4 v128, s[66:67]
	s_mov_b32 m0, s21
	s_nop 0
	global_load_lds_dwordx4 v134, s[46:47]
	s_mov_b32 m0, s52
	s_nop 0
	global_load_lds_dwordx4 v130, s[46:47]
	s_waitcnt vmcnt(8)
	s_waitcnt lgkmcnt(0)
	s_barrier
	s_setprio 1
	s_waitcnt lgkmcnt(0)
	v_mfma_f32_16x16x32_bf16 v[60:63], v[148:151], v[180:183], v[60:63]
	v_mfma_f32_16x16x32_bf16 v[56:59], v[156:159], v[180:183], v[56:59]
	v_mfma_f32_16x16x32_bf16 v[44:47], v[148:151], v[188:191], v[44:47]
	v_mfma_f32_16x16x32_bf16 v[40:43], v[156:159], v[188:191], v[40:43]
	v_mfma_f32_16x16x32_bf16 v[28:31], v[148:151], v[196:199], v[28:31]
	v_mfma_f32_16x16x32_bf16 v[24:27], v[156:159], v[196:199], v[24:27]
	v_mfma_f32_16x16x32_bf16 v[12:15], v[148:151], v[204:207], v[12:15]
	v_mfma_f32_16x16x32_bf16 v[8:11], v[156:159], v[204:207], v[8:11]
	v_mfma_f32_16x16x32_bf16 v[60:63], v[152:155], v[184:187], v[60:63]
	v_mfma_f32_16x16x32_bf16 v[56:59], v[160:163], v[184:187], v[56:59]
	v_mfma_f32_16x16x32_bf16 v[44:47], v[152:155], v[192:195], v[44:47]
	v_mfma_f32_16x16x32_bf16 v[40:43], v[160:163], v[192:195], v[40:43]
	v_mfma_f32_16x16x32_bf16 v[28:31], v[152:155], v[200:203], v[28:31]
	v_mfma_f32_16x16x32_bf16 v[24:27], v[160:163], v[200:203], v[24:27]
	v_mfma_f32_16x16x32_bf16 v[12:15], v[152:155], v[208:211], v[12:15]
	v_mfma_f32_16x16x32_bf16 v[8:11], v[160:163], v[208:211], v[8:11]
	s_setprio 0
	s_setprio 1
	v_mfma_f32_16x16x32_bf16 v[52:55], v[164:167], v[180:183], v[52:55]
	v_mfma_f32_16x16x32_bf16 v[48:51], v[172:175], v[180:183], v[48:51]
	v_mfma_f32_16x16x32_bf16 v[36:39], v[164:167], v[188:191], v[36:39]
	v_mfma_f32_16x16x32_bf16 v[32:35], v[172:175], v[188:191], v[32:35]
	v_mfma_f32_16x16x32_bf16 v[20:23], v[164:167], v[196:199], v[20:23]
	v_mfma_f32_16x16x32_bf16 v[16:19], v[172:175], v[196:199], v[16:19]
	v_mfma_f32_16x16x32_bf16 v[4:7], v[164:167], v[204:207], v[4:7]
	v_mfma_f32_16x16x32_bf16 v[0:3], v[172:175], v[204:207], v[0:3]
	v_mfma_f32_16x16x32_bf16 v[52:55], v[168:171], v[184:187], v[52:55]
	v_mfma_f32_16x16x32_bf16 v[48:51], v[176:179], v[184:187], v[48:51]
	v_mfma_f32_16x16x32_bf16 v[36:39], v[168:171], v[192:195], v[36:39]
	v_mfma_f32_16x16x32_bf16 v[32:35], v[176:179], v[192:195], v[32:35]
	v_mfma_f32_16x16x32_bf16 v[20:23], v[168:171], v[200:203], v[20:23]
	v_mfma_f32_16x16x32_bf16 v[16:19], v[176:179], v[200:203], v[16:19]
	v_mfma_f32_16x16x32_bf16 v[4:7], v[168:171], v[208:211], v[4:7]
	v_mfma_f32_16x16x32_bf16 v[0:3], v[176:179], v[208:211], v[0:3]
	s_setprio 0
	s_barrier
; #define PG8_STAGE(bufoff, gbase, voff) do { _Pragma("unroll") for (int _i = 0; _i < 2; ++_i) \
;         __builtin_amdgcn_global_load_lds((const unsigned*)((const char*)(gbase) + (voff)[_i]), (LAS unsigned*)(lds + (bufoff) + ldsw + _i * 8192), 16, 0, 0); } while (0)
; #define PG8_LDA(dst, b, h) do { _Pragma("unroll") for (int m = 0; m < 4; ++m) _Pragma("unroll") for (int k = 0; k < 2; ++k) dst[m][k] = *(const LAS bf16x8*)(lds + PG8_SA(b, h) + aoff + m * 2048 + k * 1024); } while (0)
; #define PG8_LDB(dst, b, h) do { _Pragma("unroll") for (int n = 0; n < 2; ++n) _Pragma("unroll") for (int k = 0; k < 2; ++k) dst[n][k] = *(const LAS bf16x8*)(lds + PG8_SB(b, h) + boff + n * 2048 + k * 1024); } while (0)
; #define PG8_MMA(ai, bj, At, Bt) do { __builtin_amdgcn_s_setprio(1); _Pragma("unroll") for (int m = 0; m < 4; ++m) _Pragma("unroll") for (int n = 0; n < 2; ++n) _Pragma("unroll") for (int k = 0; k < 2; ++k) \
;         acc[ai][bj][m][n] = __builtin_amdgcn_mfma_f32_16x16x32_bf16(Bt[n][k], At[m][k], acc[ai][bj][m][n], 0, 0, 0); __builtin_amdgcn_s_setprio(0); } while (0)
; #define PG8_WAIT_V(n) asm volatile("s_waitcnt vmcnt(" #n ")" ::: "memory")
; #define PG8_WAIT_L(n) asm volatile("s_waitcnt lgkmcnt(" #n ")" ::: "memory")
; #define PG8_BAR __builtin_amdgcn_s_barrier()
; #define PG8_SCHED __builtin_amdgcn_sched_barrier(0)
; template <class Epi>
; __device__ __forceinline__ void gemm_phase(LAS unsigned char* lds, const Gemm g, const StaticOrder S, const Epi E) {
;     ...
;             PG8_LDB(B0, 1, 0); PG8_LDB(B1, 1, 1); PG8_SCHED; PG8_LDA(At, 1, 0); PG8_STAGE(PG8_SA(0, 1), a2 + hstepA, voffA);
;             PG8_WAIT_V(8); PG8_WAIT_L(0); PG8_BAR; PG8_MMA(0, 0, At, B0); PG8_MMA(0, 1, At, B1); PG8_BAR; PG8_SCHED;
;             PG8_LDA(At, 1, 1); PG8_STAGE(PG8_SB(1, 0), b3, voffB); PG8_STAGE(PG8_SB(1, 1), b3 + hstepB, voffB); PG8_STAGE(PG8_SA(1, 0), a3, voffA);
;             PG8_WAIT_V(8); PG8_WAIT_L(0); PG8_BAR; PG8_MMA(1, 0, At, B0); PG8_MMA(1, 1, At, B1); PG8_BAR; PG8_SCHED;
;         }
	s_add_i32 s13, 0, 0x18000
	s_add_i32 s65, 0, 0x1c000
	ds_read_b128 v[148:151], v254 offset:32768
	ds_read_b128 v[152:155], v254 offset:33792
	ds_read_b128 v[156:159], v254 offset:34816
	ds_read_b128 v[160:163], v254 offset:35840
	ds_read_b128 v[164:167], v254 offset:49152
	ds_read_b128 v[168:171], v254 offset:50176
	ds_read_b128 v[172:175], v254 offset:51200
	ds_read_b128 v[176:179], v254 offset:52224
	s_add_u32 s46, s46, 0x80000
	s_addc_u32 s47, s47, 0
	s_mov_b32 m0, s53
	ds_read_b128 v[180:183], v145 offset:32768
	ds_read_b128 v[184:187], v145 offset:33792
	ds_read_b128 v[188:191], v145 offset:34816
	ds_read_b128 v[192:195], v145 offset:35840
	ds_read_b128 v[196:199], v145 offset:36864
	ds_read_b128 v[200:203], v145 offset:37888
	ds_read_b128 v[204:207], v145 offset:38912
	ds_read_b128 v[208:211], v145 offset:39936
	global_load_lds_dwordx4 v134, s[46:47]
	s_mov_b32 m0, s54
	s_nop 0
	global_load_lds_dwordx4 v130, s[46:47]
	s_waitcnt vmcnt(8)
	s_waitcnt lgkmcnt(0)
	s_barrier
	s_setprio 1
	s_waitcnt lgkmcnt(0)
	v_mfma_f32_16x16x32_bf16 v[116:119], v[148:151], v[180:183], v[116:119]
	v_mfma_f32_16x16x32_bf16 v[112:115], v[156:159], v[180:183], v[112:115]
	v_mfma_f32_16x16x32_bf16 v[108:111], v[148:151], v[188:191], v[108:111]
	v_mfma_f32_16x16x32_bf16 v[104:107], v[156:159], v[188:191], v[104:107]
	v_mfma_f32_16x16x32_bf16 v[92:95], v[148:151], v[196:199], v[92:95]
	v_mfma_f32_16x16x32_bf16 v[88:91], v[156:159], v[196:199], v[88:91]
	v_mfma_f32_16x16x32_bf16 v[76:79], v[148:151], v[204:207], v[76:79]
	v_mfma_f32_16x16x32_bf16 v[72:75], v[156:159], v[204:207], v[72:75]
	v_mfma_f32_16x16x32_bf16 v[116:119], v[152:155], v[184:187], v[116:119]
	v_mfma_f32_16x16x32_bf16 v[112:115], v[160:163], v[184:187], v[112:115]
	v_mfma_f32_16x16x32_bf16 v[108:111], v[152:155], v[192:195], v[108:111]
	v_mfma_f32_16x16x32_bf16 v[104:107], v[160:163], v[192:195], v[104:107]
	v_mfma_f32_16x16x32_bf16 v[92:95], v[152:155], v[200:203], v[92:95]
	v_mfma_f32_16x16x32_bf16 v[88:91], v[160:163], v[200:203], v[88:91]
	v_mfma_f32_16x16x32_bf16 v[76:79], v[152:155], v[208:211], v[76:79]
	v_mfma_f32_16x16x32_bf16 v[72:75], v[160:163], v[208:211], v[72:75]
	s_setprio 0
	s_setprio 1
	v_mfma_f32_16x16x32_bf16 v[124:127], v[164:167], v[180:183], v[124:127]
	v_mfma_f32_16x16x32_bf16 v[120:123], v[172:175], v[180:183], v[120:123]
	v_mfma_f32_16x16x32_bf16 v[100:103], v[164:167], v[188:191], v[100:103]
	v_mfma_f32_16x16x32_bf16 v[96:99], v[172:175], v[188:191], v[96:99]
	v_mfma_f32_16x16x32_bf16 v[84:87], v[164:167], v[196:199], v[84:87]
	v_mfma_f32_16x16x32_bf16 v[80:83], v[172:175], v[196:199], v[80:83]
	v_mfma_f32_16x16x32_bf16 v[68:71], v[164:167], v[204:207], v[68:71]
	v_mfma_f32_16x16x32_bf16 v[64:67], v[172:175], v[204:207], v[64:67]
	v_mfma_f32_16x16x32_bf16 v[124:127], v[168:171], v[184:187], v[124:127]
	v_mfma_f32_16x16x32_bf16 v[120:123], v[176:179], v[184:187], v[120:123]
	v_mfma_f32_16x16x32_bf16 v[100:103], v[168:171], v[192:195], v[100:103]
	v_mfma_f32_16x16x32_bf16 v[96:99], v[176:179], v[192:195], v[96:99]
	v_mfma_f32_16x16x32_bf16 v[84:87], v[168:171], v[200:203], v[84:87]
	v_mfma_f32_16x16x32_bf16 v[80:83], v[176:179], v[200:203], v[80:83]
	v_mfma_f32_16x16x32_bf16 v[68:71], v[168:171], v[208:211], v[68:71]
	v_mfma_f32_16x16x32_bf16 v[64:67], v[176:179], v[208:211], v[64:67]
	s_setprio 0
	s_barrier
	s_add_u32 s42, s42, s44
	s_addc_u32 s43, s43, s45
	s_add_i32 s13, s13, s33
	s_mov_b32 m0, s13
	ds_read_b128 v[180:183], v145 offset:49152
	ds_read_b128 v[184:187], v145 offset:50176
	ds_read_b128 v[188:191], v145 offset:51200
	ds_read_b128 v[192:195], v145 offset:52224
	ds_read_b128 v[196:199], v145 offset:53248
	ds_read_b128 v[200:203], v145 offset:54272
	ds_read_b128 v[204:207], v145 offset:55296
	ds_read_b128 v[208:211], v145 offset:56320
	global_load_lds_dwordx4 v132, s[42:43]
	s_add_i32 m0, s13, 0x2000
	s_nop 0
	global_load_lds_dwordx4 v128, s[42:43]
	s_add_u32 s42, s42, 0x80000
	s_addc_u32 s43, s43, 0
	s_add_i32 s13, s65, s33
	s_mov_b32 m0, s13
	s_nop 0
	global_load_lds_dwordx4 v132, s[42:43]
	s_add_i32 m0, s13, 0x2000
	s_nop 0
	global_load_lds_dwordx4 v128, s[42:43]
	s_mov_b32 m0, s55
	s_nop 0
	global_load_lds_dwordx4 v134, s[48:49]
	s_mov_b32 m0, s56
	s_nop 0
	global_load_lds_dwordx4 v130, s[48:49]
	s_waitcnt vmcnt(8)
	s_waitcnt lgkmcnt(0)
	s_barrier
	s_setprio 1
	s_waitcnt lgkmcnt(0)
	v_mfma_f32_16x16x32_bf16 v[60:63], v[148:151], v[180:183], v[60:63]
	v_mfma_f32_16x16x32_bf16 v[56:59], v[156:159], v[180:183], v[56:59]
	v_mfma_f32_16x16x32_bf16 v[44:47], v[148:151], v[188:191], v[44:47]
	v_mfma_f32_16x16x32_bf16 v[40:43], v[156:159], v[188:191], v[40:43]
	v_mfma_f32_16x16x32_bf16 v[28:31], v[148:151], v[196:199], v[28:31]
	v_mfma_f32_16x16x32_bf16 v[24:27], v[156:159], v[196:199], v[24:27]
	v_mfma_f32_16x16x32_bf16 v[12:15], v[148:151], v[204:207], v[12:15]
	v_mfma_f32_16x16x32_bf16 v[8:11], v[156:159], v[204:207], v[8:11]
	v_mfma_f32_16x16x32_bf16 v[60:63], v[152:155], v[184:187], v[60:63]
	v_mfma_f32_16x16x32_bf16 v[56:59], v[160:163], v[184:187], v[56:59]
	v_mfma_f32_16x16x32_bf16 v[44:47], v[152:155], v[192:195], v[44:47]
	v_mfma_f32_16x16x32_bf16 v[40:43], v[160:163], v[192:195], v[40:43]
	v_mfma_f32_16x16x32_bf16 v[28:31], v[152:155], v[200:203], v[28:31]
	v_mfma_f32_16x16x32_bf16 v[24:27], v[160:163], v[200:203], v[24:27]
	v_mfma_f32_16x16x32_bf16 v[12:15], v[152:155], v[208:211], v[12:15]
	v_mfma_f32_16x16x32_bf16 v[8:11], v[160:163], v[208:211], v[8:11]
	s_setprio 0
	s_setprio 1
	v_mfma_f32_16x16x32_bf16 v[52:55], v[164:167], v[180:183], v[52:55]
	v_mfma_f32_16x16x32_bf16 v[48:51], v[172:175], v[180:183], v[48:51]
	v_mfma_f32_16x16x32_bf16 v[36:39], v[164:167], v[188:191], v[36:39]
	v_mfma_f32_16x16x32_bf16 v[32:35], v[172:175], v[188:191], v[32:35]
	v_mfma_f32_16x16x32_bf16 v[20:23], v[164:167], v[196:199], v[20:23]
	v_mfma_f32_16x16x32_bf16 v[16:19], v[172:175], v[196:199], v[16:19]
	v_mfma_f32_16x16x32_bf16 v[4:7], v[164:167], v[204:207], v[4:7]
	v_mfma_f32_16x16x32_bf16 v[0:3], v[172:175], v[204:207], v[0:3]
	v_mfma_f32_16x16x32_bf16 v[52:55], v[168:171], v[184:187], v[52:55]
	v_mfma_f32_16x16x32_bf16 v[48:51], v[176:179], v[184:187], v[48:51]
	v_mfma_f32_16x16x32_bf16 v[36:39], v[168:171], v[192:195], v[36:39]
	v_mfma_f32_16x16x32_bf16 v[32:35], v[176:179], v[192:195], v[32:35]
	v_mfma_f32_16x16x32_bf16 v[20:23], v[168:171], v[200:203], v[20:23]
	v_mfma_f32_16x16x32_bf16 v[16:19], v[176:179], v[200:203], v[16:19]
	v_mfma_f32_16x16x32_bf16 v[4:7], v[168:171], v[208:211], v[4:7]
	v_mfma_f32_16x16x32_bf16 v[0:3], v[176:179], v[208:211], v[0:3]
	s_setprio 0
	s_barrier
	s_cmp_gt_u32 s64, 29
	s_mov_b32 s64, s11
	s_cbranch_scc1 .LBB0_858
; #define PG8_STAGE(bufoff, gbase, voff) do { _Pragma("unroll") for (int _i = 0; _i < 2; ++_i) \
;         __builtin_amdgcn_global_load_lds((const unsigned*)((const char*)(gbase) + (voff)[_i]), (LAS unsigned*)(lds + (bufoff) + ldsw + _i * 8192), 16, 0, 0); } while (0)
; #define PG8_LDA(dst, b, h) do { _Pragma("unroll") for (int m = 0; m < 4; ++m) _Pragma("unroll") for (int k = 0; k < 2; ++k) dst[m][k] = *(const LAS bf16x8*)(lds + PG8_SA(b, h) + aoff + m * 2048 + k * 1024); } while (0)
; #define PG8_LDB(dst, b, h) do { _Pragma("unroll") for (int n = 0; n < 2; ++n) _Pragma("unroll") for (int k = 0; k < 2; ++k) dst[n][k] = *(const LAS bf16x8*)(lds + PG8_SB(b, h) + boff + n * 2048 + k * 1024); } while (0)
; #define PG8_SCHED __builtin_amdgcn_sched_barrier(0)
; template <class Epi>
; __device__ __forceinline__ void gemm_phase(LAS unsigned char* lds, const Gemm g, const StaticOrder S, const Epi E) {
;     ...
;             const bool last = (t == nt - 2);
;             const char* a1 = cA + (long)(t + 1) * ksc;
;             const char* a2 = last ? nA : cA + (long)(t + 2) * ksc; const char* b2 = last ? nB : cB + (long)(t + 2) * ksc;
;             const long ks3 = last ? ksn : ksc;
;             const char* a3 = a2 + ks3; const char* b3 = b2 + ks3;
;             PG8_LDB(B0, 0, 0); PG8_LDB(B1, 0, 1); PG8_SCHED; PG8_LDA(At, 0, 0); PG8_STAGE(PG8_SA(1, 1), a1 + hstepA, voffA);
.LBB0_854:
	ds_read_b128 v[148:151], v254
	ds_read_b128 v[152:155], v254 offset:1024
	ds_read_b128 v[156:159], v254 offset:2048
	ds_read_b128 v[160:163], v254 offset:3072
	ds_read_b128 v[164:167], v254 offset:16384
	ds_read_b128 v[168:171], v254 offset:17408
	ds_read_b128 v[172:175], v254 offset:18432
	ds_read_b128 v[176:179], v254 offset:19456
	ds_read_b128 v[180:183], v145
	ds_read_b128 v[184:187], v145 offset:1024
	ds_read_b128 v[188:191], v145 offset:2048
	ds_read_b128 v[192:195], v145 offset:3072
	ds_read_b128 v[196:199], v145 offset:4096
	ds_read_b128 v[200:203], v145 offset:5120
	ds_read_b128 v[204:207], v145 offset:6144
	ds_read_b128 v[208:211], v145 offset:7168
	s_cmp_lg_u32 s64, 30
	s_cselect_b64 s[42:43], -1, 0
	s_cmp_eq_u32 s64, 30
	s_mov_b64 s[46:47], s[30:31]
	s_cbranch_scc1 .LBB0_856
	s_add_i32 s11, s64, 2
	s_mul_i32 s13, s27, s11
	s_mul_hi_u32 s44, s26, s11
	s_add_i32 s44, s44, s13
	s_mul_i32 s11, s26, s11
	s_add_u32 s46, s24, s11
	s_addc_u32 s47, s25, s44

; #define PG8_STAGE(bufoff, gbase, voff) do { _Pragma("unroll") for (int _i = 0; _i < 2; ++_i) \
;         __builtin_amdgcn_global_load_lds((const unsigned*)((const char*)(gbase) + (voff)[_i]), (LAS unsigned*)(lds + (bufoff) + ldsw + _i * 8192), 16, 0, 0); } while (0)
; #define PG8_LDA(dst, b, h) do { _Pragma("unroll") for (int m = 0; m < 4; ++m) _Pragma("unroll") for (int k = 0; k < 2; ++k) dst[m][k] = *(const LAS bf16x8*)(lds + PG8_SA(b, h) + aoff + m * 2048 + k * 1024); } while (0)
; #define PG8_LDB(dst, b, h) do { _Pragma("unroll") for (int n = 0; n < 2; ++n) _Pragma("unroll") for (int k = 0; k < 2; ++k) dst[n][k] = *(const LAS bf16x8*)(lds + PG8_SB(b, h) + boff + n * 2048 + k * 1024); } while (0)
; #define PG8_MMA(ai, bj, At, Bt) do { __builtin_amdgcn_s_setprio(1); _Pragma("unroll") for (int m = 0; m < 4; ++m) _Pragma("unroll") for (int n = 0; n < 2; ++n) _Pragma("unroll") for (int k = 0; k < 2; ++k) \
;         acc[ai][bj][m][n] = __builtin_amdgcn_mfma_f32_16x16x32_bf16(Bt[n][k], At[m][k], acc[ai][bj][m][n], 0, 0, 0); __builtin_amdgcn_s_setprio(0); } while (0)
; #define PG8_WAIT_V(n) asm volatile("s_waitcnt vmcnt(" #n ")" ::: "memory")
; #define PG8_WAIT_L(n) asm volatile("s_waitcnt lgkmcnt(" #n ")" ::: "memory")
; #define PG8_BAR __builtin_amdgcn_s_barrier()
; #define PG8_SCHED __builtin_amdgcn_sched_barrier(0)
; template <class Epi>
; __device__ __forceinline__ void gemm_phase(LAS unsigned char* lds, const Gemm g, const StaticOrder S, const Epi E) {
;     ...
;             const char* a1 = cA + (long)(t + 1) * ksc;
;             const char* a2 = last ? nA : cA + (long)(t + 2) * ksc; const char* b2 = last ? nB : cB + (long)(t + 2) * ksc;
;             const long ks3 = last ? ksn : ksc;
;             const char* a3 = a2 + ks3; const char* b3 = b2 + ks3;
;             PG8_LDB(B0, 0, 0); PG8_LDB(B1, 0, 1); PG8_SCHED; PG8_LDA(At, 0, 0); PG8_STAGE(PG8_SA(1, 1), a1 + hstepA, voffA);
;             PG8_WAIT_V(8); PG8_WAIT_L(0); PG8_BAR; PG8_MMA(0, 0, At, B0); PG8_MMA(0, 1, At, B1); PG8_BAR; PG8_SCHED;
;             PG8_LDA(At, 0, 1); PG8_STAGE(PG8_SB(0, 0), b2, voffB); PG8_STAGE(PG8_SB(0, 1), b2 + hstepB, voffB); PG8_STAGE(PG8_SA(0, 0), a2, voffA);
;             PG8_WAIT_V(8); PG8_WAIT_L(0); PG8_BAR; PG8_MMA(1, 0, At, B0); PG8_MMA(1, 1, At, B1); PG8_BAR; PG8_SCHED;
.LBB0_938:
	s_or_b32 s48, s70, 1
	s_mul_i32 s49, s35, s48
	s_mul_hi_u32 s72, s34, s48
	s_add_i32 s72, s72, s49
	s_mul_i32 s48, s34, s48
	s_add_u32 s73, s30, s48
	s_addc_u32 s74, s31, s72
	s_add_u32 s48, s46, s44
	s_addc_u32 s49, s47, s45
	s_add_u32 s72, s73, 0x160000
	s_addc_u32 s73, s74, 0
	s_add_i32 m0, s50, 0xc000
	global_load_lds_dwordx4 v140, s[72:73]
	s_add_i32 m0, s50, 0xe000
	s_nop 0
	global_load_lds_dwordx4 v144, s[72:73]
	s_waitcnt vmcnt(8)
	s_waitcnt lgkmcnt(0)
	s_barrier
	s_setprio 1
	s_waitcnt lgkmcnt(0)
	v_mfma_f32_16x16x32_bf16 v[124:127], v[128:131], v[182:185], v[124:127]
	v_mfma_f32_16x16x32_bf16 v[120:123], v[136:139], v[182:185], v[120:123]
	v_mfma_f32_16x16x32_bf16 v[108:111], v[128:131], v[190:193], v[108:111]
	v_mfma_f32_16x16x32_bf16 v[104:107], v[136:139], v[190:193], v[104:107]
	v_mfma_f32_16x16x32_bf16 v[92:95], v[128:131], v[198:201], v[92:95]
	v_mfma_f32_16x16x32_bf16 v[88:91], v[136:139], v[198:201], v[88:91]
	v_mfma_f32_16x16x32_bf16 v[76:79], v[128:131], v[206:209], v[76:79]
	v_mfma_f32_16x16x32_bf16 v[72:75], v[136:139], v[206:209], v[72:75]
	v_mfma_f32_16x16x32_bf16 v[124:127], v[132:135], v[186:189], v[124:127]
	v_mfma_f32_16x16x32_bf16 v[120:123], v[152:155], v[186:189], v[120:123]
	v_mfma_f32_16x16x32_bf16 v[108:111], v[132:135], v[194:197], v[108:111]
	v_mfma_f32_16x16x32_bf16 v[104:107], v[152:155], v[194:197], v[104:107]
	v_mfma_f32_16x16x32_bf16 v[92:95], v[132:135], v[202:205], v[92:95]
	v_mfma_f32_16x16x32_bf16 v[88:91], v[152:155], v[202:205], v[88:91]
	v_mfma_f32_16x16x32_bf16 v[76:79], v[132:135], v[210:213], v[76:79]
	v_mfma_f32_16x16x32_bf16 v[72:75], v[152:155], v[210:213], v[72:75]
	s_setprio 0
	s_setprio 1
	v_mfma_f32_16x16x32_bf16 v[116:119], v[156:159], v[182:185], v[116:119]
	v_mfma_f32_16x16x32_bf16 v[112:115], v[174:177], v[182:185], v[112:115]
	v_mfma_f32_16x16x32_bf16 v[100:103], v[156:159], v[190:193], v[100:103]
	v_mfma_f32_16x16x32_bf16 v[96:99], v[174:177], v[190:193], v[96:99]
	v_mfma_f32_16x16x32_bf16 v[84:87], v[156:159], v[198:201], v[84:87]
	v_mfma_f32_16x16x32_bf16 v[80:83], v[174:177], v[198:201], v[80:83]
	v_mfma_f32_16x16x32_bf16 v[68:71], v[156:159], v[206:209], v[68:71]
	v_mfma_f32_16x16x32_bf16 v[64:67], v[174:177], v[206:209], v[64:67]
	v_mfma_f32_16x16x32_bf16 v[116:119], v[170:173], v[186:189], v[116:119]
	v_mfma_f32_16x16x32_bf16 v[112:115], v[178:181], v[186:189], v[112:115]
	v_mfma_f32_16x16x32_bf16 v[100:103], v[170:173], v[194:197], v[100:103]
	v_mfma_f32_16x16x32_bf16 v[96:99], v[178:181], v[194:197], v[96:99]
	v_mfma_f32_16x16x32_bf16 v[84:87], v[170:173], v[202:205], v[84:87]
	v_mfma_f32_16x16x32_bf16 v[80:83], v[178:181], v[202:205], v[80:83]
	v_mfma_f32_16x16x32_bf16 v[68:71], v[170:173], v[210:213], v[68:71]
	v_mfma_f32_16x16x32_bf16 v[64:67], v[178:181], v[210:213], v[64:67]
	s_setprio 0
	s_barrier
	s_add_i32 s72, s59, s33
	s_mov_b32 m0, s72
	ds_read_b128 v[182:185], v168 offset:16384
	ds_read_b128 v[186:189], v168 offset:17408
	ds_read_b128 v[190:193], v168 offset:18432
	ds_read_b128 v[194:197], v168 offset:19456
	ds_read_b128 v[198:201], v168 offset:20480
	ds_read_b128 v[202:205], v168 offset:21504
	ds_read_b128 v[206:209], v168 offset:22528
	ds_read_b128 v[210:213], v168 offset:23552
	global_load_lds_dwordx4 v142, s[42:43]
	s_add_i32 m0, s72, 0x2000
	s_add_u32 s72, s42, 0x160000
	s_addc_u32 s73, s43, 0
	s_add_i32 s74, s60, s33
	global_load_lds_dwordx4 v146, s[42:43]
	s_mov_b32 m0, s74
	s_nop 0
	global_load_lds_dwordx4 v142, s[72:73]
	s_add_i32 m0, s74, 0x2000
	s_nop 0
	global_load_lds_dwordx4 v146, s[72:73]
	s_mov_b32 m0, s50
	s_nop 0
	global_load_lds_dwordx4 v140, s[46:47]
	s_mov_b32 m0, s51
	s_nop 0
	global_load_lds_dwordx4 v144, s[46:47]
	s_waitcnt vmcnt(8)
	s_waitcnt lgkmcnt(0)
	s_barrier
	s_setprio 1
	s_waitcnt lgkmcnt(0)
	v_mfma_f32_16x16x32_bf16 v[60:63], v[128:131], v[182:185], v[60:63]
	v_mfma_f32_16x16x32_bf16 v[56:59], v[136:139], v[182:185], v[56:59]
	v_mfma_f32_16x16x32_bf16 v[44:47], v[128:131], v[190:193], v[44:47]
	v_mfma_f32_16x16x32_bf16 v[40:43], v[136:139], v[190:193], v[40:43]
	v_mfma_f32_16x16x32_bf16 v[28:31], v[128:131], v[198:201], v[28:31]
	v_mfma_f32_16x16x32_bf16 v[24:27], v[136:139], v[198:201], v[24:27]
	v_mfma_f32_16x16x32_bf16 v[12:15], v[128:131], v[206:209], v[12:15]
	v_mfma_f32_16x16x32_bf16 v[8:11], v[136:139], v[206:209], v[8:11]
	v_mfma_f32_16x16x32_bf16 v[60:63], v[132:135], v[186:189], v[60:63]
	v_mfma_f32_16x16x32_bf16 v[56:59], v[152:155], v[186:189], v[56:59]
	v_mfma_f32_16x16x32_bf16 v[44:47], v[132:135], v[194:197], v[44:47]
	v_mfma_f32_16x16x32_bf16 v[40:43], v[152:155], v[194:197], v[40:43]
	v_mfma_f32_16x16x32_bf16 v[28:31], v[132:135], v[202:205], v[28:31]
	v_mfma_f32_16x16x32_bf16 v[24:27], v[152:155], v[202:205], v[24:27]
	v_mfma_f32_16x16x32_bf16 v[12:15], v[132:135], v[210:213], v[12:15]
	v_mfma_f32_16x16x32_bf16 v[8:11], v[152:155], v[210:213], v[8:11]
	s_setprio 0
	s_setprio 1
	v_mfma_f32_16x16x32_bf16 v[52:55], v[156:159], v[182:185], v[52:55]
	v_mfma_f32_16x16x32_bf16 v[48:51], v[174:177], v[182:185], v[48:51]
	v_mfma_f32_16x16x32_bf16 v[36:39], v[156:159], v[190:193], v[36:39]
	v_mfma_f32_16x16x32_bf16 v[32:35], v[174:177], v[190:193], v[32:35]
	v_mfma_f32_16x16x32_bf16 v[20:23], v[156:159], v[198:201], v[20:23]
	v_mfma_f32_16x16x32_bf16 v[16:19], v[174:177], v[198:201], v[16:19]
	v_mfma_f32_16x16x32_bf16 v[4:7], v[156:159], v[206:209], v[4:7]
	v_mfma_f32_16x16x32_bf16 v[0:3], v[174:177], v[206:209], v[0:3]
	v_mfma_f32_16x16x32_bf16 v[52:55], v[170:173], v[186:189], v[52:55]
	v_mfma_f32_16x16x32_bf16 v[48:51], v[178:181], v[186:189], v[48:51]
	v_mfma_f32_16x16x32_bf16 v[36:39], v[170:173], v[194:197], v[36:39]
	v_mfma_f32_16x16x32_bf16 v[32:35], v[178:181], v[194:197], v[32:35]
	v_mfma_f32_16x16x32_bf16 v[20:23], v[170:173], v[202:205], v[20:23]
	v_mfma_f32_16x16x32_bf16 v[16:19], v[178:181], v[202:205], v[16:19]
	v_mfma_f32_16x16x32_bf16 v[4:7], v[170:173], v[210:213], v[4:7]
	v_mfma_f32_16x16x32_bf16 v[0:3], v[178:181], v[210:213], v[0:3]
	s_setprio 0
	s_barrier
; #define PG8_STAGE(bufoff, gbase, voff) do { _Pragma("unroll") for (int _i = 0; _i < 2; ++_i) \
;         __builtin_amdgcn_global_load_lds((const unsigned*)((const char*)(gbase) + (voff)[_i]), (LAS unsigned*)(lds + (bufoff) + ldsw + _i * 8192), 16, 0, 0); } while (0)
; #define PG8_LDA(dst, b, h) do { _Pragma("unroll") for (int m = 0; m < 4; ++m) _Pragma("unroll") for (int k = 0; k < 2; ++k) dst[m][k] = *(const LAS bf16x8*)(lds + PG8_SA(b, h) + aoff + m * 2048 + k * 1024); } while (0)
; #define PG8_LDB(dst, b, h) do { _Pragma("unroll") for (int n = 0; n < 2; ++n) _Pragma("unroll") for (int k = 0; k < 2; ++k) dst[n][k] = *(const LAS bf16x8*)(lds + PG8_SB(b, h) + boff + n * 2048 + k * 1024); } while (0)
; #define PG8_MMA(ai, bj, At, Bt) do { __builtin_amdgcn_s_setprio(1); _Pragma("unroll") for (int m = 0; m < 4; ++m) _Pragma("unroll") for (int n = 0; n < 2; ++n) _Pragma("unroll") for (int k = 0; k < 2; ++k) \
;         acc[ai][bj][m][n] = __builtin_amdgcn_mfma_f32_16x16x32_bf16(Bt[n][k], At[m][k], acc[ai][bj][m][n], 0, 0, 0); __builtin_amdgcn_s_setprio(0); } while (0)
; #define PG8_WAIT_V(n) asm volatile("s_waitcnt vmcnt(" #n ")" ::: "memory")
; #define PG8_WAIT_L(n) asm volatile("s_waitcnt lgkmcnt(" #n ")" ::: "memory")
; #define PG8_BAR __builtin_amdgcn_s_barrier()
; #define PG8_SCHED __builtin_amdgcn_sched_barrier(0)
; template <class Epi>
; __device__ __forceinline__ void gemm_phase(LAS unsigned char* lds, const Gemm g, const StaticOrder S, const Epi E) {
;     ...
;             PG8_LDB(B0, 1, 0); PG8_LDB(B1, 1, 1); PG8_SCHED; PG8_LDA(At, 1, 0); PG8_STAGE(PG8_SA(0, 1), a2 + hstepA, voffA);
;             PG8_WAIT_V(8); PG8_WAIT_L(0); PG8_BAR; PG8_MMA(0, 0, At, B0); PG8_MMA(0, 1, At, B1); PG8_BAR; PG8_SCHED;
;             PG8_LDA(At, 1, 1); PG8_STAGE(PG8_SB(1, 0), b3, voffB); PG8_STAGE(PG8_SB(1, 1), b3 + hstepB, voffB); PG8_STAGE(PG8_SA(1, 0), a3, voffA);
;             PG8_WAIT_V(8); PG8_WAIT_L(0); PG8_BAR; PG8_MMA(1, 0, At, B0); PG8_MMA(1, 1, At, B1); PG8_BAR; PG8_SCHED;
;         }
	s_add_i32 s72, 0, 0x18000
	s_add_i32 s73, 0, 0x1c000
	v_add_u32_e32 v152, s72, v166
	v_add_u32_e32 v178, s73, v166
	ds_read_b128 v[128:131], v152
	ds_read_b128 v[132:135], v152 offset:1024
	ds_read_b128 v[136:139], v152 offset:2048
	ds_read_b128 v[152:155], v152 offset:3072
	ds_read_b128 v[156:159], v178
	ds_read_b128 v[170:173], v178 offset:1024
	ds_read_b128 v[174:177], v178 offset:2048
	ds_read_b128 v[178:181], v178 offset:3072
	s_add_u32 s46, s46, 0x160000
	s_addc_u32 s47, s47, 0
	s_mov_b32 m0, s52
	ds_read_b128 v[182:185], v168 offset:32768
	ds_read_b128 v[186:189], v168 offset:33792
	ds_read_b128 v[190:193], v168 offset:34816
	ds_read_b128 v[194:197], v168 offset:35840
	ds_read_b128 v[198:201], v168 offset:36864
	ds_read_b128 v[202:205], v168 offset:37888
	ds_read_b128 v[206:209], v168 offset:38912
	ds_read_b128 v[210:213], v168 offset:39936
	global_load_lds_dwordx4 v140, s[46:47]
	s_mov_b32 m0, s53
	s_nop 0
	global_load_lds_dwordx4 v144, s[46:47]
	s_waitcnt vmcnt(8)
	s_waitcnt lgkmcnt(0)
	s_barrier
	s_setprio 1
	s_waitcnt lgkmcnt(0)
	v_mfma_f32_16x16x32_bf16 v[124:127], v[128:131], v[182:185], v[124:127]
	v_mfma_f32_16x16x32_bf16 v[120:123], v[136:139], v[182:185], v[120:123]
	v_mfma_f32_16x16x32_bf16 v[108:111], v[128:131], v[190:193], v[108:111]
	v_mfma_f32_16x16x32_bf16 v[104:107], v[136:139], v[190:193], v[104:107]
	v_mfma_f32_16x16x32_bf16 v[92:95], v[128:131], v[198:201], v[92:95]
	v_mfma_f32_16x16x32_bf16 v[88:91], v[136:139], v[198:201], v[88:91]
	v_mfma_f32_16x16x32_bf16 v[76:79], v[128:131], v[206:209], v[76:79]
	v_mfma_f32_16x16x32_bf16 v[72:75], v[136:139], v[206:209], v[72:75]
	v_mfma_f32_16x16x32_bf16 v[124:127], v[132:135], v[186:189], v[124:127]
	v_mfma_f32_16x16x32_bf16 v[120:123], v[152:155], v[186:189], v[120:123]
	v_mfma_f32_16x16x32_bf16 v[108:111], v[132:135], v[194:197], v[108:111]
	v_mfma_f32_16x16x32_bf16 v[104:107], v[152:155], v[194:197], v[104:107]
	v_mfma_f32_16x16x32_bf16 v[92:95], v[132:135], v[202:205], v[92:95]
	v_mfma_f32_16x16x32_bf16 v[88:91], v[152:155], v[202:205], v[88:91]
	v_mfma_f32_16x16x32_bf16 v[76:79], v[132:135], v[210:213], v[76:79]
	v_mfma_f32_16x16x32_bf16 v[72:75], v[152:155], v[210:213], v[72:75]
	s_setprio 0
	s_setprio 1
	v_mfma_f32_16x16x32_bf16 v[116:119], v[156:159], v[182:185], v[116:119]
	v_mfma_f32_16x16x32_bf16 v[112:115], v[174:177], v[182:185], v[112:115]
	v_mfma_f32_16x16x32_bf16 v[100:103], v[156:159], v[190:193], v[100:103]
	v_mfma_f32_16x16x32_bf16 v[96:99], v[174:177], v[190:193], v[96:99]
	v_mfma_f32_16x16x32_bf16 v[84:87], v[156:159], v[198:201], v[84:87]
	v_mfma_f32_16x16x32_bf16 v[80:83], v[174:177], v[198:201], v[80:83]
	v_mfma_f32_16x16x32_bf16 v[68:71], v[156:159], v[206:209], v[68:71]
	v_mfma_f32_16x16x32_bf16 v[64:67], v[174:177], v[206:209], v[64:67]
	v_mfma_f32_16x16x32_bf16 v[116:119], v[170:173], v[186:189], v[116:119]
	v_mfma_f32_16x16x32_bf16 v[112:115], v[178:181], v[186:189], v[112:115]
	v_mfma_f32_16x16x32_bf16 v[100:103], v[170:173], v[194:197], v[100:103]
	v_mfma_f32_16x16x32_bf16 v[96:99], v[178:181], v[194:197], v[96:99]
	v_mfma_f32_16x16x32_bf16 v[84:87], v[170:173], v[202:205], v[84:87]
	v_mfma_f32_16x16x32_bf16 v[80:83], v[178:181], v[202:205], v[80:83]
	v_mfma_f32_16x16x32_bf16 v[68:71], v[170:173], v[210:213], v[68:71]
	v_mfma_f32_16x16x32_bf16 v[64:67], v[178:181], v[210:213], v[64:67]
	s_setprio 0
	s_barrier
	s_add_u32 s42, s42, s44
	s_addc_u32 s43, s43, s45
	s_add_i32 s44, s72, s33
	s_mov_b32 m0, s44
	ds_read_b128 v[182:185], v168 offset:49152
	ds_read_b128 v[186:189], v168 offset:50176
	ds_read_b128 v[190:193], v168 offset:51200
	ds_read_b128 v[194:197], v168 offset:52224
	ds_read_b128 v[198:201], v168 offset:53248
	ds_read_b128 v[202:205], v168 offset:54272
	ds_read_b128 v[206:209], v168 offset:55296
	ds_read_b128 v[210:213], v168 offset:56320
	global_load_lds_dwordx4 v142, s[42:43]
	s_add_i32 m0, s44, 0x2000
	s_nop 0
	global_load_lds_dwordx4 v146, s[42:43]
	s_add_u32 s42, s42, 0x160000
	s_addc_u32 s43, s43, 0
	s_add_i32 s44, s73, s33
	s_mov_b32 m0, s44
	s_nop 0
	global_load_lds_dwordx4 v142, s[42:43]
	s_add_i32 m0, s44, 0x2000
	s_nop 0
	global_load_lds_dwordx4 v146, s[42:43]
	s_mov_b32 m0, s55
	s_nop 0
	global_load_lds_dwordx4 v140, s[48:49]
	s_mov_b32 m0, s56
	s_nop 0
	global_load_lds_dwordx4 v144, s[48:49]
	s_waitcnt vmcnt(8)
	s_waitcnt lgkmcnt(0)
	s_barrier
	s_setprio 1
	s_waitcnt lgkmcnt(0)
	v_mfma_f32_16x16x32_bf16 v[60:63], v[128:131], v[182:185], v[60:63]
	v_mfma_f32_16x16x32_bf16 v[56:59], v[136:139], v[182:185], v[56:59]
	v_mfma_f32_16x16x32_bf16 v[44:47], v[128:131], v[190:193], v[44:47]
	v_mfma_f32_16x16x32_bf16 v[40:43], v[136:139], v[190:193], v[40:43]
	v_mfma_f32_16x16x32_bf16 v[28:31], v[128:131], v[198:201], v[28:31]
	v_mfma_f32_16x16x32_bf16 v[24:27], v[136:139], v[198:201], v[24:27]
	v_mfma_f32_16x16x32_bf16 v[12:15], v[128:131], v[206:209], v[12:15]
	v_mfma_f32_16x16x32_bf16 v[8:11], v[136:139], v[206:209], v[8:11]
	v_mfma_f32_16x16x32_bf16 v[60:63], v[132:135], v[186:189], v[60:63]
	v_mfma_f32_16x16x32_bf16 v[56:59], v[152:155], v[186:189], v[56:59]
	v_mfma_f32_16x16x32_bf16 v[44:47], v[132:135], v[194:197], v[44:47]
	v_mfma_f32_16x16x32_bf16 v[40:43], v[152:155], v[194:197], v[40:43]
	v_mfma_f32_16x16x32_bf16 v[28:31], v[132:135], v[202:205], v[28:31]
	v_mfma_f32_16x16x32_bf16 v[24:27], v[152:155], v[202:205], v[24:27]
	v_mfma_f32_16x16x32_bf16 v[12:15], v[132:135], v[210:213], v[12:15]
	v_mfma_f32_16x16x32_bf16 v[8:11], v[152:155], v[210:213], v[8:11]
	s_setprio 0
	s_setprio 1
	v_mfma_f32_16x16x32_bf16 v[52:55], v[156:159], v[182:185], v[52:55]
	v_mfma_f32_16x16x32_bf16 v[48:51], v[174:177], v[182:185], v[48:51]
	v_mfma_f32_16x16x32_bf16 v[36:39], v[156:159], v[190:193], v[36:39]
	v_mfma_f32_16x16x32_bf16 v[32:35], v[174:177], v[190:193], v[32:35]
	v_mfma_f32_16x16x32_bf16 v[20:23], v[156:159], v[198:201], v[20:23]
	v_mfma_f32_16x16x32_bf16 v[16:19], v[174:177], v[198:201], v[16:19]
	v_mfma_f32_16x16x32_bf16 v[4:7], v[156:159], v[206:209], v[4:7]
	v_mfma_f32_16x16x32_bf16 v[0:3], v[174:177], v[206:209], v[0:3]
	v_mfma_f32_16x16x32_bf16 v[52:55], v[170:173], v[186:189], v[52:55]
	v_mfma_f32_16x16x32_bf16 v[48:51], v[178:181], v[186:189], v[48:51]
	v_mfma_f32_16x16x32_bf16 v[36:39], v[170:173], v[194:197], v[36:39]
	v_mfma_f32_16x16x32_bf16 v[32:35], v[178:181], v[194:197], v[32:35]
	v_mfma_f32_16x16x32_bf16 v[20:23], v[170:173], v[202:205], v[20:23]
	v_mfma_f32_16x16x32_bf16 v[16:19], v[178:181], v[202:205], v[16:19]
	v_mfma_f32_16x16x32_bf16 v[4:7], v[170:173], v[210:213], v[4:7]
	v_mfma_f32_16x16x32_bf16 v[0:3], v[178:181], v[210:213], v[0:3]
	s_setprio 0
	s_barrier
	s_cmpk_gt_u32 s70, 0x55
	s_mov_b32 s70, s71
	s_cbranch_scc1 .LBB0_943
; #define PG8_STAGE(bufoff, gbase, voff) do { _Pragma("unroll") for (int _i = 0; _i < 2; ++_i) \
;         __builtin_amdgcn_global_load_lds((const unsigned*)((const char*)(gbase) + (voff)[_i]), (LAS unsigned*)(lds + (bufoff) + ldsw + _i * 8192), 16, 0, 0); } while (0)
; #define PG8_LDA(dst, b, h) do { _Pragma("unroll") for (int m = 0; m < 4; ++m) _Pragma("unroll") for (int k = 0; k < 2; ++k) dst[m][k] = *(const LAS bf16x8*)(lds + PG8_SA(b, h) + aoff + m * 2048 + k * 1024); } while (0)
; #define PG8_LDB(dst, b, h) do { _Pragma("unroll") for (int n = 0; n < 2; ++n) _Pragma("unroll") for (int k = 0; k < 2; ++k) dst[n][k] = *(const LAS bf16x8*)(lds + PG8_SB(b, h) + boff + n * 2048 + k * 1024); } while (0)
; #define PG8_SCHED __builtin_amdgcn_sched_barrier(0)
; template <class Epi>
; __device__ __forceinline__ void gemm_phase(LAS unsigned char* lds, const Gemm g, const StaticOrder S, const Epi E) {
;     ...
;             const bool last = (t == nt - 2);
;             const char* a1 = cA + (long)(t + 1) * ksc;
;             const char* a2 = last ? nA : cA + (long)(t + 2) * ksc; const char* b2 = last ? nB : cB + (long)(t + 2) * ksc;
;             const long ks3 = last ? ksn : ksc;
;             const char* a3 = a2 + ks3; const char* b3 = b2 + ks3;
;             PG8_LDB(B0, 0, 0); PG8_LDB(B1, 0, 1); PG8_SCHED; PG8_LDA(At, 0, 0); PG8_STAGE(PG8_SA(1, 1), a1 + hstepA, voffA);
.LBB0_939:
	v_add_u32_e32 v152, s59, v166
	v_add_u32_e32 v178, s60, v166
	ds_read_b128 v[128:131], v152
	ds_read_b128 v[132:135], v152 offset:1024
	ds_read_b128 v[136:139], v152 offset:2048
	ds_read_b128 v[152:155], v152 offset:3072
	ds_read_b128 v[156:159], v178
	ds_read_b128 v[170:173], v178 offset:1024
	ds_read_b128 v[174:177], v178 offset:2048
	ds_read_b128 v[178:181], v178 offset:3072
	ds_read_b128 v[182:185], v168
	ds_read_b128 v[186:189], v168 offset:1024
	ds_read_b128 v[190:193], v168 offset:2048
	ds_read_b128 v[194:197], v168 offset:3072
	ds_read_b128 v[198:201], v168 offset:4096
	ds_read_b128 v[202:205], v168 offset:5120
	ds_read_b128 v[206:209], v168 offset:6144
	ds_read_b128 v[210:213], v168 offset:7168
	s_cmpk_lg_i32 s70, 0x56
	s_cselect_b64 s[42:43], -1, 0
	s_cmpk_eq_i32 s70, 0x56
	s_mov_b64 s[46:47], s[22:23]
	s_cbranch_scc1 .LBB0_941
	s_add_i32 s44, s70, 2
	s_mul_i32 s45, s35, s44
	s_mul_hi_u32 s46, s34, s44
	s_add_i32 s45, s46, s45
	s_mul_i32 s44, s34, s44
	s_add_u32 s46, s30, s44
	s_addc_u32 s47, s31, s45

; #define PG8_STAGE(bufoff, gbase, voff) do { _Pragma("unroll") for (int _i = 0; _i < 2; ++_i) \
;         __builtin_amdgcn_global_load_lds((const unsigned*)((const char*)(gbase) + (voff)[_i]), (LAS unsigned*)(lds + (bufoff) + ldsw + _i * 8192), 16, 0, 0); } while (0)
; #define PG8_LDA(dst, b, h) do { _Pragma("unroll") for (int m = 0; m < 4; ++m) _Pragma("unroll") for (int k = 0; k < 2; ++k) dst[m][k] = *(const LAS bf16x8*)(lds + PG8_SA(b, h) + aoff + m * 2048 + k * 1024); } while (0)
; #define PG8_LDB(dst, b, h) do { _Pragma("unroll") for (int n = 0; n < 2; ++n) _Pragma("unroll") for (int k = 0; k < 2; ++k) dst[n][k] = *(const LAS bf16x8*)(lds + PG8_SB(b, h) + boff + n * 2048 + k * 1024); } while (0)
; #define PG8_MMA(ai, bj, At, Bt) do { __builtin_amdgcn_s_setprio(1); _Pragma("unroll") for (int m = 0; m < 4; ++m) _Pragma("unroll") for (int n = 0; n < 2; ++n) _Pragma("unroll") for (int k = 0; k < 2; ++k) \
;         acc[ai][bj][m][n] = __builtin_amdgcn_mfma_f32_16x16x32_bf16(Bt[n][k], At[m][k], acc[ai][bj][m][n], 0, 0, 0); __builtin_amdgcn_s_setprio(0); } while (0)
; #define PG8_WAIT_V(n) asm volatile("s_waitcnt vmcnt(" #n ")" ::: "memory")
; #define PG8_WAIT_L(n) asm volatile("s_waitcnt lgkmcnt(" #n ")" ::: "memory")
; #define PG8_BAR __builtin_amdgcn_s_barrier()
; #define PG8_SCHED __builtin_amdgcn_sched_barrier(0)
; template <class Epi>
; __device__ __forceinline__ void gemm_phase(LAS unsigned char* lds, const Gemm g, const StaticOrder S, const Epi E) {
;     ...
;             const char* a1 = cA + (long)(t + 1) * ksc;
;             const char* a2 = last ? nA : cA + (long)(t + 2) * ksc; const char* b2 = last ? nB : cB + (long)(t + 2) * ksc;
;             const long ks3 = last ? ksn : ksc;
;             const char* a3 = a2 + ks3; const char* b3 = b2 + ks3;
;             PG8_LDB(B0, 0, 0); PG8_LDB(B1, 0, 1); PG8_SCHED; PG8_LDA(At, 0, 0); PG8_STAGE(PG8_SA(1, 1), a1 + hstepA, voffA);
;             PG8_WAIT_V(8); PG8_WAIT_L(0); PG8_BAR; PG8_MMA(0, 0, At, B0); PG8_MMA(0, 1, At, B1); PG8_BAR; PG8_SCHED;
;             PG8_LDA(At, 0, 1); PG8_STAGE(PG8_SB(0, 0), b2, voffB); PG8_STAGE(PG8_SB(0, 1), b2 + hstepB, voffB); PG8_STAGE(PG8_SA(0, 0), a2, voffA);
;             PG8_WAIT_V(8); PG8_WAIT_L(0); PG8_BAR; PG8_MMA(1, 0, At, B0); PG8_MMA(1, 1, At, B1); PG8_BAR; PG8_SCHED;
.LBB0_1032:
	s_or_b32 s17, s3, 1
	s_mul_i32 s48, s31, s17
	s_mul_hi_u32 s49, s30, s17
	s_add_i32 s49, s49, s48
	s_mul_i32 s17, s30, s17
	s_add_u32 s17, s28, s17
	s_addc_u32 s63, s29, s49
	s_add_u32 s48, s46, s44
	s_addc_u32 s49, s47, s45
	s_add_u32 s64, s17, 0x80000
	s_addc_u32 s65, s63, 0
	s_add_i32 m0, s25, 0xc000
	global_load_lds_dwordx4 v192, s[64:65]
	s_add_i32 m0, s25, 0xe000
	s_nop 0
	global_load_lds_dwordx4 v196, s[64:65]
	s_waitcnt vmcnt(8)
	s_waitcnt lgkmcnt(0)
	s_barrier
	s_setprio 1
	s_waitcnt lgkmcnt(0)
	v_mfma_f32_16x16x32_bf16 v[124:127], v[128:131], v[160:163], v[124:127]
	v_mfma_f32_16x16x32_bf16 v[120:123], v[136:139], v[160:163], v[120:123]
	v_mfma_f32_16x16x32_bf16 v[108:111], v[128:131], v[168:171], v[108:111]
	v_mfma_f32_16x16x32_bf16 v[104:107], v[136:139], v[168:171], v[104:107]
	v_mfma_f32_16x16x32_bf16 v[92:95], v[128:131], v[176:179], v[92:95]
	v_mfma_f32_16x16x32_bf16 v[88:91], v[136:139], v[176:179], v[88:91]
	v_mfma_f32_16x16x32_bf16 v[76:79], v[128:131], v[184:187], v[76:79]
	v_mfma_f32_16x16x32_bf16 v[72:75], v[136:139], v[184:187], v[72:75]
	v_mfma_f32_16x16x32_bf16 v[124:127], v[132:135], v[164:167], v[124:127]
	v_mfma_f32_16x16x32_bf16 v[120:123], v[140:143], v[164:167], v[120:123]
	v_mfma_f32_16x16x32_bf16 v[108:111], v[132:135], v[172:175], v[108:111]
	v_mfma_f32_16x16x32_bf16 v[104:107], v[140:143], v[172:175], v[104:107]
	v_mfma_f32_16x16x32_bf16 v[92:95], v[132:135], v[180:183], v[92:95]
	v_mfma_f32_16x16x32_bf16 v[88:91], v[140:143], v[180:183], v[88:91]
	v_mfma_f32_16x16x32_bf16 v[76:79], v[132:135], v[188:191], v[76:79]
	v_mfma_f32_16x16x32_bf16 v[72:75], v[140:143], v[188:191], v[72:75]
	s_setprio 0
	s_setprio 1
	v_mfma_f32_16x16x32_bf16 v[116:119], v[144:147], v[160:163], v[116:119]
	v_mfma_f32_16x16x32_bf16 v[112:115], v[152:155], v[160:163], v[112:115]
	v_mfma_f32_16x16x32_bf16 v[100:103], v[144:147], v[168:171], v[100:103]
	v_mfma_f32_16x16x32_bf16 v[96:99], v[152:155], v[168:171], v[96:99]
	v_mfma_f32_16x16x32_bf16 v[84:87], v[144:147], v[176:179], v[84:87]
	v_mfma_f32_16x16x32_bf16 v[80:83], v[152:155], v[176:179], v[80:83]
	v_mfma_f32_16x16x32_bf16 v[68:71], v[144:147], v[184:187], v[68:71]
	v_mfma_f32_16x16x32_bf16 v[64:67], v[152:155], v[184:187], v[64:67]
	v_mfma_f32_16x16x32_bf16 v[116:119], v[148:151], v[164:167], v[116:119]
	v_mfma_f32_16x16x32_bf16 v[112:115], v[156:159], v[164:167], v[112:115]
	v_mfma_f32_16x16x32_bf16 v[100:103], v[148:151], v[172:175], v[100:103]
	v_mfma_f32_16x16x32_bf16 v[96:99], v[156:159], v[172:175], v[96:99]
	v_mfma_f32_16x16x32_bf16 v[84:87], v[148:151], v[180:183], v[84:87]
	v_mfma_f32_16x16x32_bf16 v[80:83], v[156:159], v[180:183], v[80:83]
	v_mfma_f32_16x16x32_bf16 v[68:71], v[148:151], v[188:191], v[68:71]
	v_mfma_f32_16x16x32_bf16 v[64:67], v[156:159], v[188:191], v[64:67]
	s_setprio 0
	s_barrier
	s_add_i32 s17, s59, s33
	s_mov_b32 m0, s17
	ds_read_b128 v[160:163], v229 offset:16384
	ds_read_b128 v[164:167], v229 offset:17408
	ds_read_b128 v[168:171], v229 offset:18432
	ds_read_b128 v[172:175], v229 offset:19456
	ds_read_b128 v[176:179], v229 offset:20480
	ds_read_b128 v[180:183], v229 offset:21504
	ds_read_b128 v[184:187], v229 offset:22528
	ds_read_b128 v[188:191], v229 offset:23552
	global_load_lds_dwordx4 v194, s[42:43]
	s_add_i32 m0, s17, 0x2000
	s_add_u32 s64, s42, 0x80000
	s_addc_u32 s65, s43, 0
	s_add_i32 s17, s60, s33
	global_load_lds_dwordx4 v198, s[42:43]
	s_mov_b32 m0, s17
	s_nop 0
	global_load_lds_dwordx4 v194, s[64:65]
	s_add_i32 m0, s17, 0x2000
	s_nop 0
	global_load_lds_dwordx4 v198, s[64:65]
	s_mov_b32 m0, s25
	s_nop 0
	global_load_lds_dwordx4 v192, s[46:47]
	s_mov_b32 m0, s50
	s_nop 0
	global_load_lds_dwordx4 v196, s[46:47]
	s_waitcnt vmcnt(8)
	s_waitcnt lgkmcnt(0)
	s_barrier
	s_setprio 1
	s_waitcnt lgkmcnt(0)
	v_mfma_f32_16x16x32_bf16 v[60:63], v[128:131], v[160:163], v[60:63]
	v_mfma_f32_16x16x32_bf16 v[56:59], v[136:139], v[160:163], v[56:59]
	v_mfma_f32_16x16x32_bf16 v[44:47], v[128:131], v[168:171], v[44:47]
	v_mfma_f32_16x16x32_bf16 v[40:43], v[136:139], v[168:171], v[40:43]
	v_mfma_f32_16x16x32_bf16 v[28:31], v[128:131], v[176:179], v[28:31]
	v_mfma_f32_16x16x32_bf16 v[24:27], v[136:139], v[176:179], v[24:27]
	v_mfma_f32_16x16x32_bf16 v[12:15], v[128:131], v[184:187], v[12:15]
	v_mfma_f32_16x16x32_bf16 v[8:11], v[136:139], v[184:187], v[8:11]
	v_mfma_f32_16x16x32_bf16 v[60:63], v[132:135], v[164:167], v[60:63]
	v_mfma_f32_16x16x32_bf16 v[56:59], v[140:143], v[164:167], v[56:59]
	v_mfma_f32_16x16x32_bf16 v[44:47], v[132:135], v[172:175], v[44:47]
	v_mfma_f32_16x16x32_bf16 v[40:43], v[140:143], v[172:175], v[40:43]
	v_mfma_f32_16x16x32_bf16 v[28:31], v[132:135], v[180:183], v[28:31]
	v_mfma_f32_16x16x32_bf16 v[24:27], v[140:143], v[180:183], v[24:27]
	v_mfma_f32_16x16x32_bf16 v[12:15], v[132:135], v[188:191], v[12:15]
	v_mfma_f32_16x16x32_bf16 v[8:11], v[140:143], v[188:191], v[8:11]
	s_setprio 0
	s_setprio 1
	v_mfma_f32_16x16x32_bf16 v[52:55], v[144:147], v[160:163], v[52:55]
	v_mfma_f32_16x16x32_bf16 v[48:51], v[152:155], v[160:163], v[48:51]
	v_mfma_f32_16x16x32_bf16 v[36:39], v[144:147], v[168:171], v[36:39]
	v_mfma_f32_16x16x32_bf16 v[32:35], v[152:155], v[168:171], v[32:35]
	v_mfma_f32_16x16x32_bf16 v[20:23], v[144:147], v[176:179], v[20:23]
	v_mfma_f32_16x16x32_bf16 v[16:19], v[152:155], v[176:179], v[16:19]
	v_mfma_f32_16x16x32_bf16 v[4:7], v[144:147], v[184:187], v[4:7]
	v_mfma_f32_16x16x32_bf16 v[0:3], v[152:155], v[184:187], v[0:3]
	v_mfma_f32_16x16x32_bf16 v[52:55], v[148:151], v[164:167], v[52:55]
	v_mfma_f32_16x16x32_bf16 v[48:51], v[156:159], v[164:167], v[48:51]
	v_mfma_f32_16x16x32_bf16 v[36:39], v[148:151], v[172:175], v[36:39]
	v_mfma_f32_16x16x32_bf16 v[32:35], v[156:159], v[172:175], v[32:35]
	v_mfma_f32_16x16x32_bf16 v[20:23], v[148:151], v[180:183], v[20:23]
	v_mfma_f32_16x16x32_bf16 v[16:19], v[156:159], v[180:183], v[16:19]
	v_mfma_f32_16x16x32_bf16 v[4:7], v[148:151], v[188:191], v[4:7]
	v_mfma_f32_16x16x32_bf16 v[0:3], v[156:159], v[188:191], v[0:3]
	s_setprio 0
	s_barrier
; #define PG8_STAGE(bufoff, gbase, voff) do { _Pragma("unroll") for (int _i = 0; _i < 2; ++_i) \
;         __builtin_amdgcn_global_load_lds((const unsigned*)((const char*)(gbase) + (voff)[_i]), (LAS unsigned*)(lds + (bufoff) + ldsw + _i * 8192), 16, 0, 0); } while (0)
; #define PG8_LDA(dst, b, h) do { _Pragma("unroll") for (int m = 0; m < 4; ++m) _Pragma("unroll") for (int k = 0; k < 2; ++k) dst[m][k] = *(const LAS bf16x8*)(lds + PG8_SA(b, h) + aoff + m * 2048 + k * 1024); } while (0)
; #define PG8_LDB(dst, b, h) do { _Pragma("unroll") for (int n = 0; n < 2; ++n) _Pragma("unroll") for (int k = 0; k < 2; ++k) dst[n][k] = *(const LAS bf16x8*)(lds + PG8_SB(b, h) + boff + n * 2048 + k * 1024); } while (0)
; #define PG8_MMA(ai, bj, At, Bt) do { __builtin_amdgcn_s_setprio(1); _Pragma("unroll") for (int m = 0; m < 4; ++m) _Pragma("unroll") for (int n = 0; n < 2; ++n) _Pragma("unroll") for (int k = 0; k < 2; ++k) \
;         acc[ai][bj][m][n] = __builtin_amdgcn_mfma_f32_16x16x32_bf16(Bt[n][k], At[m][k], acc[ai][bj][m][n], 0, 0, 0); __builtin_amdgcn_s_setprio(0); } while (0)
; #define PG8_WAIT_V(n) asm volatile("s_waitcnt vmcnt(" #n ")" ::: "memory")
; #define PG8_WAIT_L(n) asm volatile("s_waitcnt lgkmcnt(" #n ")" ::: "memory")
; #define PG8_BAR __builtin_amdgcn_s_barrier()
; #define PG8_SCHED __builtin_amdgcn_sched_barrier(0)
; template <class Epi>
; __device__ __forceinline__ void gemm_phase(LAS unsigned char* lds, const Gemm g, const StaticOrder S, const Epi E) {
;     ...
;             PG8_LDB(B0, 1, 0); PG8_LDB(B1, 1, 1); PG8_SCHED; PG8_LDA(At, 1, 0); PG8_STAGE(PG8_SA(0, 1), a2 + hstepA, voffA);
;             PG8_WAIT_V(8); PG8_WAIT_L(0); PG8_BAR; PG8_MMA(0, 0, At, B0); PG8_MMA(0, 1, At, B1); PG8_BAR; PG8_SCHED;
;             PG8_LDA(At, 1, 1); PG8_STAGE(PG8_SB(1, 0), b3, voffB); PG8_STAGE(PG8_SB(1, 1), b3 + hstepB, voffB); PG8_STAGE(PG8_SA(1, 0), a3, voffA);
;             PG8_WAIT_V(8); PG8_WAIT_L(0); PG8_BAR; PG8_MMA(1, 0, At, B0); PG8_MMA(1, 1, At, B1); PG8_BAR; PG8_SCHED;
;         }
	s_add_i32 s17, 0, 0x18000
	s_add_i32 s63, 0, 0x1c000
	v_add_u32_e32 v140, s17, v227
	v_add_u32_e32 v156, s63, v227
	ds_read_b128 v[128:131], v140
	ds_read_b128 v[132:135], v140 offset:1024
	ds_read_b128 v[136:139], v140 offset:2048
	ds_read_b128 v[140:143], v140 offset:3072
	ds_read_b128 v[144:147], v156
	ds_read_b128 v[148:151], v156 offset:1024
	ds_read_b128 v[152:155], v156 offset:2048
	ds_read_b128 v[156:159], v156 offset:3072
	s_add_u32 s46, s46, 0x80000
	s_addc_u32 s47, s47, 0
	s_mov_b32 m0, s51
	ds_read_b128 v[160:163], v229 offset:32768
	ds_read_b128 v[164:167], v229 offset:33792
	ds_read_b128 v[168:171], v229 offset:34816
	ds_read_b128 v[172:175], v229 offset:35840
	ds_read_b128 v[176:179], v229 offset:36864
	ds_read_b128 v[180:183], v229 offset:37888
	ds_read_b128 v[184:187], v229 offset:38912
	ds_read_b128 v[188:191], v229 offset:39936
	global_load_lds_dwordx4 v192, s[46:47]
	s_mov_b32 m0, s52
	s_nop 0
	global_load_lds_dwordx4 v196, s[46:47]
	s_waitcnt vmcnt(8)
	s_waitcnt lgkmcnt(0)
	s_barrier
	s_setprio 1
	s_waitcnt lgkmcnt(0)
	v_mfma_f32_16x16x32_bf16 v[124:127], v[128:131], v[160:163], v[124:127]
	v_mfma_f32_16x16x32_bf16 v[120:123], v[136:139], v[160:163], v[120:123]
	v_mfma_f32_16x16x32_bf16 v[108:111], v[128:131], v[168:171], v[108:111]
	v_mfma_f32_16x16x32_bf16 v[104:107], v[136:139], v[168:171], v[104:107]
	v_mfma_f32_16x16x32_bf16 v[92:95], v[128:131], v[176:179], v[92:95]
	v_mfma_f32_16x16x32_bf16 v[88:91], v[136:139], v[176:179], v[88:91]
	v_mfma_f32_16x16x32_bf16 v[76:79], v[128:131], v[184:187], v[76:79]
	v_mfma_f32_16x16x32_bf16 v[72:75], v[136:139], v[184:187], v[72:75]
	v_mfma_f32_16x16x32_bf16 v[124:127], v[132:135], v[164:167], v[124:127]
	v_mfma_f32_16x16x32_bf16 v[120:123], v[140:143], v[164:167], v[120:123]
	v_mfma_f32_16x16x32_bf16 v[108:111], v[132:135], v[172:175], v[108:111]
	v_mfma_f32_16x16x32_bf16 v[104:107], v[140:143], v[172:175], v[104:107]
	v_mfma_f32_16x16x32_bf16 v[92:95], v[132:135], v[180:183], v[92:95]
	v_mfma_f32_16x16x32_bf16 v[88:91], v[140:143], v[180:183], v[88:91]
	v_mfma_f32_16x16x32_bf16 v[76:79], v[132:135], v[188:191], v[76:79]
	v_mfma_f32_16x16x32_bf16 v[72:75], v[140:143], v[188:191], v[72:75]
	s_setprio 0
	s_setprio 1
	v_mfma_f32_16x16x32_bf16 v[116:119], v[144:147], v[160:163], v[116:119]
	v_mfma_f32_16x16x32_bf16 v[112:115], v[152:155], v[160:163], v[112:115]
	v_mfma_f32_16x16x32_bf16 v[100:103], v[144:147], v[168:171], v[100:103]
	v_mfma_f32_16x16x32_bf16 v[96:99], v[152:155], v[168:171], v[96:99]
	v_mfma_f32_16x16x32_bf16 v[84:87], v[144:147], v[176:179], v[84:87]
	v_mfma_f32_16x16x32_bf16 v[80:83], v[152:155], v[176:179], v[80:83]
	v_mfma_f32_16x16x32_bf16 v[68:71], v[144:147], v[184:187], v[68:71]
	v_mfma_f32_16x16x32_bf16 v[64:67], v[152:155], v[184:187], v[64:67]
	v_mfma_f32_16x16x32_bf16 v[116:119], v[148:151], v[164:167], v[116:119]
	v_mfma_f32_16x16x32_bf16 v[112:115], v[156:159], v[164:167], v[112:115]
	v_mfma_f32_16x16x32_bf16 v[100:103], v[148:151], v[172:175], v[100:103]
	v_mfma_f32_16x16x32_bf16 v[96:99], v[156:159], v[172:175], v[96:99]
	v_mfma_f32_16x16x32_bf16 v[84:87], v[148:151], v[180:183], v[84:87]
	v_mfma_f32_16x16x32_bf16 v[80:83], v[156:159], v[180:183], v[80:83]
	v_mfma_f32_16x16x32_bf16 v[68:71], v[148:151], v[188:191], v[68:71]
	v_mfma_f32_16x16x32_bf16 v[64:67], v[156:159], v[188:191], v[64:67]
	s_setprio 0
	s_barrier
	s_add_u32 s42, s42, s44
	s_addc_u32 s43, s43, s45
	s_add_i32 s17, s17, s33
	s_mov_b32 m0, s17
	ds_read_b128 v[160:163], v229 offset:49152
	ds_read_b128 v[164:167], v229 offset:50176
	ds_read_b128 v[168:171], v229 offset:51200
	ds_read_b128 v[172:175], v229 offset:52224
	ds_read_b128 v[176:179], v229 offset:53248
	ds_read_b128 v[180:183], v229 offset:54272
	ds_read_b128 v[184:187], v229 offset:55296
	ds_read_b128 v[188:191], v229 offset:56320
	global_load_lds_dwordx4 v194, s[42:43]
	s_add_i32 m0, s17, 0x2000
	s_nop 0
	global_load_lds_dwordx4 v198, s[42:43]
	s_add_u32 s42, s42, 0x80000
	s_addc_u32 s43, s43, 0
	s_add_i32 s17, s63, s33
	s_mov_b32 m0, s17
	s_nop 0
	global_load_lds_dwordx4 v194, s[42:43]
	s_add_i32 m0, s17, 0x2000
	s_nop 0
	global_load_lds_dwordx4 v198, s[42:43]
	s_mov_b32 m0, s54
	s_nop 0
	global_load_lds_dwordx4 v192, s[48:49]
	s_mov_b32 m0, s55
	s_nop 0
	global_load_lds_dwordx4 v196, s[48:49]
	s_waitcnt vmcnt(8)
	s_waitcnt lgkmcnt(0)
	s_barrier
	s_setprio 1
	s_waitcnt lgkmcnt(0)
	v_mfma_f32_16x16x32_bf16 v[60:63], v[128:131], v[160:163], v[60:63]
	v_mfma_f32_16x16x32_bf16 v[56:59], v[136:139], v[160:163], v[56:59]
	v_mfma_f32_16x16x32_bf16 v[44:47], v[128:131], v[168:171], v[44:47]
	v_mfma_f32_16x16x32_bf16 v[40:43], v[136:139], v[168:171], v[40:43]
	v_mfma_f32_16x16x32_bf16 v[28:31], v[128:131], v[176:179], v[28:31]
	v_mfma_f32_16x16x32_bf16 v[24:27], v[136:139], v[176:179], v[24:27]
	v_mfma_f32_16x16x32_bf16 v[12:15], v[128:131], v[184:187], v[12:15]
	v_mfma_f32_16x16x32_bf16 v[8:11], v[136:139], v[184:187], v[8:11]
	v_mfma_f32_16x16x32_bf16 v[60:63], v[132:135], v[164:167], v[60:63]
	v_mfma_f32_16x16x32_bf16 v[56:59], v[140:143], v[164:167], v[56:59]
	v_mfma_f32_16x16x32_bf16 v[44:47], v[132:135], v[172:175], v[44:47]
	v_mfma_f32_16x16x32_bf16 v[40:43], v[140:143], v[172:175], v[40:43]
	v_mfma_f32_16x16x32_bf16 v[28:31], v[132:135], v[180:183], v[28:31]
	v_mfma_f32_16x16x32_bf16 v[24:27], v[140:143], v[180:183], v[24:27]
	v_mfma_f32_16x16x32_bf16 v[12:15], v[132:135], v[188:191], v[12:15]
	v_mfma_f32_16x16x32_bf16 v[8:11], v[140:143], v[188:191], v[8:11]
	s_setprio 0
	s_setprio 1
	v_mfma_f32_16x16x32_bf16 v[52:55], v[144:147], v[160:163], v[52:55]
	v_mfma_f32_16x16x32_bf16 v[48:51], v[152:155], v[160:163], v[48:51]
	v_mfma_f32_16x16x32_bf16 v[36:39], v[144:147], v[168:171], v[36:39]
	v_mfma_f32_16x16x32_bf16 v[32:35], v[152:155], v[168:171], v[32:35]
	v_mfma_f32_16x16x32_bf16 v[20:23], v[144:147], v[176:179], v[20:23]
	v_mfma_f32_16x16x32_bf16 v[16:19], v[152:155], v[176:179], v[16:19]
	v_mfma_f32_16x16x32_bf16 v[4:7], v[144:147], v[184:187], v[4:7]
	v_mfma_f32_16x16x32_bf16 v[0:3], v[152:155], v[184:187], v[0:3]
	v_mfma_f32_16x16x32_bf16 v[52:55], v[148:151], v[164:167], v[52:55]
	v_mfma_f32_16x16x32_bf16 v[48:51], v[156:159], v[164:167], v[48:51]
	v_mfma_f32_16x16x32_bf16 v[36:39], v[148:151], v[172:175], v[36:39]
	v_mfma_f32_16x16x32_bf16 v[32:35], v[156:159], v[172:175], v[32:35]
	v_mfma_f32_16x16x32_bf16 v[20:23], v[148:151], v[180:183], v[20:23]
	v_mfma_f32_16x16x32_bf16 v[16:19], v[156:159], v[180:183], v[16:19]
	v_mfma_f32_16x16x32_bf16 v[4:7], v[148:151], v[188:191], v[4:7]
	v_mfma_f32_16x16x32_bf16 v[0:3], v[156:159], v[188:191], v[0:3]
	s_setprio 0
	s_barrier
	s_cmp_gt_u32 s3, 29
	s_mov_b32 s3, s15
	s_cbranch_scc1 .LBB0_1037
; #define PG8_STAGE(bufoff, gbase, voff) do { _Pragma("unroll") for (int _i = 0; _i < 2; ++_i) \
;         __builtin_amdgcn_global_load_lds((const unsigned*)((const char*)(gbase) + (voff)[_i]), (LAS unsigned*)(lds + (bufoff) + ldsw + _i * 8192), 16, 0, 0); } while (0)
; #define PG8_LDA(dst, b, h) do { _Pragma("unroll") for (int m = 0; m < 4; ++m) _Pragma("unroll") for (int k = 0; k < 2; ++k) dst[m][k] = *(const LAS bf16x8*)(lds + PG8_SA(b, h) + aoff + m * 2048 + k * 1024); } while (0)
; #define PG8_LDB(dst, b, h) do { _Pragma("unroll") for (int n = 0; n < 2; ++n) _Pragma("unroll") for (int k = 0; k < 2; ++k) dst[n][k] = *(const LAS bf16x8*)(lds + PG8_SB(b, h) + boff + n * 2048 + k * 1024); } while (0)
; #define PG8_SCHED __builtin_amdgcn_sched_barrier(0)
; template <class Epi>
; __device__ __forceinline__ void gemm_phase(LAS unsigned char* lds, const Gemm g, const StaticOrder S, const Epi E) {
;     ...
;             const bool last = (t == nt - 2);
;             const char* a1 = cA + (long)(t + 1) * ksc;
;             const char* a2 = last ? nA : cA + (long)(t + 2) * ksc; const char* b2 = last ? nB : cB + (long)(t + 2) * ksc;
;             const long ks3 = last ? ksn : ksc;
;             const char* a3 = a2 + ks3; const char* b3 = b2 + ks3;
;             PG8_LDB(B0, 0, 0); PG8_LDB(B1, 0, 1); PG8_SCHED; PG8_LDA(At, 0, 0); PG8_STAGE(PG8_SA(1, 1), a1 + hstepA, voffA);
.LBB0_1033:
	v_add_u32_e32 v140, s59, v227
	v_add_u32_e32 v156, s60, v227
	ds_read_b128 v[128:131], v140
	ds_read_b128 v[132:135], v140 offset:1024
	ds_read_b128 v[136:139], v140 offset:2048
	ds_read_b128 v[140:143], v140 offset:3072
	ds_read_b128 v[144:147], v156
	ds_read_b128 v[148:151], v156 offset:1024
	ds_read_b128 v[152:155], v156 offset:2048
	ds_read_b128 v[156:159], v156 offset:3072
	ds_read_b128 v[160:163], v229
	ds_read_b128 v[164:167], v229 offset:1024
	ds_read_b128 v[168:171], v229 offset:2048
	ds_read_b128 v[172:175], v229 offset:3072
	ds_read_b128 v[176:179], v229 offset:4096
	ds_read_b128 v[180:183], v229 offset:5120
	ds_read_b128 v[184:187], v229 offset:6144
	ds_read_b128 v[188:191], v229 offset:7168
	s_cmp_lg_u32 s3, 30
	s_cselect_b64 s[42:43], -1, 0
	s_cmp_eq_u32 s3, 30
	s_mov_b64 s[46:47], s[36:37]
	s_cbranch_scc1 .LBB0_1035
	s_add_i32 s15, s3, 2
	s_mul_i32 s17, s31, s15
	s_mul_hi_u32 s44, s30, s15
	s_add_i32 s44, s44, s17
	s_mul_i32 s15, s30, s15
	s_add_u32 s46, s28, s15
	s_addc_u32 s47, s29, s44

; #define PG8_STAGE(bufoff, gbase, voff) do { _Pragma("unroll") for (int _i = 0; _i < 2; ++_i) \
;         __builtin_amdgcn_global_load_lds((const unsigned*)((const char*)(gbase) + (voff)[_i]), (LAS unsigned*)(lds + (bufoff) + ldsw + _i * 8192), 16, 0, 0); } while (0)
; #define PG8_LDA(dst, b, h) do { _Pragma("unroll") for (int m = 0; m < 4; ++m) _Pragma("unroll") for (int k = 0; k < 2; ++k) dst[m][k] = *(const LAS bf16x8*)(lds + PG8_SA(b, h) + aoff + m * 2048 + k * 1024); } while (0)
; #define PG8_LDB(dst, b, h) do { _Pragma("unroll") for (int n = 0; n < 2; ++n) _Pragma("unroll") for (int k = 0; k < 2; ++k) dst[n][k] = *(const LAS bf16x8*)(lds + PG8_SB(b, h) + boff + n * 2048 + k * 1024); } while (0)
; #define PG8_MMA(ai, bj, At, Bt) do { __builtin_amdgcn_s_setprio(1); _Pragma("unroll") for (int m = 0; m < 4; ++m) _Pragma("unroll") for (int n = 0; n < 2; ++n) _Pragma("unroll") for (int k = 0; k < 2; ++k) \
;         acc[ai][bj][m][n] = __builtin_amdgcn_mfma_f32_16x16x32_bf16(Bt[n][k], At[m][k], acc[ai][bj][m][n], 0, 0, 0); __builtin_amdgcn_s_setprio(0); } while (0)
; #define PG8_WAIT_V(n) asm volatile("s_waitcnt vmcnt(" #n ")" ::: "memory")
; #define PG8_WAIT_L(n) asm volatile("s_waitcnt lgkmcnt(" #n ")" ::: "memory")
; #define PG8_BAR __builtin_amdgcn_s_barrier()
; #define PG8_SCHED __builtin_amdgcn_sched_barrier(0)
; template <class Epi>
; __device__ __forceinline__ void gemm_phase(LAS unsigned char* lds, const Gemm g, const StaticOrder S, const Epi E) {
;     ...
;             const char* a1 = cA + (long)(t + 1) * ksc;
;             const char* a2 = last ? nA : cA + (long)(t + 2) * ksc; const char* b2 = last ? nB : cB + (long)(t + 2) * ksc;
;             const long ks3 = last ? ksn : ksc;
;             const char* a3 = a2 + ks3; const char* b3 = b2 + ks3;
;             PG8_LDB(B0, 0, 0); PG8_LDB(B1, 0, 1); PG8_SCHED; PG8_LDA(At, 0, 0); PG8_STAGE(PG8_SA(1, 1), a1 + hstepA, voffA);
;             PG8_WAIT_V(8); PG8_WAIT_L(0); PG8_BAR; PG8_MMA(0, 0, At, B0); PG8_MMA(0, 1, At, B1); PG8_BAR; PG8_SCHED;
;             PG8_LDA(At, 0, 1); PG8_STAGE(PG8_SB(0, 0), b2, voffB); PG8_STAGE(PG8_SB(0, 1), b2 + hstepB, voffB); PG8_STAGE(PG8_SA(0, 0), a2, voffA);
;             PG8_WAIT_V(8); PG8_WAIT_L(0); PG8_BAR; PG8_MMA(1, 0, At, B0); PG8_MMA(1, 1, At, B1); PG8_BAR; PG8_SCHED;
.LBB0_1373:
	s_or_b32 s23, s31, 1
	s_mul_i32 s54, s41, s23
	s_mul_hi_u32 s55, s40, s23
	s_add_i32 s55, s55, s54
	s_mul_i32 s23, s40, s23
	s_add_u32 s23, s38, s23
	s_addc_u32 s71, s39, s55
	s_add_u32 s54, s52, s50
	s_addc_u32 s55, s53, s51
	s_add_u32 s72, s23, 0x80000
	s_addc_u32 s73, s71, 0
	s_add_i32 m0, s35, 0xc000
	global_load_lds_dwordx4 v140, s[72:73]
	s_add_i32 m0, s35, 0xe000
	s_nop 0
	global_load_lds_dwordx4 v144, s[72:73]
	s_waitcnt vmcnt(8)
	s_waitcnt lgkmcnt(0)
	s_barrier
	s_setprio 1
	s_waitcnt lgkmcnt(0)
	v_mfma_f32_16x16x32_bf16 v[124:127], v[128:131], v[180:183], v[124:127]
	v_mfma_f32_16x16x32_bf16 v[120:123], v[136:139], v[180:183], v[120:123]
	v_mfma_f32_16x16x32_bf16 v[108:111], v[128:131], v[188:191], v[108:111]
	v_mfma_f32_16x16x32_bf16 v[104:107], v[136:139], v[188:191], v[104:107]
	v_mfma_f32_16x16x32_bf16 v[92:95], v[128:131], v[196:199], v[92:95]
	v_mfma_f32_16x16x32_bf16 v[88:91], v[136:139], v[196:199], v[88:91]
	v_mfma_f32_16x16x32_bf16 v[76:79], v[128:131], v[204:207], v[76:79]
	v_mfma_f32_16x16x32_bf16 v[72:75], v[136:139], v[204:207], v[72:75]
	v_mfma_f32_16x16x32_bf16 v[124:127], v[132:135], v[184:187], v[124:127]
	v_mfma_f32_16x16x32_bf16 v[120:123], v[152:155], v[184:187], v[120:123]
	v_mfma_f32_16x16x32_bf16 v[108:111], v[132:135], v[192:195], v[108:111]
	v_mfma_f32_16x16x32_bf16 v[104:107], v[152:155], v[192:195], v[104:107]
	v_mfma_f32_16x16x32_bf16 v[92:95], v[132:135], v[200:203], v[92:95]
	v_mfma_f32_16x16x32_bf16 v[88:91], v[152:155], v[200:203], v[88:91]
	v_mfma_f32_16x16x32_bf16 v[76:79], v[132:135], v[208:211], v[76:79]
	v_mfma_f32_16x16x32_bf16 v[72:75], v[152:155], v[208:211], v[72:75]
	s_setprio 0
	s_setprio 1
	v_mfma_f32_16x16x32_bf16 v[116:119], v[156:159], v[180:183], v[116:119]
	v_mfma_f32_16x16x32_bf16 v[112:115], v[172:175], v[180:183], v[112:115]
	v_mfma_f32_16x16x32_bf16 v[100:103], v[156:159], v[188:191], v[100:103]
	v_mfma_f32_16x16x32_bf16 v[96:99], v[172:175], v[188:191], v[96:99]
	v_mfma_f32_16x16x32_bf16 v[84:87], v[156:159], v[196:199], v[84:87]
	v_mfma_f32_16x16x32_bf16 v[80:83], v[172:175], v[196:199], v[80:83]
	v_mfma_f32_16x16x32_bf16 v[68:71], v[156:159], v[204:207], v[68:71]
	v_mfma_f32_16x16x32_bf16 v[64:67], v[172:175], v[204:207], v[64:67]
	v_mfma_f32_16x16x32_bf16 v[116:119], v[168:171], v[184:187], v[116:119]
	v_mfma_f32_16x16x32_bf16 v[112:115], v[176:179], v[184:187], v[112:115]
	v_mfma_f32_16x16x32_bf16 v[100:103], v[168:171], v[192:195], v[100:103]
	v_mfma_f32_16x16x32_bf16 v[96:99], v[176:179], v[192:195], v[96:99]
	v_mfma_f32_16x16x32_bf16 v[84:87], v[168:171], v[200:203], v[84:87]
	v_mfma_f32_16x16x32_bf16 v[80:83], v[176:179], v[200:203], v[80:83]
	v_mfma_f32_16x16x32_bf16 v[68:71], v[168:171], v[208:211], v[68:71]
	v_mfma_f32_16x16x32_bf16 v[64:67], v[176:179], v[208:211], v[64:67]
	s_setprio 0
	s_barrier
	s_add_i32 s23, s64, s33
	s_mov_b32 m0, s23
	ds_read_b128 v[180:183], v166 offset:16384
	ds_read_b128 v[184:187], v166 offset:17408
	ds_read_b128 v[188:191], v166 offset:18432
	ds_read_b128 v[192:195], v166 offset:19456
	ds_read_b128 v[196:199], v166 offset:20480
	ds_read_b128 v[200:203], v166 offset:21504
	ds_read_b128 v[204:207], v166 offset:22528
	ds_read_b128 v[208:211], v166 offset:23552
	global_load_lds_dwordx4 v142, s[48:49]
	s_add_i32 m0, s23, 0x2000
	s_add_u32 s72, s48, 0x80000
	s_addc_u32 s73, s49, 0
	s_add_i32 s23, s65, s33
	global_load_lds_dwordx4 v146, s[48:49]
	s_mov_b32 m0, s23
	s_nop 0
	global_load_lds_dwordx4 v142, s[72:73]
	s_add_i32 m0, s23, 0x2000
	s_nop 0
	global_load_lds_dwordx4 v146, s[72:73]
	s_mov_b32 m0, s35
	s_nop 0
	global_load_lds_dwordx4 v140, s[52:53]
	s_mov_b32 m0, s56
	s_nop 0
	global_load_lds_dwordx4 v144, s[52:53]
	s_waitcnt vmcnt(8)
	s_waitcnt lgkmcnt(0)
	s_barrier
	s_setprio 1
	s_waitcnt lgkmcnt(0)
	v_mfma_f32_16x16x32_bf16 v[60:63], v[128:131], v[180:183], v[60:63]
	v_mfma_f32_16x16x32_bf16 v[56:59], v[136:139], v[180:183], v[56:59]
	v_mfma_f32_16x16x32_bf16 v[44:47], v[128:131], v[188:191], v[44:47]
	v_mfma_f32_16x16x32_bf16 v[40:43], v[136:139], v[188:191], v[40:43]
	v_mfma_f32_16x16x32_bf16 v[28:31], v[128:131], v[196:199], v[28:31]
	v_mfma_f32_16x16x32_bf16 v[24:27], v[136:139], v[196:199], v[24:27]
	v_mfma_f32_16x16x32_bf16 v[12:15], v[128:131], v[204:207], v[12:15]
	v_mfma_f32_16x16x32_bf16 v[8:11], v[136:139], v[204:207], v[8:11]
	v_mfma_f32_16x16x32_bf16 v[60:63], v[132:135], v[184:187], v[60:63]
	v_mfma_f32_16x16x32_bf16 v[56:59], v[152:155], v[184:187], v[56:59]
	v_mfma_f32_16x16x32_bf16 v[44:47], v[132:135], v[192:195], v[44:47]
	v_mfma_f32_16x16x32_bf16 v[40:43], v[152:155], v[192:195], v[40:43]
	v_mfma_f32_16x16x32_bf16 v[28:31], v[132:135], v[200:203], v[28:31]
	v_mfma_f32_16x16x32_bf16 v[24:27], v[152:155], v[200:203], v[24:27]
	v_mfma_f32_16x16x32_bf16 v[12:15], v[132:135], v[208:211], v[12:15]
	v_mfma_f32_16x16x32_bf16 v[8:11], v[152:155], v[208:211], v[8:11]
	s_setprio 0
	s_setprio 1
	v_mfma_f32_16x16x32_bf16 v[52:55], v[156:159], v[180:183], v[52:55]
	v_mfma_f32_16x16x32_bf16 v[48:51], v[172:175], v[180:183], v[48:51]
	v_mfma_f32_16x16x32_bf16 v[36:39], v[156:159], v[188:191], v[36:39]
	v_mfma_f32_16x16x32_bf16 v[32:35], v[172:175], v[188:191], v[32:35]
	v_mfma_f32_16x16x32_bf16 v[20:23], v[156:159], v[196:199], v[20:23]
	v_mfma_f32_16x16x32_bf16 v[16:19], v[172:175], v[196:199], v[16:19]
	v_mfma_f32_16x16x32_bf16 v[4:7], v[156:159], v[204:207], v[4:7]
	v_mfma_f32_16x16x32_bf16 v[0:3], v[172:175], v[204:207], v[0:3]
	v_mfma_f32_16x16x32_bf16 v[52:55], v[168:171], v[184:187], v[52:55]
	v_mfma_f32_16x16x32_bf16 v[48:51], v[176:179], v[184:187], v[48:51]
	v_mfma_f32_16x16x32_bf16 v[36:39], v[168:171], v[192:195], v[36:39]
	v_mfma_f32_16x16x32_bf16 v[32:35], v[176:179], v[192:195], v[32:35]
	v_mfma_f32_16x16x32_bf16 v[20:23], v[168:171], v[200:203], v[20:23]
	v_mfma_f32_16x16x32_bf16 v[16:19], v[176:179], v[200:203], v[16:19]
	v_mfma_f32_16x16x32_bf16 v[4:7], v[168:171], v[208:211], v[4:7]
	v_mfma_f32_16x16x32_bf16 v[0:3], v[176:179], v[208:211], v[0:3]
	s_setprio 0
	s_barrier
; #define PG8_STAGE(bufoff, gbase, voff) do { _Pragma("unroll") for (int _i = 0; _i < 2; ++_i) \
;         __builtin_amdgcn_global_load_lds((const unsigned*)((const char*)(gbase) + (voff)[_i]), (LAS unsigned*)(lds + (bufoff) + ldsw + _i * 8192), 16, 0, 0); } while (0)
; #define PG8_LDA(dst, b, h) do { _Pragma("unroll") for (int m = 0; m < 4; ++m) _Pragma("unroll") for (int k = 0; k < 2; ++k) dst[m][k] = *(const LAS bf16x8*)(lds + PG8_SA(b, h) + aoff + m * 2048 + k * 1024); } while (0)
; #define PG8_LDB(dst, b, h) do { _Pragma("unroll") for (int n = 0; n < 2; ++n) _Pragma("unroll") for (int k = 0; k < 2; ++k) dst[n][k] = *(const LAS bf16x8*)(lds + PG8_SB(b, h) + boff + n * 2048 + k * 1024); } while (0)
; #define PG8_MMA(ai, bj, At, Bt) do { __builtin_amdgcn_s_setprio(1); _Pragma("unroll") for (int m = 0; m < 4; ++m) _Pragma("unroll") for (int n = 0; n < 2; ++n) _Pragma("unroll") for (int k = 0; k < 2; ++k) \
;         acc[ai][bj][m][n] = __builtin_amdgcn_mfma_f32_16x16x32_bf16(Bt[n][k], At[m][k], acc[ai][bj][m][n], 0, 0, 0); __builtin_amdgcn_s_setprio(0); } while (0)
; #define PG8_WAIT_V(n) asm volatile("s_waitcnt vmcnt(" #n ")" ::: "memory")
; #define PG8_WAIT_L(n) asm volatile("s_waitcnt lgkmcnt(" #n ")" ::: "memory")
; #define PG8_BAR __builtin_amdgcn_s_barrier()
; #define PG8_SCHED __builtin_amdgcn_sched_barrier(0)
; template <class Epi>
; __device__ __forceinline__ void gemm_phase(LAS unsigned char* lds, const Gemm g, const StaticOrder S, const Epi E) {
;     ...
;             PG8_LDB(B0, 1, 0); PG8_LDB(B1, 1, 1); PG8_SCHED; PG8_LDA(At, 1, 0); PG8_STAGE(PG8_SA(0, 1), a2 + hstepA, voffA);
;             PG8_WAIT_V(8); PG8_WAIT_L(0); PG8_BAR; PG8_MMA(0, 0, At, B0); PG8_MMA(0, 1, At, B1); PG8_BAR; PG8_SCHED;
;             PG8_LDA(At, 1, 1); PG8_STAGE(PG8_SB(1, 0), b3, voffB); PG8_STAGE(PG8_SB(1, 1), b3 + hstepB, voffB); PG8_STAGE(PG8_SA(1, 0), a3, voffA);
;             PG8_WAIT_V(8); PG8_WAIT_L(0); PG8_BAR; PG8_MMA(1, 0, At, B0); PG8_MMA(1, 1, At, B1); PG8_BAR; PG8_SCHED;
;         }
	s_add_i32 s23, 0, 0x18000
	s_add_i32 s71, 0, 0x1c000
	v_add_u32_e32 v152, s23, v164
	v_add_u32_e32 v176, s71, v164
	ds_read_b128 v[128:131], v152
	ds_read_b128 v[132:135], v152 offset:1024
	ds_read_b128 v[136:139], v152 offset:2048
	ds_read_b128 v[152:155], v152 offset:3072
	ds_read_b128 v[156:159], v176
	ds_read_b128 v[168:171], v176 offset:1024
	ds_read_b128 v[172:175], v176 offset:2048
	ds_read_b128 v[176:179], v176 offset:3072
	s_add_u32 s52, s52, 0x80000
	s_addc_u32 s53, s53, 0
	s_mov_b32 m0, s57
	ds_read_b128 v[180:183], v166 offset:32768
	ds_read_b128 v[184:187], v166 offset:33792
	ds_read_b128 v[188:191], v166 offset:34816
	ds_read_b128 v[192:195], v166 offset:35840
	ds_read_b128 v[196:199], v166 offset:36864
	ds_read_b128 v[200:203], v166 offset:37888
	ds_read_b128 v[204:207], v166 offset:38912
	ds_read_b128 v[208:211], v166 offset:39936
	global_load_lds_dwordx4 v140, s[52:53]
	s_mov_b32 m0, s58
	s_nop 0
	global_load_lds_dwordx4 v144, s[52:53]
	s_waitcnt vmcnt(8)
	s_waitcnt lgkmcnt(0)
	s_barrier
	s_setprio 1
	s_waitcnt lgkmcnt(0)
	v_mfma_f32_16x16x32_bf16 v[124:127], v[128:131], v[180:183], v[124:127]
	v_mfma_f32_16x16x32_bf16 v[120:123], v[136:139], v[180:183], v[120:123]
	v_mfma_f32_16x16x32_bf16 v[108:111], v[128:131], v[188:191], v[108:111]
	v_mfma_f32_16x16x32_bf16 v[104:107], v[136:139], v[188:191], v[104:107]
	v_mfma_f32_16x16x32_bf16 v[92:95], v[128:131], v[196:199], v[92:95]
	v_mfma_f32_16x16x32_bf16 v[88:91], v[136:139], v[196:199], v[88:91]
	v_mfma_f32_16x16x32_bf16 v[76:79], v[128:131], v[204:207], v[76:79]
	v_mfma_f32_16x16x32_bf16 v[72:75], v[136:139], v[204:207], v[72:75]
	v_mfma_f32_16x16x32_bf16 v[124:127], v[132:135], v[184:187], v[124:127]
	v_mfma_f32_16x16x32_bf16 v[120:123], v[152:155], v[184:187], v[120:123]
	v_mfma_f32_16x16x32_bf16 v[108:111], v[132:135], v[192:195], v[108:111]
	v_mfma_f32_16x16x32_bf16 v[104:107], v[152:155], v[192:195], v[104:107]
	v_mfma_f32_16x16x32_bf16 v[92:95], v[132:135], v[200:203], v[92:95]
	v_mfma_f32_16x16x32_bf16 v[88:91], v[152:155], v[200:203], v[88:91]
	v_mfma_f32_16x16x32_bf16 v[76:79], v[132:135], v[208:211], v[76:79]
	v_mfma_f32_16x16x32_bf16 v[72:75], v[152:155], v[208:211], v[72:75]
	s_setprio 0
	s_setprio 1
	v_mfma_f32_16x16x32_bf16 v[116:119], v[156:159], v[180:183], v[116:119]
	v_mfma_f32_16x16x32_bf16 v[112:115], v[172:175], v[180:183], v[112:115]
	v_mfma_f32_16x16x32_bf16 v[100:103], v[156:159], v[188:191], v[100:103]
	v_mfma_f32_16x16x32_bf16 v[96:99], v[172:175], v[188:191], v[96:99]
	v_mfma_f32_16x16x32_bf16 v[84:87], v[156:159], v[196:199], v[84:87]
	v_mfma_f32_16x16x32_bf16 v[80:83], v[172:175], v[196:199], v[80:83]
	v_mfma_f32_16x16x32_bf16 v[68:71], v[156:159], v[204:207], v[68:71]
	v_mfma_f32_16x16x32_bf16 v[64:67], v[172:175], v[204:207], v[64:67]
	v_mfma_f32_16x16x32_bf16 v[116:119], v[168:171], v[184:187], v[116:119]
	v_mfma_f32_16x16x32_bf16 v[112:115], v[176:179], v[184:187], v[112:115]
	v_mfma_f32_16x16x32_bf16 v[100:103], v[168:171], v[192:195], v[100:103]
	v_mfma_f32_16x16x32_bf16 v[96:99], v[176:179], v[192:195], v[96:99]
	v_mfma_f32_16x16x32_bf16 v[84:87], v[168:171], v[200:203], v[84:87]
	v_mfma_f32_16x16x32_bf16 v[80:83], v[176:179], v[200:203], v[80:83]
	v_mfma_f32_16x16x32_bf16 v[68:71], v[168:171], v[208:211], v[68:71]
	v_mfma_f32_16x16x32_bf16 v[64:67], v[176:179], v[208:211], v[64:67]
	s_setprio 0
	s_barrier
	s_add_u32 s48, s48, s50
	s_addc_u32 s49, s49, s51
	s_add_i32 s23, s23, s33
	s_mov_b32 m0, s23
	ds_read_b128 v[180:183], v166 offset:49152
	ds_read_b128 v[184:187], v166 offset:50176
	ds_read_b128 v[188:191], v166 offset:51200
	ds_read_b128 v[192:195], v166 offset:52224
	ds_read_b128 v[196:199], v166 offset:53248
	ds_read_b128 v[200:203], v166 offset:54272
	ds_read_b128 v[204:207], v166 offset:55296
	ds_read_b128 v[208:211], v166 offset:56320
	global_load_lds_dwordx4 v142, s[48:49]
	s_add_i32 m0, s23, 0x2000
	s_nop 0
	global_load_lds_dwordx4 v146, s[48:49]
	s_add_u32 s48, s48, 0x80000
	s_addc_u32 s49, s49, 0
	s_add_i32 s23, s71, s33
	s_mov_b32 m0, s23
	s_nop 0
	global_load_lds_dwordx4 v142, s[48:49]
	s_add_i32 m0, s23, 0x2000
	s_nop 0
	global_load_lds_dwordx4 v146, s[48:49]
	s_mov_b32 m0, s60
	s_nop 0
	global_load_lds_dwordx4 v140, s[54:55]
	s_mov_b32 m0, s61
	s_nop 0
	global_load_lds_dwordx4 v144, s[54:55]
	s_waitcnt vmcnt(8)
	s_waitcnt lgkmcnt(0)
	s_barrier
	s_setprio 1
	s_waitcnt lgkmcnt(0)
	v_mfma_f32_16x16x32_bf16 v[60:63], v[128:131], v[180:183], v[60:63]
	v_mfma_f32_16x16x32_bf16 v[56:59], v[136:139], v[180:183], v[56:59]
	v_mfma_f32_16x16x32_bf16 v[44:47], v[128:131], v[188:191], v[44:47]
	v_mfma_f32_16x16x32_bf16 v[40:43], v[136:139], v[188:191], v[40:43]
	v_mfma_f32_16x16x32_bf16 v[28:31], v[128:131], v[196:199], v[28:31]
	v_mfma_f32_16x16x32_bf16 v[24:27], v[136:139], v[196:199], v[24:27]
	v_mfma_f32_16x16x32_bf16 v[12:15], v[128:131], v[204:207], v[12:15]
	v_mfma_f32_16x16x32_bf16 v[8:11], v[136:139], v[204:207], v[8:11]
	v_mfma_f32_16x16x32_bf16 v[60:63], v[132:135], v[184:187], v[60:63]
	v_mfma_f32_16x16x32_bf16 v[56:59], v[152:155], v[184:187], v[56:59]
	v_mfma_f32_16x16x32_bf16 v[44:47], v[132:135], v[192:195], v[44:47]
	v_mfma_f32_16x16x32_bf16 v[40:43], v[152:155], v[192:195], v[40:43]
	v_mfma_f32_16x16x32_bf16 v[28:31], v[132:135], v[200:203], v[28:31]
	v_mfma_f32_16x16x32_bf16 v[24:27], v[152:155], v[200:203], v[24:27]
	v_mfma_f32_16x16x32_bf16 v[12:15], v[132:135], v[208:211], v[12:15]
	v_mfma_f32_16x16x32_bf16 v[8:11], v[152:155], v[208:211], v[8:11]
	s_setprio 0
	s_setprio 1
	v_mfma_f32_16x16x32_bf16 v[52:55], v[156:159], v[180:183], v[52:55]
	v_mfma_f32_16x16x32_bf16 v[48:51], v[172:175], v[180:183], v[48:51]
	v_mfma_f32_16x16x32_bf16 v[36:39], v[156:159], v[188:191], v[36:39]
	v_mfma_f32_16x16x32_bf16 v[32:35], v[172:175], v[188:191], v[32:35]
	v_mfma_f32_16x16x32_bf16 v[20:23], v[156:159], v[196:199], v[20:23]
	v_mfma_f32_16x16x32_bf16 v[16:19], v[172:175], v[196:199], v[16:19]
	v_mfma_f32_16x16x32_bf16 v[4:7], v[156:159], v[204:207], v[4:7]
	v_mfma_f32_16x16x32_bf16 v[0:3], v[172:175], v[204:207], v[0:3]
	v_mfma_f32_16x16x32_bf16 v[52:55], v[168:171], v[184:187], v[52:55]
	v_mfma_f32_16x16x32_bf16 v[48:51], v[176:179], v[184:187], v[48:51]
	v_mfma_f32_16x16x32_bf16 v[36:39], v[168:171], v[192:195], v[36:39]
	v_mfma_f32_16x16x32_bf16 v[32:35], v[176:179], v[192:195], v[32:35]
	v_mfma_f32_16x16x32_bf16 v[20:23], v[168:171], v[200:203], v[20:23]
	v_mfma_f32_16x16x32_bf16 v[16:19], v[176:179], v[200:203], v[16:19]
	v_mfma_f32_16x16x32_bf16 v[4:7], v[168:171], v[208:211], v[4:7]
	v_mfma_f32_16x16x32_bf16 v[0:3], v[176:179], v[208:211], v[0:3]
	s_setprio 0
	s_barrier
	s_cmp_gt_u32 s31, 29
	s_mov_b32 s31, s21
	s_cbranch_scc1 .LBB0_1378
; #define PG8_STAGE(bufoff, gbase, voff) do { _Pragma("unroll") for (int _i = 0; _i < 2; ++_i) \
;         __builtin_amdgcn_global_load_lds((const unsigned*)((const char*)(gbase) + (voff)[_i]), (LAS unsigned*)(lds + (bufoff) + ldsw + _i * 8192), 16, 0, 0); } while (0)
; #define PG8_LDA(dst, b, h) do { _Pragma("unroll") for (int m = 0; m < 4; ++m) _Pragma("unroll") for (int k = 0; k < 2; ++k) dst[m][k] = *(const LAS bf16x8*)(lds + PG8_SA(b, h) + aoff + m * 2048 + k * 1024); } while (0)
; #define PG8_LDB(dst, b, h) do { _Pragma("unroll") for (int n = 0; n < 2; ++n) _Pragma("unroll") for (int k = 0; k < 2; ++k) dst[n][k] = *(const LAS bf16x8*)(lds + PG8_SB(b, h) + boff + n * 2048 + k * 1024); } while (0)
; #define PG8_SCHED __builtin_amdgcn_sched_barrier(0)
; template <class Epi>
; __device__ __forceinline__ void gemm_phase(LAS unsigned char* lds, const Gemm g, const StaticOrder S, const Epi E) {
;     ...
;             const bool last = (t == nt - 2);
;             const char* a1 = cA + (long)(t + 1) * ksc;
;             const char* a2 = last ? nA : cA + (long)(t + 2) * ksc; const char* b2 = last ? nB : cB + (long)(t + 2) * ksc;
;             const long ks3 = last ? ksn : ksc;
;             const char* a3 = a2 + ks3; const char* b3 = b2 + ks3;
;             PG8_LDB(B0, 0, 0); PG8_LDB(B1, 0, 1); PG8_SCHED; PG8_LDA(At, 0, 0); PG8_STAGE(PG8_SA(1, 1), a1 + hstepA, voffA);
.LBB0_1374:
	v_add_u32_e32 v152, s64, v164
	v_add_u32_e32 v176, s65, v164
	ds_read_b128 v[128:131], v152
	ds_read_b128 v[132:135], v152 offset:1024
	ds_read_b128 v[136:139], v152 offset:2048
	ds_read_b128 v[152:155], v152 offset:3072
	ds_read_b128 v[156:159], v176
	ds_read_b128 v[168:171], v176 offset:1024
	ds_read_b128 v[172:175], v176 offset:2048
	ds_read_b128 v[176:179], v176 offset:3072
	ds_read_b128 v[180:183], v166
	ds_read_b128 v[184:187], v166 offset:1024
	ds_read_b128 v[188:191], v166 offset:2048
	ds_read_b128 v[192:195], v166 offset:3072
	ds_read_b128 v[196:199], v166 offset:4096
	ds_read_b128 v[200:203], v166 offset:5120
	ds_read_b128 v[204:207], v166 offset:6144
	ds_read_b128 v[208:211], v166 offset:7168
	s_cmp_lg_u32 s31, 30
	s_cselect_b64 s[48:49], -1, 0
	s_cmp_eq_u32 s31, 30
	s_mov_b64 s[52:53], s[44:45]
	s_cbranch_scc1 .LBB0_1376
	s_add_i32 s21, s31, 2
	s_mul_i32 s23, s41, s21
	s_mul_hi_u32 s50, s40, s21
	s_add_i32 s50, s50, s23
	s_mul_i32 s21, s40, s21
	s_add_u32 s52, s38, s21
	s_addc_u32 s53, s39, s50

; #define PG8_STAGE(bufoff, gbase, voff) do { _Pragma("unroll") for (int _i = 0; _i < 2; ++_i) \
;         __builtin_amdgcn_global_load_lds((const unsigned*)((const char*)(gbase) + (voff)[_i]), (LAS unsigned*)(lds + (bufoff) + ldsw + _i * 8192), 16, 0, 0); } while (0)
; #define PG8_LDA(dst, b, h) do { _Pragma("unroll") for (int m = 0; m < 4; ++m) _Pragma("unroll") for (int k = 0; k < 2; ++k) dst[m][k] = *(const LAS bf16x8*)(lds + PG8_SA(b, h) + aoff + m * 2048 + k * 1024); } while (0)
; #define PG8_LDB(dst, b, h) do { _Pragma("unroll") for (int n = 0; n < 2; ++n) _Pragma("unroll") for (int k = 0; k < 2; ++k) dst[n][k] = *(const LAS bf16x8*)(lds + PG8_SB(b, h) + boff + n * 2048 + k * 1024); } while (0)
; #define PG8_MMA(ai, bj, At, Bt) do { __builtin_amdgcn_s_setprio(1); _Pragma("unroll") for (int m = 0; m < 4; ++m) _Pragma("unroll") for (int n = 0; n < 2; ++n) _Pragma("unroll") for (int k = 0; k < 2; ++k) \
;         acc[ai][bj][m][n] = __builtin_amdgcn_mfma_f32_16x16x32_bf16(Bt[n][k], At[m][k], acc[ai][bj][m][n], 0, 0, 0); __builtin_amdgcn_s_setprio(0); } while (0)
; #define PG8_WAIT_V(n) asm volatile("s_waitcnt vmcnt(" #n ")" ::: "memory")
; #define PG8_WAIT_L(n) asm volatile("s_waitcnt lgkmcnt(" #n ")" ::: "memory")
; #define PG8_BAR __builtin_amdgcn_s_barrier()
; #define PG8_SCHED __builtin_amdgcn_sched_barrier(0)
; template <class Epi>
; __device__ __forceinline__ void gemm_phase(LAS unsigned char* lds, const Gemm g, const StaticOrder S, const Epi E) {
;     ...
;             const char* a1 = cA + (long)(t + 1) * ksc;
;             const char* a2 = last ? nA : cA + (long)(t + 2) * ksc; const char* b2 = last ? nB : cB + (long)(t + 2) * ksc;
;             const long ks3 = last ? ksn : ksc;
;             const char* a3 = a2 + ks3; const char* b3 = b2 + ks3;
;             PG8_LDB(B0, 0, 0); PG8_LDB(B1, 0, 1); PG8_SCHED; PG8_LDA(At, 0, 0); PG8_STAGE(PG8_SA(1, 1), a1 + hstepA, voffA);
;             PG8_WAIT_V(8); PG8_WAIT_L(0); PG8_BAR; PG8_MMA(0, 0, At, B0); PG8_MMA(0, 1, At, B1); PG8_BAR; PG8_SCHED;
;             PG8_LDA(At, 0, 1); PG8_STAGE(PG8_SB(0, 0), b2, voffB); PG8_STAGE(PG8_SB(0, 1), b2 + hstepB, voffB); PG8_STAGE(PG8_SA(0, 0), a2, voffA);
;             PG8_WAIT_V(8); PG8_WAIT_L(0); PG8_BAR; PG8_MMA(1, 0, At, B0); PG8_MMA(1, 1, At, B1); PG8_BAR; PG8_SCHED;
.LBB0_1473:
	s_or_b32 s13, s60, 1
	s_mul_i32 s42, s27, s13
	s_mul_hi_u32 s43, s26, s13
	s_add_i32 s43, s43, s42
	s_mul_i32 s13, s26, s13
	s_add_u32 s13, s24, s13
	s_addc_u32 s61, s25, s43
	s_add_u32 s42, s40, s38
	s_addc_u32 s43, s41, s39
	s_add_u32 s62, s13, 0x80000
	s_addc_u32 s63, s61, 0
	s_add_i32 m0, s21, 0xc000
	global_load_lds_dwordx4 v134, s[62:63]
	s_add_i32 m0, s21, 0xe000
	s_nop 0
	global_load_lds_dwordx4 v130, s[62:63]
	s_waitcnt vmcnt(8)
	s_waitcnt lgkmcnt(0)
	s_barrier
	s_setprio 1
	s_waitcnt lgkmcnt(0)
	v_mfma_f32_16x16x32_bf16 v[116:119], v[148:151], v[180:183], v[116:119]
	v_mfma_f32_16x16x32_bf16 v[112:115], v[156:159], v[180:183], v[112:115]
	v_mfma_f32_16x16x32_bf16 v[108:111], v[148:151], v[188:191], v[108:111]
	v_mfma_f32_16x16x32_bf16 v[104:107], v[156:159], v[188:191], v[104:107]
	v_mfma_f32_16x16x32_bf16 v[92:95], v[148:151], v[196:199], v[92:95]
	v_mfma_f32_16x16x32_bf16 v[88:91], v[156:159], v[196:199], v[88:91]
	v_mfma_f32_16x16x32_bf16 v[76:79], v[148:151], v[204:207], v[76:79]
	v_mfma_f32_16x16x32_bf16 v[72:75], v[156:159], v[204:207], v[72:75]
	v_mfma_f32_16x16x32_bf16 v[116:119], v[152:155], v[184:187], v[116:119]
	v_mfma_f32_16x16x32_bf16 v[112:115], v[160:163], v[184:187], v[112:115]
	v_mfma_f32_16x16x32_bf16 v[108:111], v[152:155], v[192:195], v[108:111]
	v_mfma_f32_16x16x32_bf16 v[104:107], v[160:163], v[192:195], v[104:107]
	v_mfma_f32_16x16x32_bf16 v[92:95], v[152:155], v[200:203], v[92:95]
	v_mfma_f32_16x16x32_bf16 v[88:91], v[160:163], v[200:203], v[88:91]
	v_mfma_f32_16x16x32_bf16 v[76:79], v[152:155], v[208:211], v[76:79]
	v_mfma_f32_16x16x32_bf16 v[72:75], v[160:163], v[208:211], v[72:75]
	s_setprio 0
	s_setprio 1
	v_mfma_f32_16x16x32_bf16 v[124:127], v[164:167], v[180:183], v[124:127]
	v_mfma_f32_16x16x32_bf16 v[120:123], v[172:175], v[180:183], v[120:123]
	v_mfma_f32_16x16x32_bf16 v[100:103], v[164:167], v[188:191], v[100:103]
	v_mfma_f32_16x16x32_bf16 v[96:99], v[172:175], v[188:191], v[96:99]
	v_mfma_f32_16x16x32_bf16 v[84:87], v[164:167], v[196:199], v[84:87]
	v_mfma_f32_16x16x32_bf16 v[80:83], v[172:175], v[196:199], v[80:83]
	v_mfma_f32_16x16x32_bf16 v[68:71], v[164:167], v[204:207], v[68:71]
	v_mfma_f32_16x16x32_bf16 v[64:67], v[172:175], v[204:207], v[64:67]
	v_mfma_f32_16x16x32_bf16 v[124:127], v[168:171], v[184:187], v[124:127]
	v_mfma_f32_16x16x32_bf16 v[120:123], v[176:179], v[184:187], v[120:123]
	v_mfma_f32_16x16x32_bf16 v[100:103], v[168:171], v[192:195], v[100:103]
	v_mfma_f32_16x16x32_bf16 v[96:99], v[176:179], v[192:195], v[96:99]
	v_mfma_f32_16x16x32_bf16 v[84:87], v[168:171], v[200:203], v[84:87]
	v_mfma_f32_16x16x32_bf16 v[80:83], v[176:179], v[200:203], v[80:83]
	v_mfma_f32_16x16x32_bf16 v[68:71], v[168:171], v[208:211], v[68:71]
	v_mfma_f32_16x16x32_bf16 v[64:67], v[176:179], v[208:211], v[64:67]
	s_setprio 0
	s_barrier
	s_add_i32 s13, s55, s45
	s_mov_b32 m0, s13
	ds_read_b128 v[180:183], v145 offset:16384
	ds_read_b128 v[184:187], v145 offset:17408
	ds_read_b128 v[188:191], v145 offset:18432
	ds_read_b128 v[192:195], v145 offset:19456
	ds_read_b128 v[196:199], v145 offset:20480
	ds_read_b128 v[200:203], v145 offset:21504
	ds_read_b128 v[204:207], v145 offset:22528
	ds_read_b128 v[208:211], v145 offset:23552
	global_load_lds_dwordx4 v132, s[36:37]
	s_add_i32 m0, s13, 0x2000
	s_add_u32 s62, s36, 0x80000
	s_addc_u32 s63, s37, 0
	s_add_i32 s13, s56, s45
	global_load_lds_dwordx4 v128, s[36:37]
	s_mov_b32 m0, s13
	s_nop 0
	global_load_lds_dwordx4 v132, s[62:63]
	s_add_i32 m0, s13, 0x2000
	s_nop 0
	global_load_lds_dwordx4 v128, s[62:63]
	s_mov_b32 m0, s21
	s_nop 0
	global_load_lds_dwordx4 v134, s[40:41]
	s_mov_b32 m0, s48
	s_nop 0
	global_load_lds_dwordx4 v130, s[40:41]
	s_waitcnt vmcnt(8)
	s_waitcnt lgkmcnt(0)
	s_barrier
	s_setprio 1
	s_waitcnt lgkmcnt(0)
	v_mfma_f32_16x16x32_bf16 v[60:63], v[148:151], v[180:183], v[60:63]
	v_mfma_f32_16x16x32_bf16 v[56:59], v[156:159], v[180:183], v[56:59]
	v_mfma_f32_16x16x32_bf16 v[44:47], v[148:151], v[188:191], v[44:47]
	v_mfma_f32_16x16x32_bf16 v[40:43], v[156:159], v[188:191], v[40:43]
	v_mfma_f32_16x16x32_bf16 v[28:31], v[148:151], v[196:199], v[28:31]
	v_mfma_f32_16x16x32_bf16 v[24:27], v[156:159], v[196:199], v[24:27]
	v_mfma_f32_16x16x32_bf16 v[12:15], v[148:151], v[204:207], v[12:15]
	v_mfma_f32_16x16x32_bf16 v[8:11], v[156:159], v[204:207], v[8:11]
	v_mfma_f32_16x16x32_bf16 v[60:63], v[152:155], v[184:187], v[60:63]
	v_mfma_f32_16x16x32_bf16 v[56:59], v[160:163], v[184:187], v[56:59]
	v_mfma_f32_16x16x32_bf16 v[44:47], v[152:155], v[192:195], v[44:47]
	v_mfma_f32_16x16x32_bf16 v[40:43], v[160:163], v[192:195], v[40:43]
	v_mfma_f32_16x16x32_bf16 v[28:31], v[152:155], v[200:203], v[28:31]
	v_mfma_f32_16x16x32_bf16 v[24:27], v[160:163], v[200:203], v[24:27]
	v_mfma_f32_16x16x32_bf16 v[12:15], v[152:155], v[208:211], v[12:15]
	v_mfma_f32_16x16x32_bf16 v[8:11], v[160:163], v[208:211], v[8:11]
	s_setprio 0
	s_setprio 1
	v_mfma_f32_16x16x32_bf16 v[52:55], v[164:167], v[180:183], v[52:55]
	v_mfma_f32_16x16x32_bf16 v[48:51], v[172:175], v[180:183], v[48:51]
	v_mfma_f32_16x16x32_bf16 v[36:39], v[164:167], v[188:191], v[36:39]
	v_mfma_f32_16x16x32_bf16 v[32:35], v[172:175], v[188:191], v[32:35]
	v_mfma_f32_16x16x32_bf16 v[20:23], v[164:167], v[196:199], v[20:23]
	v_mfma_f32_16x16x32_bf16 v[16:19], v[172:175], v[196:199], v[16:19]
	v_mfma_f32_16x16x32_bf16 v[4:7], v[164:167], v[204:207], v[4:7]
	v_mfma_f32_16x16x32_bf16 v[0:3], v[172:175], v[204:207], v[0:3]
	v_mfma_f32_16x16x32_bf16 v[52:55], v[168:171], v[184:187], v[52:55]
	v_mfma_f32_16x16x32_bf16 v[48:51], v[176:179], v[184:187], v[48:51]
	v_mfma_f32_16x16x32_bf16 v[36:39], v[168:171], v[192:195], v[36:39]
	v_mfma_f32_16x16x32_bf16 v[32:35], v[176:179], v[192:195], v[32:35]
	v_mfma_f32_16x16x32_bf16 v[20:23], v[168:171], v[200:203], v[20:23]
	v_mfma_f32_16x16x32_bf16 v[16:19], v[176:179], v[200:203], v[16:19]
	v_mfma_f32_16x16x32_bf16 v[4:7], v[168:171], v[208:211], v[4:7]
	v_mfma_f32_16x16x32_bf16 v[0:3], v[176:179], v[208:211], v[0:3]
	s_setprio 0
	s_barrier
; #define PG8_STAGE(bufoff, gbase, voff) do { _Pragma("unroll") for (int _i = 0; _i < 2; ++_i) \
;         __builtin_amdgcn_global_load_lds((const unsigned*)((const char*)(gbase) + (voff)[_i]), (LAS unsigned*)(lds + (bufoff) + ldsw + _i * 8192), 16, 0, 0); } while (0)
; #define PG8_LDA(dst, b, h) do { _Pragma("unroll") for (int m = 0; m < 4; ++m) _Pragma("unroll") for (int k = 0; k < 2; ++k) dst[m][k] = *(const LAS bf16x8*)(lds + PG8_SA(b, h) + aoff + m * 2048 + k * 1024); } while (0)
; #define PG8_LDB(dst, b, h) do { _Pragma("unroll") for (int n = 0; n < 2; ++n) _Pragma("unroll") for (int k = 0; k < 2; ++k) dst[n][k] = *(const LAS bf16x8*)(lds + PG8_SB(b, h) + boff + n * 2048 + k * 1024); } while (0)
; #define PG8_MMA(ai, bj, At, Bt) do { __builtin_amdgcn_s_setprio(1); _Pragma("unroll") for (int m = 0; m < 4; ++m) _Pragma("unroll") for (int n = 0; n < 2; ++n) _Pragma("unroll") for (int k = 0; k < 2; ++k) \
;         acc[ai][bj][m][n] = __builtin_amdgcn_mfma_f32_16x16x32_bf16(Bt[n][k], At[m][k], acc[ai][bj][m][n], 0, 0, 0); __builtin_amdgcn_s_setprio(0); } while (0)
; #define PG8_WAIT_V(n) asm volatile("s_waitcnt vmcnt(" #n ")" ::: "memory")
; #define PG8_WAIT_L(n) asm volatile("s_waitcnt lgkmcnt(" #n ")" ::: "memory")
; #define PG8_BAR __builtin_amdgcn_s_barrier()
; #define PG8_SCHED __builtin_amdgcn_sched_barrier(0)
; template <class Epi>
; __device__ __forceinline__ void gemm_phase(LAS unsigned char* lds, const Gemm g, const StaticOrder S, const Epi E) {
;     ...
;             PG8_LDB(B0, 1, 0); PG8_LDB(B1, 1, 1); PG8_SCHED; PG8_LDA(At, 1, 0); PG8_STAGE(PG8_SA(0, 1), a2 + hstepA, voffA);
;             PG8_WAIT_V(8); PG8_WAIT_L(0); PG8_BAR; PG8_MMA(0, 0, At, B0); PG8_MMA(0, 1, At, B1); PG8_BAR; PG8_SCHED;
;             PG8_LDA(At, 1, 1); PG8_STAGE(PG8_SB(1, 0), b3, voffB); PG8_STAGE(PG8_SB(1, 1), b3 + hstepB, voffB); PG8_STAGE(PG8_SA(1, 0), a3, voffA);
;             PG8_WAIT_V(8); PG8_WAIT_L(0); PG8_BAR; PG8_MMA(1, 0, At, B0); PG8_MMA(1, 1, At, B1); PG8_BAR; PG8_SCHED;
;         }
	s_add_i32 s13, 0, 0x18000
	s_add_i32 s61, 0, 0x1c000
	ds_read_b128 v[148:151], v254 offset:32768
	ds_read_b128 v[152:155], v254 offset:33792
	ds_read_b128 v[156:159], v254 offset:34816
	ds_read_b128 v[160:163], v254 offset:35840
	ds_read_b128 v[164:167], v254 offset:49152
	ds_read_b128 v[168:171], v254 offset:50176
	ds_read_b128 v[172:175], v254 offset:51200
	ds_read_b128 v[176:179], v254 offset:52224
	s_add_u32 s40, s40, 0x80000
	s_addc_u32 s41, s41, 0
	s_mov_b32 m0, s49
	ds_read_b128 v[180:183], v145 offset:32768
	ds_read_b128 v[184:187], v145 offset:33792
	ds_read_b128 v[188:191], v145 offset:34816
	ds_read_b128 v[192:195], v145 offset:35840
	ds_read_b128 v[196:199], v145 offset:36864
	ds_read_b128 v[200:203], v145 offset:37888
	ds_read_b128 v[204:207], v145 offset:38912
	ds_read_b128 v[208:211], v145 offset:39936
	global_load_lds_dwordx4 v134, s[40:41]
	s_mov_b32 m0, s50
	s_nop 0
	global_load_lds_dwordx4 v130, s[40:41]
	s_waitcnt vmcnt(8)
	s_waitcnt lgkmcnt(0)
	s_barrier
	s_setprio 1
	s_waitcnt lgkmcnt(0)
	v_mfma_f32_16x16x32_bf16 v[116:119], v[148:151], v[180:183], v[116:119]
	v_mfma_f32_16x16x32_bf16 v[112:115], v[156:159], v[180:183], v[112:115]
	v_mfma_f32_16x16x32_bf16 v[108:111], v[148:151], v[188:191], v[108:111]
	v_mfma_f32_16x16x32_bf16 v[104:107], v[156:159], v[188:191], v[104:107]
	v_mfma_f32_16x16x32_bf16 v[92:95], v[148:151], v[196:199], v[92:95]
	v_mfma_f32_16x16x32_bf16 v[88:91], v[156:159], v[196:199], v[88:91]
	v_mfma_f32_16x16x32_bf16 v[76:79], v[148:151], v[204:207], v[76:79]
	v_mfma_f32_16x16x32_bf16 v[72:75], v[156:159], v[204:207], v[72:75]
	v_mfma_f32_16x16x32_bf16 v[116:119], v[152:155], v[184:187], v[116:119]
	v_mfma_f32_16x16x32_bf16 v[112:115], v[160:163], v[184:187], v[112:115]
	v_mfma_f32_16x16x32_bf16 v[108:111], v[152:155], v[192:195], v[108:111]
	v_mfma_f32_16x16x32_bf16 v[104:107], v[160:163], v[192:195], v[104:107]
	v_mfma_f32_16x16x32_bf16 v[92:95], v[152:155], v[200:203], v[92:95]
	v_mfma_f32_16x16x32_bf16 v[88:91], v[160:163], v[200:203], v[88:91]
	v_mfma_f32_16x16x32_bf16 v[76:79], v[152:155], v[208:211], v[76:79]
	v_mfma_f32_16x16x32_bf16 v[72:75], v[160:163], v[208:211], v[72:75]
	s_setprio 0
	s_setprio 1
	v_mfma_f32_16x16x32_bf16 v[124:127], v[164:167], v[180:183], v[124:127]
	v_mfma_f32_16x16x32_bf16 v[120:123], v[172:175], v[180:183], v[120:123]
	v_mfma_f32_16x16x32_bf16 v[100:103], v[164:167], v[188:191], v[100:103]
	v_mfma_f32_16x16x32_bf16 v[96:99], v[172:175], v[188:191], v[96:99]
	v_mfma_f32_16x16x32_bf16 v[84:87], v[164:167], v[196:199], v[84:87]
	v_mfma_f32_16x16x32_bf16 v[80:83], v[172:175], v[196:199], v[80:83]
	v_mfma_f32_16x16x32_bf16 v[68:71], v[164:167], v[204:207], v[68:71]
	v_mfma_f32_16x16x32_bf16 v[64:67], v[172:175], v[204:207], v[64:67]
	v_mfma_f32_16x16x32_bf16 v[124:127], v[168:171], v[184:187], v[124:127]
	v_mfma_f32_16x16x32_bf16 v[120:123], v[176:179], v[184:187], v[120:123]
	v_mfma_f32_16x16x32_bf16 v[100:103], v[168:171], v[192:195], v[100:103]
	v_mfma_f32_16x16x32_bf16 v[96:99], v[176:179], v[192:195], v[96:99]
	v_mfma_f32_16x16x32_bf16 v[84:87], v[168:171], v[200:203], v[84:87]
	v_mfma_f32_16x16x32_bf16 v[80:83], v[176:179], v[200:203], v[80:83]
	v_mfma_f32_16x16x32_bf16 v[68:71], v[168:171], v[208:211], v[68:71]
	v_mfma_f32_16x16x32_bf16 v[64:67], v[176:179], v[208:211], v[64:67]
	s_setprio 0
	s_barrier
	s_add_u32 s36, s36, s38
	s_addc_u32 s37, s37, s39
	s_add_i32 s13, s13, s45
	s_mov_b32 m0, s13
	ds_read_b128 v[180:183], v145 offset:49152
	ds_read_b128 v[184:187], v145 offset:50176
	ds_read_b128 v[188:191], v145 offset:51200
	ds_read_b128 v[192:195], v145 offset:52224
	ds_read_b128 v[196:199], v145 offset:53248
	ds_read_b128 v[200:203], v145 offset:54272
	ds_read_b128 v[204:207], v145 offset:55296
	ds_read_b128 v[208:211], v145 offset:56320
	global_load_lds_dwordx4 v132, s[36:37]
	s_add_i32 m0, s13, 0x2000
	s_nop 0
	global_load_lds_dwordx4 v128, s[36:37]
	s_add_u32 s36, s36, 0x80000
	s_addc_u32 s37, s37, 0
	s_add_i32 s13, s61, s45
	s_mov_b32 m0, s13
	s_nop 0
	global_load_lds_dwordx4 v132, s[36:37]
	s_add_i32 m0, s13, 0x2000
	s_nop 0
	global_load_lds_dwordx4 v128, s[36:37]
	s_mov_b32 m0, s51
	s_nop 0
	global_load_lds_dwordx4 v134, s[42:43]
	s_mov_b32 m0, s52
	s_nop 0
	global_load_lds_dwordx4 v130, s[42:43]
	s_waitcnt vmcnt(8)
	s_waitcnt lgkmcnt(0)
	s_barrier
	s_setprio 1
	s_waitcnt lgkmcnt(0)
	v_mfma_f32_16x16x32_bf16 v[60:63], v[148:151], v[180:183], v[60:63]
	v_mfma_f32_16x16x32_bf16 v[56:59], v[156:159], v[180:183], v[56:59]
	v_mfma_f32_16x16x32_bf16 v[44:47], v[148:151], v[188:191], v[44:47]
	v_mfma_f32_16x16x32_bf16 v[40:43], v[156:159], v[188:191], v[40:43]
	v_mfma_f32_16x16x32_bf16 v[28:31], v[148:151], v[196:199], v[28:31]
	v_mfma_f32_16x16x32_bf16 v[24:27], v[156:159], v[196:199], v[24:27]
	v_mfma_f32_16x16x32_bf16 v[12:15], v[148:151], v[204:207], v[12:15]
	v_mfma_f32_16x16x32_bf16 v[8:11], v[156:159], v[204:207], v[8:11]
	v_mfma_f32_16x16x32_bf16 v[60:63], v[152:155], v[184:187], v[60:63]
	v_mfma_f32_16x16x32_bf16 v[56:59], v[160:163], v[184:187], v[56:59]
	v_mfma_f32_16x16x32_bf16 v[44:47], v[152:155], v[192:195], v[44:47]
	v_mfma_f32_16x16x32_bf16 v[40:43], v[160:163], v[192:195], v[40:43]
	v_mfma_f32_16x16x32_bf16 v[28:31], v[152:155], v[200:203], v[28:31]
	v_mfma_f32_16x16x32_bf16 v[24:27], v[160:163], v[200:203], v[24:27]
	v_mfma_f32_16x16x32_bf16 v[12:15], v[152:155], v[208:211], v[12:15]
	v_mfma_f32_16x16x32_bf16 v[8:11], v[160:163], v[208:211], v[8:11]
	s_setprio 0
	s_setprio 1
	v_mfma_f32_16x16x32_bf16 v[52:55], v[164:167], v[180:183], v[52:55]
	v_mfma_f32_16x16x32_bf16 v[48:51], v[172:175], v[180:183], v[48:51]
	v_mfma_f32_16x16x32_bf16 v[36:39], v[164:167], v[188:191], v[36:39]
	v_mfma_f32_16x16x32_bf16 v[32:35], v[172:175], v[188:191], v[32:35]
	v_mfma_f32_16x16x32_bf16 v[20:23], v[164:167], v[196:199], v[20:23]
	v_mfma_f32_16x16x32_bf16 v[16:19], v[172:175], v[196:199], v[16:19]
	v_mfma_f32_16x16x32_bf16 v[4:7], v[164:167], v[204:207], v[4:7]
	v_mfma_f32_16x16x32_bf16 v[0:3], v[172:175], v[204:207], v[0:3]
	v_mfma_f32_16x16x32_bf16 v[52:55], v[168:171], v[184:187], v[52:55]
	v_mfma_f32_16x16x32_bf16 v[48:51], v[176:179], v[184:187], v[48:51]
	v_mfma_f32_16x16x32_bf16 v[36:39], v[168:171], v[192:195], v[36:39]
	v_mfma_f32_16x16x32_bf16 v[32:35], v[176:179], v[192:195], v[32:35]
	v_mfma_f32_16x16x32_bf16 v[20:23], v[168:171], v[200:203], v[20:23]
	v_mfma_f32_16x16x32_bf16 v[16:19], v[176:179], v[200:203], v[16:19]
	v_mfma_f32_16x16x32_bf16 v[4:7], v[168:171], v[208:211], v[4:7]
	v_mfma_f32_16x16x32_bf16 v[0:3], v[176:179], v[208:211], v[0:3]
	s_setprio 0
	s_barrier
	s_cmp_gt_u32 s60, 29
	s_mov_b32 s60, s11
	s_cbranch_scc1 .LBB0_1478
; #define PG8_STAGE(bufoff, gbase, voff) do { _Pragma("unroll") for (int _i = 0; _i < 2; ++_i) \
;         __builtin_amdgcn_global_load_lds((const unsigned*)((const char*)(gbase) + (voff)[_i]), (LAS unsigned*)(lds + (bufoff) + ldsw + _i * 8192), 16, 0, 0); } while (0)
; #define PG8_LDA(dst, b, h) do { _Pragma("unroll") for (int m = 0; m < 4; ++m) _Pragma("unroll") for (int k = 0; k < 2; ++k) dst[m][k] = *(const LAS bf16x8*)(lds + PG8_SA(b, h) + aoff + m * 2048 + k * 1024); } while (0)
; #define PG8_LDB(dst, b, h) do { _Pragma("unroll") for (int n = 0; n < 2; ++n) _Pragma("unroll") for (int k = 0; k < 2; ++k) dst[n][k] = *(const LAS bf16x8*)(lds + PG8_SB(b, h) + boff + n * 2048 + k * 1024); } while (0)
; #define PG8_SCHED __builtin_amdgcn_sched_barrier(0)
; template <class Epi>
; __device__ __forceinline__ void gemm_phase(LAS unsigned char* lds, const Gemm g, const StaticOrder S, const Epi E) {
;     ...
;             const bool last = (t == nt - 2);
;             const char* a1 = cA + (long)(t + 1) * ksc;
;             const char* a2 = last ? nA : cA + (long)(t + 2) * ksc; const char* b2 = last ? nB : cB + (long)(t + 2) * ksc;
;             const long ks3 = last ? ksn : ksc;
;             const char* a3 = a2 + ks3; const char* b3 = b2 + ks3;
;             PG8_LDB(B0, 0, 0); PG8_LDB(B1, 0, 1); PG8_SCHED; PG8_LDA(At, 0, 0); PG8_STAGE(PG8_SA(1, 1), a1 + hstepA, voffA);
.LBB0_1474:
	ds_read_b128 v[148:151], v254
	ds_read_b128 v[152:155], v254 offset:1024
	ds_read_b128 v[156:159], v254 offset:2048
	ds_read_b128 v[160:163], v254 offset:3072
	ds_read_b128 v[164:167], v254 offset:16384
	ds_read_b128 v[168:171], v254 offset:17408
	ds_read_b128 v[172:175], v254 offset:18432
	ds_read_b128 v[176:179], v254 offset:19456
	ds_read_b128 v[180:183], v145
	ds_read_b128 v[184:187], v145 offset:1024
	ds_read_b128 v[188:191], v145 offset:2048
	ds_read_b128 v[192:195], v145 offset:3072
	ds_read_b128 v[196:199], v145 offset:4096
	ds_read_b128 v[200:203], v145 offset:5120
	ds_read_b128 v[204:207], v145 offset:6144
	ds_read_b128 v[208:211], v145 offset:7168
	s_cmp_lg_u32 s60, 30
	s_cselect_b64 s[36:37], -1, 0
	s_cmp_eq_u32 s60, 30
	s_mov_b64 s[40:41], s[30:31]
	s_cbranch_scc1 .LBB0_1476
	s_add_i32 s11, s60, 2
	s_mul_i32 s13, s27, s11
	s_mul_hi_u32 s38, s26, s11
	s_add_i32 s38, s38, s13
	s_mul_i32 s11, s26, s11
	s_add_u32 s40, s24, s11
	s_addc_u32 s41, s25, s38

; #define PG8_STAGE(bufoff, gbase, voff) do { _Pragma("unroll") for (int _i = 0; _i < 2; ++_i) \
;         __builtin_amdgcn_global_load_lds((const unsigned*)((const char*)(gbase) + (voff)[_i]), (LAS unsigned*)(lds + (bufoff) + ldsw + _i * 8192), 16, 0, 0); } while (0)
; #define PG8_LDA(dst, b, h) do { _Pragma("unroll") for (int m = 0; m < 4; ++m) _Pragma("unroll") for (int k = 0; k < 2; ++k) dst[m][k] = *(const LAS bf16x8*)(lds + PG8_SA(b, h) + aoff + m * 2048 + k * 1024); } while (0)
; #define PG8_LDB(dst, b, h) do { _Pragma("unroll") for (int n = 0; n < 2; ++n) _Pragma("unroll") for (int k = 0; k < 2; ++k) dst[n][k] = *(const LAS bf16x8*)(lds + PG8_SB(b, h) + boff + n * 2048 + k * 1024); } while (0)
; #define PG8_MMA(ai, bj, At, Bt) do { __builtin_amdgcn_s_setprio(1); _Pragma("unroll") for (int m = 0; m < 4; ++m) _Pragma("unroll") for (int n = 0; n < 2; ++n) _Pragma("unroll") for (int k = 0; k < 2; ++k) \
;         acc[ai][bj][m][n] = __builtin_amdgcn_mfma_f32_16x16x32_bf16(Bt[n][k], At[m][k], acc[ai][bj][m][n], 0, 0, 0); __builtin_amdgcn_s_setprio(0); } while (0)
; #define PG8_WAIT_V(n) asm volatile("s_waitcnt vmcnt(" #n ")" ::: "memory")
; #define PG8_WAIT_L(n) asm volatile("s_waitcnt lgkmcnt(" #n ")" ::: "memory")
; #define PG8_BAR __builtin_amdgcn_s_barrier()
; #define PG8_SCHED __builtin_amdgcn_sched_barrier(0)
; template <class Epi>
; __device__ __forceinline__ void gemm_phase(LAS unsigned char* lds, const Gemm g, const StaticOrder S, const Epi E) {
;     ...
;             const char* a1 = cA + (long)(t + 1) * ksc;
;             const char* a2 = last ? nA : cA + (long)(t + 2) * ksc; const char* b2 = last ? nB : cB + (long)(t + 2) * ksc;
;             const long ks3 = last ? ksn : ksc;
;             const char* a3 = a2 + ks3; const char* b3 = b2 + ks3;
;             PG8_LDB(B0, 0, 0); PG8_LDB(B1, 0, 1); PG8_SCHED; PG8_LDA(At, 0, 0); PG8_STAGE(PG8_SA(1, 1), a1 + hstepA, voffA);
;             PG8_WAIT_V(8); PG8_WAIT_L(0); PG8_BAR; PG8_MMA(0, 0, At, B0); PG8_MMA(0, 1, At, B1); PG8_BAR; PG8_SCHED;
;             PG8_LDA(At, 0, 1); PG8_STAGE(PG8_SB(0, 0), b2, voffB); PG8_STAGE(PG8_SB(0, 1), b2 + hstepB, voffB); PG8_STAGE(PG8_SA(0, 0), a2, voffA);
;             PG8_WAIT_V(8); PG8_WAIT_L(0); PG8_BAR; PG8_MMA(1, 0, At, B0); PG8_MMA(1, 1, At, B1); PG8_BAR; PG8_SCHED;
.LBB0_1558:
	s_or_b32 s42, s66, 1
	s_mul_i32 s43, s35, s42
	s_mul_hi_u32 s68, s34, s42
	s_add_i32 s68, s68, s43
	s_mul_i32 s42, s34, s42
	s_add_u32 s69, s30, s42
	s_addc_u32 s70, s31, s68
	s_add_u32 s42, s40, s38
	s_addc_u32 s43, s41, s39
	s_add_u32 s68, s69, 0x160000
	s_addc_u32 s69, s70, 0
	s_add_i32 m0, s46, 0xc000
	global_load_lds_dwordx4 v140, s[68:69]
	s_add_i32 m0, s46, 0xe000
	s_nop 0
	global_load_lds_dwordx4 v144, s[68:69]
	s_waitcnt vmcnt(8)
	s_waitcnt lgkmcnt(0)
	s_barrier
	s_setprio 1
	s_waitcnt lgkmcnt(0)
	v_mfma_f32_16x16x32_bf16 v[124:127], v[128:131], v[178:181], v[124:127]
	v_mfma_f32_16x16x32_bf16 v[120:123], v[136:139], v[178:181], v[120:123]
	v_mfma_f32_16x16x32_bf16 v[108:111], v[128:131], v[186:189], v[108:111]
	v_mfma_f32_16x16x32_bf16 v[104:107], v[136:139], v[186:189], v[104:107]
	v_mfma_f32_16x16x32_bf16 v[92:95], v[128:131], v[194:197], v[92:95]
	v_mfma_f32_16x16x32_bf16 v[88:91], v[136:139], v[194:197], v[88:91]
	v_mfma_f32_16x16x32_bf16 v[76:79], v[128:131], v[202:205], v[76:79]
	v_mfma_f32_16x16x32_bf16 v[72:75], v[136:139], v[202:205], v[72:75]
	v_mfma_f32_16x16x32_bf16 v[124:127], v[132:135], v[182:185], v[124:127]
	v_mfma_f32_16x16x32_bf16 v[120:123], v[152:155], v[182:185], v[120:123]
	v_mfma_f32_16x16x32_bf16 v[108:111], v[132:135], v[190:193], v[108:111]
	v_mfma_f32_16x16x32_bf16 v[104:107], v[152:155], v[190:193], v[104:107]
	v_mfma_f32_16x16x32_bf16 v[92:95], v[132:135], v[198:201], v[92:95]
	v_mfma_f32_16x16x32_bf16 v[88:91], v[152:155], v[198:201], v[88:91]
	v_mfma_f32_16x16x32_bf16 v[76:79], v[132:135], v[206:209], v[76:79]
	v_mfma_f32_16x16x32_bf16 v[72:75], v[152:155], v[206:209], v[72:75]
	s_setprio 0
	s_setprio 1
	v_mfma_f32_16x16x32_bf16 v[116:119], v[156:159], v[178:181], v[116:119]
	v_mfma_f32_16x16x32_bf16 v[112:115], v[170:173], v[178:181], v[112:115]
	v_mfma_f32_16x16x32_bf16 v[100:103], v[156:159], v[186:189], v[100:103]
	v_mfma_f32_16x16x32_bf16 v[96:99], v[170:173], v[186:189], v[96:99]
	v_mfma_f32_16x16x32_bf16 v[84:87], v[156:159], v[194:197], v[84:87]
	v_mfma_f32_16x16x32_bf16 v[80:83], v[170:173], v[194:197], v[80:83]
	v_mfma_f32_16x16x32_bf16 v[68:71], v[156:159], v[202:205], v[68:71]
	v_mfma_f32_16x16x32_bf16 v[64:67], v[170:173], v[202:205], v[64:67]
	v_mfma_f32_16x16x32_bf16 v[116:119], v[166:169], v[182:185], v[116:119]
	v_mfma_f32_16x16x32_bf16 v[112:115], v[174:177], v[182:185], v[112:115]
	v_mfma_f32_16x16x32_bf16 v[100:103], v[166:169], v[190:193], v[100:103]
	v_mfma_f32_16x16x32_bf16 v[96:99], v[174:177], v[190:193], v[96:99]
	v_mfma_f32_16x16x32_bf16 v[84:87], v[166:169], v[198:201], v[84:87]
	v_mfma_f32_16x16x32_bf16 v[80:83], v[174:177], v[198:201], v[80:83]
	v_mfma_f32_16x16x32_bf16 v[68:71], v[166:169], v[206:209], v[68:71]
	v_mfma_f32_16x16x32_bf16 v[64:67], v[174:177], v[206:209], v[64:67]
	s_setprio 0
	s_barrier
	s_add_i32 s68, s55, s45
	s_mov_b32 m0, s68
	ds_read_b128 v[178:181], v163 offset:16384
	ds_read_b128 v[182:185], v163 offset:17408
	ds_read_b128 v[186:189], v163 offset:18432
	ds_read_b128 v[190:193], v163 offset:19456
	ds_read_b128 v[194:197], v163 offset:20480
	ds_read_b128 v[198:201], v163 offset:21504
	ds_read_b128 v[202:205], v163 offset:22528
	ds_read_b128 v[206:209], v163 offset:23552
	global_load_lds_dwordx4 v142, s[36:37]
	s_add_i32 m0, s68, 0x2000
	s_add_u32 s68, s36, 0x160000
	s_addc_u32 s69, s37, 0
	s_add_i32 s70, s56, s45
	global_load_lds_dwordx4 v146, s[36:37]
	s_mov_b32 m0, s70
	s_nop 0
	global_load_lds_dwordx4 v142, s[68:69]
	s_add_i32 m0, s70, 0x2000
	s_nop 0
	global_load_lds_dwordx4 v146, s[68:69]
	s_mov_b32 m0, s46
	s_nop 0
	global_load_lds_dwordx4 v140, s[40:41]
	s_mov_b32 m0, s47
	s_nop 0
	global_load_lds_dwordx4 v144, s[40:41]
	s_waitcnt vmcnt(8)
	s_waitcnt lgkmcnt(0)
	s_barrier
	s_setprio 1
	s_waitcnt lgkmcnt(0)
	v_mfma_f32_16x16x32_bf16 v[60:63], v[128:131], v[178:181], v[60:63]
	v_mfma_f32_16x16x32_bf16 v[56:59], v[136:139], v[178:181], v[56:59]
	v_mfma_f32_16x16x32_bf16 v[44:47], v[128:131], v[186:189], v[44:47]
	v_mfma_f32_16x16x32_bf16 v[40:43], v[136:139], v[186:189], v[40:43]
	v_mfma_f32_16x16x32_bf16 v[28:31], v[128:131], v[194:197], v[28:31]
	v_mfma_f32_16x16x32_bf16 v[24:27], v[136:139], v[194:197], v[24:27]
	v_mfma_f32_16x16x32_bf16 v[12:15], v[128:131], v[202:205], v[12:15]
	v_mfma_f32_16x16x32_bf16 v[8:11], v[136:139], v[202:205], v[8:11]
	v_mfma_f32_16x16x32_bf16 v[60:63], v[132:135], v[182:185], v[60:63]
	v_mfma_f32_16x16x32_bf16 v[56:59], v[152:155], v[182:185], v[56:59]
	v_mfma_f32_16x16x32_bf16 v[44:47], v[132:135], v[190:193], v[44:47]
	v_mfma_f32_16x16x32_bf16 v[40:43], v[152:155], v[190:193], v[40:43]
	v_mfma_f32_16x16x32_bf16 v[28:31], v[132:135], v[198:201], v[28:31]
	v_mfma_f32_16x16x32_bf16 v[24:27], v[152:155], v[198:201], v[24:27]
	v_mfma_f32_16x16x32_bf16 v[12:15], v[132:135], v[206:209], v[12:15]
	v_mfma_f32_16x16x32_bf16 v[8:11], v[152:155], v[206:209], v[8:11]
	s_setprio 0
	s_setprio 1
	v_mfma_f32_16x16x32_bf16 v[52:55], v[156:159], v[178:181], v[52:55]
	v_mfma_f32_16x16x32_bf16 v[48:51], v[170:173], v[178:181], v[48:51]
	v_mfma_f32_16x16x32_bf16 v[36:39], v[156:159], v[186:189], v[36:39]
	v_mfma_f32_16x16x32_bf16 v[32:35], v[170:173], v[186:189], v[32:35]
	v_mfma_f32_16x16x32_bf16 v[20:23], v[156:159], v[194:197], v[20:23]
	v_mfma_f32_16x16x32_bf16 v[16:19], v[170:173], v[194:197], v[16:19]
	v_mfma_f32_16x16x32_bf16 v[4:7], v[156:159], v[202:205], v[4:7]
	v_mfma_f32_16x16x32_bf16 v[0:3], v[170:173], v[202:205], v[0:3]
	v_mfma_f32_16x16x32_bf16 v[52:55], v[166:169], v[182:185], v[52:55]
	v_mfma_f32_16x16x32_bf16 v[48:51], v[174:177], v[182:185], v[48:51]
	v_mfma_f32_16x16x32_bf16 v[36:39], v[166:169], v[190:193], v[36:39]
	v_mfma_f32_16x16x32_bf16 v[32:35], v[174:177], v[190:193], v[32:35]
	v_mfma_f32_16x16x32_bf16 v[20:23], v[166:169], v[198:201], v[20:23]
	v_mfma_f32_16x16x32_bf16 v[16:19], v[174:177], v[198:201], v[16:19]
	v_mfma_f32_16x16x32_bf16 v[4:7], v[166:169], v[206:209], v[4:7]
	v_mfma_f32_16x16x32_bf16 v[0:3], v[174:177], v[206:209], v[0:3]
	s_setprio 0
	s_barrier
; #define PG8_STAGE(bufoff, gbase, voff) do { _Pragma("unroll") for (int _i = 0; _i < 2; ++_i) \
;         __builtin_amdgcn_global_load_lds((const unsigned*)((const char*)(gbase) + (voff)[_i]), (LAS unsigned*)(lds + (bufoff) + ldsw + _i * 8192), 16, 0, 0); } while (0)
; #define PG8_LDA(dst, b, h) do { _Pragma("unroll") for (int m = 0; m < 4; ++m) _Pragma("unroll") for (int k = 0; k < 2; ++k) dst[m][k] = *(const LAS bf16x8*)(lds + PG8_SA(b, h) + aoff + m * 2048 + k * 1024); } while (0)
; #define PG8_LDB(dst, b, h) do { _Pragma("unroll") for (int n = 0; n < 2; ++n) _Pragma("unroll") for (int k = 0; k < 2; ++k) dst[n][k] = *(const LAS bf16x8*)(lds + PG8_SB(b, h) + boff + n * 2048 + k * 1024); } while (0)
; #define PG8_MMA(ai, bj, At, Bt) do { __builtin_amdgcn_s_setprio(1); _Pragma("unroll") for (int m = 0; m < 4; ++m) _Pragma("unroll") for (int n = 0; n < 2; ++n) _Pragma("unroll") for (int k = 0; k < 2; ++k) \
;         acc[ai][bj][m][n] = __builtin_amdgcn_mfma_f32_16x16x32_bf16(Bt[n][k], At[m][k], acc[ai][bj][m][n], 0, 0, 0); __builtin_amdgcn_s_setprio(0); } while (0)
; #define PG8_WAIT_V(n) asm volatile("s_waitcnt vmcnt(" #n ")" ::: "memory")
; #define PG8_WAIT_L(n) asm volatile("s_waitcnt lgkmcnt(" #n ")" ::: "memory")
; #define PG8_BAR __builtin_amdgcn_s_barrier()
; #define PG8_SCHED __builtin_amdgcn_sched_barrier(0)
; template <class Epi>
; __device__ __forceinline__ void gemm_phase(LAS unsigned char* lds, const Gemm g, const StaticOrder S, const Epi E) {
;     ...
;             PG8_LDB(B0, 1, 0); PG8_LDB(B1, 1, 1); PG8_SCHED; PG8_LDA(At, 1, 0); PG8_STAGE(PG8_SA(0, 1), a2 + hstepA, voffA);
;             PG8_WAIT_V(8); PG8_WAIT_L(0); PG8_BAR; PG8_MMA(0, 0, At, B0); PG8_MMA(0, 1, At, B1); PG8_BAR; PG8_SCHED;
;             PG8_LDA(At, 1, 1); PG8_STAGE(PG8_SB(1, 0), b3, voffB); PG8_STAGE(PG8_SB(1, 1), b3 + hstepB, voffB); PG8_STAGE(PG8_SA(1, 0), a3, voffA);
;             PG8_WAIT_V(8); PG8_WAIT_L(0); PG8_BAR; PG8_MMA(1, 0, At, B0); PG8_MMA(1, 1, At, B1); PG8_BAR; PG8_SCHED;
;         }
	s_add_i32 s68, 0, 0x18000
	s_add_i32 s69, 0, 0x1c000
	v_add_u32_e32 v152, s68, v161
	ds_read_b128 v[128:131], v152
	ds_read_b128 v[132:135], v152 offset:1024
	ds_read_b128 v[136:139], v152 offset:2048
	ds_read_b128 v[152:155], v152 offset:3072
	ds_read_b128 v[156:159], v254 offset:49152
	ds_read_b128 v[166:169], v254 offset:50176
	ds_read_b128 v[170:173], v254 offset:51200
	ds_read_b128 v[174:177], v254 offset:52224
	s_add_u32 s40, s40, 0x160000
	s_addc_u32 s41, s41, 0
	s_mov_b32 m0, s48
	ds_read_b128 v[178:181], v163 offset:32768
	ds_read_b128 v[182:185], v163 offset:33792
	ds_read_b128 v[186:189], v163 offset:34816
	ds_read_b128 v[190:193], v163 offset:35840
	ds_read_b128 v[194:197], v163 offset:36864
	ds_read_b128 v[198:201], v163 offset:37888
	ds_read_b128 v[202:205], v163 offset:38912
	ds_read_b128 v[206:209], v163 offset:39936
	global_load_lds_dwordx4 v140, s[40:41]
	s_mov_b32 m0, s49
	s_nop 0
	global_load_lds_dwordx4 v144, s[40:41]
	s_waitcnt vmcnt(8)
	s_waitcnt lgkmcnt(0)
	s_barrier
	s_setprio 1
	s_waitcnt lgkmcnt(0)
	v_mfma_f32_16x16x32_bf16 v[124:127], v[128:131], v[178:181], v[124:127]
	v_mfma_f32_16x16x32_bf16 v[120:123], v[136:139], v[178:181], v[120:123]
	v_mfma_f32_16x16x32_bf16 v[108:111], v[128:131], v[186:189], v[108:111]
	v_mfma_f32_16x16x32_bf16 v[104:107], v[136:139], v[186:189], v[104:107]
	v_mfma_f32_16x16x32_bf16 v[92:95], v[128:131], v[194:197], v[92:95]
	v_mfma_f32_16x16x32_bf16 v[88:91], v[136:139], v[194:197], v[88:91]
	v_mfma_f32_16x16x32_bf16 v[76:79], v[128:131], v[202:205], v[76:79]
	v_mfma_f32_16x16x32_bf16 v[72:75], v[136:139], v[202:205], v[72:75]
	v_mfma_f32_16x16x32_bf16 v[124:127], v[132:135], v[182:185], v[124:127]
	v_mfma_f32_16x16x32_bf16 v[120:123], v[152:155], v[182:185], v[120:123]
	v_mfma_f32_16x16x32_bf16 v[108:111], v[132:135], v[190:193], v[108:111]
	v_mfma_f32_16x16x32_bf16 v[104:107], v[152:155], v[190:193], v[104:107]
	v_mfma_f32_16x16x32_bf16 v[92:95], v[132:135], v[198:201], v[92:95]
	v_mfma_f32_16x16x32_bf16 v[88:91], v[152:155], v[198:201], v[88:91]
	v_mfma_f32_16x16x32_bf16 v[76:79], v[132:135], v[206:209], v[76:79]
	v_mfma_f32_16x16x32_bf16 v[72:75], v[152:155], v[206:209], v[72:75]
	s_setprio 0
	s_setprio 1
	v_mfma_f32_16x16x32_bf16 v[116:119], v[156:159], v[178:181], v[116:119]
	v_mfma_f32_16x16x32_bf16 v[112:115], v[170:173], v[178:181], v[112:115]
	v_mfma_f32_16x16x32_bf16 v[100:103], v[156:159], v[186:189], v[100:103]
	v_mfma_f32_16x16x32_bf16 v[96:99], v[170:173], v[186:189], v[96:99]
	v_mfma_f32_16x16x32_bf16 v[84:87], v[156:159], v[194:197], v[84:87]
	v_mfma_f32_16x16x32_bf16 v[80:83], v[170:173], v[194:197], v[80:83]
	v_mfma_f32_16x16x32_bf16 v[68:71], v[156:159], v[202:205], v[68:71]
	v_mfma_f32_16x16x32_bf16 v[64:67], v[170:173], v[202:205], v[64:67]
	v_mfma_f32_16x16x32_bf16 v[116:119], v[166:169], v[182:185], v[116:119]
	v_mfma_f32_16x16x32_bf16 v[112:115], v[174:177], v[182:185], v[112:115]
	v_mfma_f32_16x16x32_bf16 v[100:103], v[166:169], v[190:193], v[100:103]
	v_mfma_f32_16x16x32_bf16 v[96:99], v[174:177], v[190:193], v[96:99]
	v_mfma_f32_16x16x32_bf16 v[84:87], v[166:169], v[198:201], v[84:87]
	v_mfma_f32_16x16x32_bf16 v[80:83], v[174:177], v[198:201], v[80:83]
	v_mfma_f32_16x16x32_bf16 v[68:71], v[166:169], v[206:209], v[68:71]
	v_mfma_f32_16x16x32_bf16 v[64:67], v[174:177], v[206:209], v[64:67]
	s_setprio 0
	s_barrier
	s_add_u32 s36, s36, s38
	s_addc_u32 s37, s37, s39
	s_add_i32 s38, s68, s45
	s_mov_b32 m0, s38
	ds_read_b128 v[178:181], v163 offset:49152
	ds_read_b128 v[182:185], v163 offset:50176
	ds_read_b128 v[186:189], v163 offset:51200
	ds_read_b128 v[190:193], v163 offset:52224
	ds_read_b128 v[194:197], v163 offset:53248
	ds_read_b128 v[198:201], v163 offset:54272
	ds_read_b128 v[202:205], v163 offset:55296
	ds_read_b128 v[206:209], v163 offset:56320
	global_load_lds_dwordx4 v142, s[36:37]
	s_add_i32 m0, s38, 0x2000
	s_nop 0
	global_load_lds_dwordx4 v146, s[36:37]
	s_add_u32 s36, s36, 0x160000
	s_addc_u32 s37, s37, 0
	s_add_i32 s38, s69, s45
	s_mov_b32 m0, s38
	s_nop 0
	global_load_lds_dwordx4 v142, s[36:37]
	s_add_i32 m0, s38, 0x2000
	s_nop 0
	global_load_lds_dwordx4 v146, s[36:37]
	s_mov_b32 m0, s51
	s_nop 0
	global_load_lds_dwordx4 v140, s[42:43]
	s_mov_b32 m0, s52
	s_nop 0
	global_load_lds_dwordx4 v144, s[42:43]
	s_waitcnt vmcnt(8)
	s_waitcnt lgkmcnt(0)
	s_barrier
	s_setprio 1
	s_waitcnt lgkmcnt(0)
	v_mfma_f32_16x16x32_bf16 v[60:63], v[128:131], v[178:181], v[60:63]
	v_mfma_f32_16x16x32_bf16 v[56:59], v[136:139], v[178:181], v[56:59]
	v_mfma_f32_16x16x32_bf16 v[44:47], v[128:131], v[186:189], v[44:47]
	v_mfma_f32_16x16x32_bf16 v[40:43], v[136:139], v[186:189], v[40:43]
	v_mfma_f32_16x16x32_bf16 v[28:31], v[128:131], v[194:197], v[28:31]
	v_mfma_f32_16x16x32_bf16 v[24:27], v[136:139], v[194:197], v[24:27]
	v_mfma_f32_16x16x32_bf16 v[12:15], v[128:131], v[202:205], v[12:15]
	v_mfma_f32_16x16x32_bf16 v[8:11], v[136:139], v[202:205], v[8:11]
	v_mfma_f32_16x16x32_bf16 v[60:63], v[132:135], v[182:185], v[60:63]
	v_mfma_f32_16x16x32_bf16 v[56:59], v[152:155], v[182:185], v[56:59]
	v_mfma_f32_16x16x32_bf16 v[44:47], v[132:135], v[190:193], v[44:47]
	v_mfma_f32_16x16x32_bf16 v[40:43], v[152:155], v[190:193], v[40:43]
	v_mfma_f32_16x16x32_bf16 v[28:31], v[132:135], v[198:201], v[28:31]
	v_mfma_f32_16x16x32_bf16 v[24:27], v[152:155], v[198:201], v[24:27]
	v_mfma_f32_16x16x32_bf16 v[12:15], v[132:135], v[206:209], v[12:15]
	v_mfma_f32_16x16x32_bf16 v[8:11], v[152:155], v[206:209], v[8:11]
	s_setprio 0
	s_setprio 1
	v_mfma_f32_16x16x32_bf16 v[52:55], v[156:159], v[178:181], v[52:55]
	v_mfma_f32_16x16x32_bf16 v[48:51], v[170:173], v[178:181], v[48:51]
	v_mfma_f32_16x16x32_bf16 v[36:39], v[156:159], v[186:189], v[36:39]
	v_mfma_f32_16x16x32_bf16 v[32:35], v[170:173], v[186:189], v[32:35]
	v_mfma_f32_16x16x32_bf16 v[20:23], v[156:159], v[194:197], v[20:23]
	v_mfma_f32_16x16x32_bf16 v[16:19], v[170:173], v[194:197], v[16:19]
	v_mfma_f32_16x16x32_bf16 v[4:7], v[156:159], v[202:205], v[4:7]
	v_mfma_f32_16x16x32_bf16 v[0:3], v[170:173], v[202:205], v[0:3]
	v_mfma_f32_16x16x32_bf16 v[52:55], v[166:169], v[182:185], v[52:55]
	v_mfma_f32_16x16x32_bf16 v[48:51], v[174:177], v[182:185], v[48:51]
	v_mfma_f32_16x16x32_bf16 v[36:39], v[166:169], v[190:193], v[36:39]
	v_mfma_f32_16x16x32_bf16 v[32:35], v[174:177], v[190:193], v[32:35]
	v_mfma_f32_16x16x32_bf16 v[20:23], v[166:169], v[198:201], v[20:23]
	v_mfma_f32_16x16x32_bf16 v[16:19], v[174:177], v[198:201], v[16:19]
	v_mfma_f32_16x16x32_bf16 v[4:7], v[166:169], v[206:209], v[4:7]
	v_mfma_f32_16x16x32_bf16 v[0:3], v[174:177], v[206:209], v[0:3]
	s_setprio 0
	s_barrier
	s_cmpk_gt_u32 s66, 0x55
	s_mov_b32 s66, s67
	s_cbranch_scc1 .LBB0_1563
; #define PG8_STAGE(bufoff, gbase, voff) do { _Pragma("unroll") for (int _i = 0; _i < 2; ++_i) \
;         __builtin_amdgcn_global_load_lds((const unsigned*)((const char*)(gbase) + (voff)[_i]), (LAS unsigned*)(lds + (bufoff) + ldsw + _i * 8192), 16, 0, 0); } while (0)
; #define PG8_LDA(dst, b, h) do { _Pragma("unroll") for (int m = 0; m < 4; ++m) _Pragma("unroll") for (int k = 0; k < 2; ++k) dst[m][k] = *(const LAS bf16x8*)(lds + PG8_SA(b, h) + aoff + m * 2048 + k * 1024); } while (0)
; #define PG8_LDB(dst, b, h) do { _Pragma("unroll") for (int n = 0; n < 2; ++n) _Pragma("unroll") for (int k = 0; k < 2; ++k) dst[n][k] = *(const LAS bf16x8*)(lds + PG8_SB(b, h) + boff + n * 2048 + k * 1024); } while (0)
; #define PG8_SCHED __builtin_amdgcn_sched_barrier(0)
; template <class Epi>
; __device__ __forceinline__ void gemm_phase(LAS unsigned char* lds, const Gemm g, const StaticOrder S, const Epi E) {
;     ...
;             const bool last = (t == nt - 2);
;             const char* a1 = cA + (long)(t + 1) * ksc;
;             const char* a2 = last ? nA : cA + (long)(t + 2) * ksc; const char* b2 = last ? nB : cB + (long)(t + 2) * ksc;
;             const long ks3 = last ? ksn : ksc;
;             const char* a3 = a2 + ks3; const char* b3 = b2 + ks3;
;             PG8_LDB(B0, 0, 0); PG8_LDB(B1, 0, 1); PG8_SCHED; PG8_LDA(At, 0, 0); PG8_STAGE(PG8_SA(1, 1), a1 + hstepA, voffA);
.LBB0_1559:
	v_add_u32_e32 v152, s55, v161
	ds_read_b128 v[128:131], v152
	ds_read_b128 v[132:135], v152 offset:1024
	ds_read_b128 v[136:139], v152 offset:2048
	ds_read_b128 v[152:155], v152 offset:3072
	ds_read_b128 v[156:159], v254 offset:16384
	ds_read_b128 v[166:169], v254 offset:17408
	ds_read_b128 v[170:173], v254 offset:18432
	ds_read_b128 v[174:177], v254 offset:19456
	ds_read_b128 v[178:181], v163
	ds_read_b128 v[182:185], v163 offset:1024
	ds_read_b128 v[186:189], v163 offset:2048
	ds_read_b128 v[190:193], v163 offset:3072
	ds_read_b128 v[194:197], v163 offset:4096
	ds_read_b128 v[198:201], v163 offset:5120
	ds_read_b128 v[202:205], v163 offset:6144
	ds_read_b128 v[206:209], v163 offset:7168
	s_cmpk_lg_i32 s66, 0x56
	s_cselect_b64 s[36:37], -1, 0
	s_cmpk_eq_i32 s66, 0x56
	s_mov_b64 s[40:41], s[22:23]
	s_cbranch_scc1 .LBB0_1561
	s_add_i32 s38, s66, 2
	s_mul_i32 s39, s35, s38
	s_mul_hi_u32 s40, s34, s38
	s_add_i32 s39, s40, s39
	s_mul_i32 s38, s34, s38
	s_add_u32 s40, s30, s38
	s_addc_u32 s41, s31, s39
